# K-loops: read-free phases 4 and 8 merged into the preceding burst (32-MFMA segments, 12 instead of 16 barriers per K iteration), LDS reads drained before every closing barrier, vmcnt(8) added at load
# baseline (speedup 1.0000x reference)
.LBB0_124:
	s_nop 0
	s_ashr_i32 s79, s78, 31
	s_lshl_b64 s[10:11], s[78:79], 19
	s_add_u32 s80, s54, s10
	v_cmp_lt_i64_e32 vcc, s[72:73], v[178:179]
	s_addc_u32 s81, s55, s11
	s_and_b64 s[10:11], vcc, exec
	s_cselect_b32 s1, s81, s87
	s_cselect_b32 s10, s80, s86
	s_ashr_i32 s77, s76, 31
	s_lshl_b64 s[36:37], s[76:77], 19
	s_add_u32 s72, s66, s36
	s_addc_u32 s73, s59, s37
	s_and_b64 s[36:37], vcc, exec
	s_cselect_b32 s11, s73, s83
	s_cselect_b32 s25, s72, s82
	s_add_u32 s86, s86, 0x40080
	s_addc_u32 s87, s87, 0
	s_add_u32 s33, s82, 0x100
	s_addc_u32 s36, s83, 0
	s_mov_b32 s37, -2
	s_add_u32 s27, s86, 0xfffc0080
	s_addc_u32 s56, s87, -1
	s_add_i32 s57, 0, 0x10000
	ds_read_b128 v[64:67], v217
	ds_read_b128 v[68:71], v217 offset:1024
	ds_read_b128 v[72:75], v217 offset:2048
	ds_read_b128 v[76:79], v217 offset:3072
	s_cmp_eq_u32 s37, 12
	s_cselect_b32 vcc_hi, s1, s56
	s_cselect_b32 vcc_lo, s10, s27
	s_cselect_b32 s83, s11, s36
	s_cselect_b32 s82, s25, s33
	s_add_i32 m0, s75, 0xc000
	ds_read_b128 v[80:83], v220
	ds_read_b128 v[84:87], v220 offset:1024
	ds_read_b128 v[88:91], v220 offset:2048
	ds_read_b128 v[92:95], v220 offset:3072
	ds_read_b128 v[188:191], v220 offset:4096
	ds_read_b128 v[192:195], v220 offset:5120
	ds_read_b128 v[196:199], v220 offset:6144
	ds_read_b128 v[200:203], v220 offset:7168
	global_load_lds_dwordx4 v164, s[86:87]
	s_add_i32 m0, s75, 0xe000
	s_nop 0
	global_load_lds_dwordx4 v166, s[86:87]
	s_waitcnt lgkmcnt(0)
	s_barrier
	v_mfma_f32_16x16x32_bf16 v[146:149], v[64:67], v[80:83], 0
	v_mfma_f32_16x16x32_bf16 v[116:119], v[72:75], v[80:83], 0
	v_mfma_f32_16x16x32_bf16 v[158:161], v[64:67], v[88:91], 0
	v_mfma_f32_16x16x32_bf16 v[124:127], v[72:75], v[88:91], 0
	v_mfma_f32_16x16x32_bf16 v[154:157], v[64:67], v[188:191], 0
	v_mfma_f32_16x16x32_bf16 v[112:115], v[72:75], v[188:191], 0
	v_mfma_f32_16x16x32_bf16 v[150:153], v[64:67], v[196:199], 0
	v_mfma_f32_16x16x32_bf16 v[120:123], v[72:75], v[196:199], 0
	v_mfma_f32_16x16x32_bf16 v[146:149], v[68:71], v[84:87], v[146:149]
	v_mfma_f32_16x16x32_bf16 v[116:119], v[76:79], v[84:87], v[116:119]
	v_mfma_f32_16x16x32_bf16 v[158:161], v[68:71], v[92:95], v[158:161]
	v_mfma_f32_16x16x32_bf16 v[124:127], v[76:79], v[92:95], v[124:127]
	v_mfma_f32_16x16x32_bf16 v[154:157], v[68:71], v[192:195], v[154:157]
	v_mfma_f32_16x16x32_bf16 v[112:115], v[76:79], v[192:195], v[112:115]
	v_mfma_f32_16x16x32_bf16 v[150:153], v[68:71], v[200:203], v[150:153]
	v_mfma_f32_16x16x32_bf16 v[120:123], v[76:79], v[200:203], v[120:123]
	s_barrier
	s_add_i32 s27, 0, 0x14000
	s_add_i32 s56, s57, s74
	ds_read_b128 v[204:207], v217 offset:16384
	ds_read_b128 v[222:225], v217 offset:17408
	ds_read_b128 v[228:231], v217 offset:18432
	ds_read_b128 v[232:235], v217 offset:19456
	s_mov_b32 m0, s56
	global_load_lds_dwordx4 v144, s[82:83]
	s_add_i32 m0, s56, 0x2000
	s_nop 0
	global_load_lds_dwordx4 v162, s[82:83]
	s_waitcnt lgkmcnt(0)
	s_barrier
	v_mfma_f32_16x16x32_bf16 v[140:143], v[204:207], v[80:83], 0
	v_mfma_f32_16x16x32_bf16 v[80:83], v[228:231], v[80:83], 0
	v_mfma_f32_16x16x32_bf16 v[140:143], v[222:225], v[84:87], v[140:143]
	v_mfma_f32_16x16x32_bf16 v[80:83], v[232:235], v[84:87], v[80:83]
	v_mfma_f32_16x16x32_bf16 v[84:87], v[204:207], v[88:91], 0
	v_mfma_f32_16x16x32_bf16 v[88:91], v[228:231], v[88:91], 0
	v_mfma_f32_16x16x32_bf16 v[100:103], v[228:231], v[188:191], 0
	v_mfma_f32_16x16x32_bf16 v[104:107], v[204:207], v[196:199], 0
	v_mfma_f32_16x16x32_bf16 v[96:99], v[228:231], v[196:199], 0
	v_mfma_f32_16x16x32_bf16 v[84:87], v[222:225], v[92:95], v[84:87]
	v_mfma_f32_16x16x32_bf16 v[88:91], v[232:235], v[92:95], v[88:91]
	v_mfma_f32_16x16x32_bf16 v[92:95], v[204:207], v[188:191], 0
	v_mfma_f32_16x16x32_bf16 v[100:103], v[232:235], v[192:195], v[100:103]
	v_mfma_f32_16x16x32_bf16 v[128:131], v[222:225], v[200:203], v[104:107]
	v_mfma_f32_16x16x32_bf16 v[96:99], v[232:235], v[200:203], v[96:99]
	v_mfma_f32_16x16x32_bf16 v[92:95], v[222:225], v[192:195], v[92:95]
	s_barrier
	s_mov_b32 m0, s75
	ds_read_b128 v[104:107], v220 offset:16384
	ds_read_b128 v[108:111], v220 offset:17408
	ds_read_b128 v[132:135], v220 offset:18432
	ds_read_b128 v[136:139], v220 offset:19456
	ds_read_b128 v[188:191], v220 offset:20480
	ds_read_b128 v[192:195], v220 offset:21504
	ds_read_b128 v[196:199], v220 offset:22528
	ds_read_b128 v[200:203], v220 offset:23552
	global_load_lds_dwordx4 v144, vcc
	s_mov_b32 m0, s85
	s_nop 0
	global_load_lds_dwordx4 v162, vcc
	s_waitcnt lgkmcnt(0)
	s_waitcnt vmcnt(8)
	s_barrier
	v_mfma_f32_16x16x32_bf16 v[48:51], v[64:67], v[104:107], 0
	v_mfma_f32_16x16x32_bf16 v[20:23], v[72:75], v[104:107], 0
	v_mfma_f32_16x16x32_bf16 v[60:63], v[64:67], v[132:135], 0
	v_mfma_f32_16x16x32_bf16 v[28:31], v[72:75], v[132:135], 0
	v_mfma_f32_16x16x32_bf16 v[56:59], v[64:67], v[188:191], 0
	v_mfma_f32_16x16x32_bf16 v[16:19], v[72:75], v[188:191], 0
	v_mfma_f32_16x16x32_bf16 v[52:55], v[64:67], v[196:199], 0
	v_mfma_f32_16x16x32_bf16 v[24:27], v[72:75], v[196:199], 0
	v_mfma_f32_16x16x32_bf16 v[48:51], v[68:71], v[108:111], v[48:51]
	v_mfma_f32_16x16x32_bf16 v[20:23], v[76:79], v[108:111], v[20:23]
	v_mfma_f32_16x16x32_bf16 v[60:63], v[68:71], v[136:139], v[60:63]
	v_mfma_f32_16x16x32_bf16 v[28:31], v[76:79], v[136:139], v[28:31]
	v_mfma_f32_16x16x32_bf16 v[56:59], v[68:71], v[192:195], v[56:59]
	v_mfma_f32_16x16x32_bf16 v[16:19], v[76:79], v[192:195], v[16:19]
	v_mfma_f32_16x16x32_bf16 v[52:55], v[68:71], v[200:203], v[52:55]
	v_mfma_f32_16x16x32_bf16 v[24:27], v[76:79], v[200:203], v[24:27]
	s_add_u32 s56, s82, 0x40000
	s_addc_u32 s57, s83, 0
	s_add_i32 s27, s27, s74
	s_mov_b32 m0, s27
	s_nop 0
	global_load_lds_dwordx4 v144, s[56:57]
	s_add_i32 m0, s27, 0x2000
	s_nop 0
	global_load_lds_dwordx4 v162, s[56:57]
	s_waitcnt vmcnt(6)
	v_mfma_f32_16x16x32_bf16 v[44:47], v[204:207], v[104:107], 0
	v_mfma_f32_16x16x32_bf16 v[12:15], v[228:231], v[104:107], 0
	v_mfma_f32_16x16x32_bf16 v[40:43], v[204:207], v[132:135], 0
	v_mfma_f32_16x16x32_bf16 v[8:11], v[228:231], v[132:135], 0
	v_mfma_f32_16x16x32_bf16 v[36:39], v[204:207], v[188:191], 0
	v_mfma_f32_16x16x32_bf16 v[4:7], v[228:231], v[188:191], 0
	v_mfma_f32_16x16x32_bf16 v[32:35], v[204:207], v[196:199], 0
	v_mfma_f32_16x16x32_bf16 v[0:3], v[228:231], v[196:199], 0
	v_mfma_f32_16x16x32_bf16 v[44:47], v[222:225], v[108:111], v[44:47]
	v_mfma_f32_16x16x32_bf16 v[12:15], v[232:235], v[108:111], v[12:15]
	v_mfma_f32_16x16x32_bf16 v[40:43], v[222:225], v[136:139], v[40:43]
	v_mfma_f32_16x16x32_bf16 v[8:11], v[232:235], v[136:139], v[8:11]
	v_mfma_f32_16x16x32_bf16 v[36:39], v[222:225], v[192:195], v[36:39]
	v_mfma_f32_16x16x32_bf16 v[4:7], v[232:235], v[192:195], v[4:7]
	v_mfma_f32_16x16x32_bf16 v[32:35], v[222:225], v[200:203], v[32:35]
	v_mfma_f32_16x16x32_bf16 v[0:3], v[232:235], v[200:203], v[0:3]
	s_barrier
	s_add_i32 s27, 0, 0x18000
	ds_read_b128 v[64:67], v217 offset:32768
	ds_read_b128 v[68:71], v217 offset:33792
	ds_read_b128 v[72:75], v217 offset:34816
	ds_read_b128 v[76:79], v217 offset:35840
	s_add_u32 s56, vcc_lo, 0x40000
	s_addc_u32 s57, vcc_hi, 0
	s_mov_b32 m0, s98
	ds_read_b128 v[104:107], v220 offset:32768
	ds_read_b128 v[108:111], v220 offset:33792
	ds_read_b128 v[132:135], v220 offset:34816
	ds_read_b128 v[188:191], v220 offset:35840
	ds_read_b128 v[192:195], v220 offset:36864
	ds_read_b128 v[196:199], v220 offset:37888
	ds_read_b128 v[200:203], v220 offset:38912
	ds_read_b128 v[204:207], v220 offset:39936
	global_load_lds_dwordx4 v144, s[56:57]
	s_mov_b32 m0, s29
	s_nop 0
	global_load_lds_dwordx4 v162, s[56:57]
	s_waitcnt lgkmcnt(0)
	s_barrier
	v_mfma_f32_16x16x32_bf16 v[136:139], v[64:67], v[104:107], v[146:149]
	v_mfma_f32_16x16x32_bf16 v[146:149], v[68:71], v[108:111], v[136:139]
	v_mfma_f32_16x16x32_bf16 v[136:139], v[64:67], v[132:135], v[158:161]
	v_mfma_f32_16x16x32_bf16 v[158:161], v[68:71], v[188:191], v[136:139]
	v_mfma_f32_16x16x32_bf16 v[136:139], v[64:67], v[192:195], v[154:157]
	v_mfma_f32_16x16x32_bf16 v[116:119], v[72:75], v[104:107], v[116:119]
	v_mfma_f32_16x16x32_bf16 v[124:127], v[72:75], v[132:135], v[124:127]
	v_mfma_f32_16x16x32_bf16 v[154:157], v[68:71], v[196:199], v[136:139]
	v_mfma_f32_16x16x32_bf16 v[112:115], v[72:75], v[192:195], v[112:115]
	v_mfma_f32_16x16x32_bf16 v[136:139], v[64:67], v[200:203], v[150:153]
	v_mfma_f32_16x16x32_bf16 v[120:123], v[72:75], v[200:203], v[120:123]
	v_mfma_f32_16x16x32_bf16 v[116:119], v[76:79], v[108:111], v[116:119]
	v_mfma_f32_16x16x32_bf16 v[124:127], v[76:79], v[188:191], v[124:127]
	v_mfma_f32_16x16x32_bf16 v[112:115], v[76:79], v[196:199], v[112:115]
	v_mfma_f32_16x16x32_bf16 v[150:153], v[68:71], v[204:207], v[136:139]
	v_mfma_f32_16x16x32_bf16 v[120:123], v[76:79], v[204:207], v[120:123]
	s_barrier
	s_nop 0
	s_add_i32 s58, 0, 0x1c000
	s_add_i32 s27, s27, s74
	ds_read_b128 v[222:225], v217 offset:49152
	ds_read_b128 v[228:231], v217 offset:50176
	ds_read_b128 v[232:235], v217 offset:51200
	ds_read_b128 v[236:239], v217 offset:52224
	s_add_u32 s56, s82, s18
	s_addc_u32 s57, s83, s19
	s_mov_b32 m0, s27
	s_nop 0
	global_load_lds_dwordx4 v144, s[56:57]
	s_add_u32 s56, s82, s18
	s_addc_u32 s57, s83, s19
	s_add_i32 m0, s27, 0x2000
	s_nop 0
	global_load_lds_dwordx4 v162, s[56:57]
	s_waitcnt lgkmcnt(0)
	s_barrier
	v_mfma_f32_16x16x32_bf16 v[136:139], v[222:225], v[104:107], v[140:143]
	v_mfma_f32_16x16x32_bf16 v[80:83], v[232:235], v[104:107], v[80:83]
	v_mfma_f32_16x16x32_bf16 v[140:143], v[228:231], v[108:111], v[136:139]
	v_mfma_f32_16x16x32_bf16 v[108:111], v[236:239], v[108:111], v[80:83]
	v_mfma_f32_16x16x32_bf16 v[80:83], v[222:225], v[132:135], v[84:87]
	v_mfma_f32_16x16x32_bf16 v[136:139], v[228:231], v[188:191], v[80:83]
	v_mfma_f32_16x16x32_bf16 v[80:83], v[232:235], v[132:135], v[88:91]
	v_mfma_f32_16x16x32_bf16 v[104:107], v[236:239], v[188:191], v[80:83]
	v_mfma_f32_16x16x32_bf16 v[80:83], v[222:225], v[192:195], v[92:95]
	v_mfma_f32_16x16x32_bf16 v[132:135], v[228:231], v[196:199], v[80:83]
	v_mfma_f32_16x16x32_bf16 v[80:83], v[232:235], v[192:195], v[100:103]
	v_mfma_f32_16x16x32_bf16 v[100:103], v[236:239], v[196:199], v[80:83]
	v_mfma_f32_16x16x32_bf16 v[80:83], v[222:225], v[200:203], v[128:131]
	v_mfma_f32_16x16x32_bf16 v[128:131], v[228:231], v[204:207], v[80:83]
	v_mfma_f32_16x16x32_bf16 v[80:83], v[232:235], v[200:203], v[96:99]
	v_mfma_f32_16x16x32_bf16 v[96:99], v[236:239], v[204:207], v[80:83]
	s_barrier
	s_nop 0
	s_mov_b32 m0, s31
	s_add_u32 s56, vcc_lo, s18
	s_addc_u32 s57, vcc_hi, s19
	s_nop 2
	ds_read_b128 v[80:83], v220 offset:49152
	ds_read_b128 v[84:87], v220 offset:50176
	ds_read_b128 v[88:91], v220 offset:51200
	ds_read_b128 v[92:95], v220 offset:52224
	ds_read_b128 v[188:191], v220 offset:53248
	ds_read_b128 v[192:195], v220 offset:54272
	ds_read_b128 v[196:199], v220 offset:55296
	ds_read_b128 v[200:203], v220 offset:56320
	global_load_lds_dwordx4 v144, s[56:57]
	s_add_u32 s56, vcc_lo, s18
	s_addc_u32 s57, vcc_hi, s19
	s_mov_b32 m0, s34
	s_nop 0
	global_load_lds_dwordx4 v162, s[56:57]
	s_waitcnt lgkmcnt(0)
	s_waitcnt vmcnt(8)
	s_barrier
	v_mfma_f32_16x16x32_bf16 v[48:51], v[64:67], v[80:83], v[48:51]
	v_mfma_f32_16x16x32_bf16 v[20:23], v[72:75], v[80:83], v[20:23]
	v_mfma_f32_16x16x32_bf16 v[60:63], v[64:67], v[88:91], v[60:63]
	v_mfma_f32_16x16x32_bf16 v[28:31], v[72:75], v[88:91], v[28:31]
	v_mfma_f32_16x16x32_bf16 v[56:59], v[64:67], v[188:191], v[56:59]
	v_mfma_f32_16x16x32_bf16 v[16:19], v[72:75], v[188:191], v[16:19]
	v_mfma_f32_16x16x32_bf16 v[52:55], v[64:67], v[196:199], v[52:55]
	v_mfma_f32_16x16x32_bf16 v[24:27], v[72:75], v[196:199], v[24:27]
	v_mfma_f32_16x16x32_bf16 v[48:51], v[68:71], v[84:87], v[48:51]
	v_mfma_f32_16x16x32_bf16 v[20:23], v[76:79], v[84:87], v[20:23]
	v_mfma_f32_16x16x32_bf16 v[60:63], v[68:71], v[92:95], v[60:63]
	v_mfma_f32_16x16x32_bf16 v[28:31], v[76:79], v[92:95], v[28:31]
	v_mfma_f32_16x16x32_bf16 v[56:59], v[68:71], v[192:195], v[56:59]
	v_mfma_f32_16x16x32_bf16 v[16:19], v[76:79], v[192:195], v[16:19]
	v_mfma_f32_16x16x32_bf16 v[52:55], v[68:71], v[200:203], v[52:55]
	v_mfma_f32_16x16x32_bf16 v[24:27], v[76:79], v[200:203], v[24:27]
	s_add_u32 s56, s82, 0x40080
	s_addc_u32 s57, s83, 0
	s_add_i32 s27, s58, s74
	s_mov_b32 m0, s27
	s_nop 0
	global_load_lds_dwordx4 v144, s[56:57]
	s_add_i32 m0, s27, 0x2000
	s_nop 0
	global_load_lds_dwordx4 v162, s[56:57]
	s_waitcnt vmcnt(6)
	v_mfma_f32_16x16x32_bf16 v[44:47], v[222:225], v[80:83], v[44:47]
	v_mfma_f32_16x16x32_bf16 v[12:15], v[232:235], v[80:83], v[12:15]
	v_mfma_f32_16x16x32_bf16 v[40:43], v[222:225], v[88:91], v[40:43]
	v_mfma_f32_16x16x32_bf16 v[8:11], v[232:235], v[88:91], v[8:11]
	v_mfma_f32_16x16x32_bf16 v[36:39], v[222:225], v[188:191], v[36:39]
	v_mfma_f32_16x16x32_bf16 v[4:7], v[232:235], v[188:191], v[4:7]
	v_mfma_f32_16x16x32_bf16 v[32:35], v[222:225], v[196:199], v[32:35]
	v_mfma_f32_16x16x32_bf16 v[0:3], v[232:235], v[196:199], v[0:3]
	v_mfma_f32_16x16x32_bf16 v[44:47], v[228:231], v[84:87], v[44:47]
	v_mfma_f32_16x16x32_bf16 v[12:15], v[236:239], v[84:87], v[12:15]
	v_mfma_f32_16x16x32_bf16 v[40:43], v[228:231], v[92:95], v[40:43]
	v_mfma_f32_16x16x32_bf16 v[8:11], v[236:239], v[92:95], v[8:11]
	v_mfma_f32_16x16x32_bf16 v[36:39], v[228:231], v[192:195], v[36:39]
	v_mfma_f32_16x16x32_bf16 v[4:7], v[236:239], v[192:195], v[4:7]
	v_mfma_f32_16x16x32_bf16 v[32:35], v[228:231], v[200:203], v[32:35]
	v_mfma_f32_16x16x32_bf16 v[0:3], v[236:239], v[200:203], v[0:3]
	s_barrier
	s_add_i32 s37, s37, 2
	s_add_u32 s86, s86, 0x100
	s_addc_u32 s87, s87, 0
	s_add_u32 s33, s33, 0x100
	s_addc_u32 s36, s36, 0
	s_cmp_gt_u32 s37, 13
.LBB0_125:
	s_nop 0
	s_add_u32 s27, s86, 0xfffc0080
	s_addc_u32 s56, s87, -1
	s_add_i32 s57, 0, 0x10000
	ds_read_b128 v[64:67], v217
	ds_read_b128 v[68:71], v217 offset:1024
	ds_read_b128 v[72:75], v217 offset:2048
	ds_read_b128 v[76:79], v217 offset:3072
	s_cmp_eq_u32 s37, 12
	s_cselect_b32 vcc_hi, s1, s56
	s_cselect_b32 vcc_lo, s10, s27
	s_cselect_b32 s83, s11, s36
	s_cselect_b32 s82, s25, s33
	s_add_i32 m0, s75, 0xc000
	ds_read_b128 v[80:83], v220
	ds_read_b128 v[84:87], v220 offset:1024
	ds_read_b128 v[88:91], v220 offset:2048
	ds_read_b128 v[92:95], v220 offset:3072
	ds_read_b128 v[188:191], v220 offset:4096
	ds_read_b128 v[192:195], v220 offset:5120
	ds_read_b128 v[196:199], v220 offset:6144
	ds_read_b128 v[200:203], v220 offset:7168
	global_load_lds_dwordx4 v164, s[86:87]
	s_add_i32 m0, s75, 0xe000
	s_nop 0
	global_load_lds_dwordx4 v166, s[86:87]
	s_waitcnt lgkmcnt(0)
	s_barrier
	v_mfma_f32_16x16x32_bf16 v[146:149], v[64:67], v[80:83], v[146:149]
	v_mfma_f32_16x16x32_bf16 v[116:119], v[72:75], v[80:83], v[116:119]
	v_mfma_f32_16x16x32_bf16 v[158:161], v[64:67], v[88:91], v[158:161]
	v_mfma_f32_16x16x32_bf16 v[124:127], v[72:75], v[88:91], v[124:127]
	v_mfma_f32_16x16x32_bf16 v[154:157], v[64:67], v[188:191], v[154:157]
	v_mfma_f32_16x16x32_bf16 v[112:115], v[72:75], v[188:191], v[112:115]
	v_mfma_f32_16x16x32_bf16 v[150:153], v[64:67], v[196:199], v[150:153]
	v_mfma_f32_16x16x32_bf16 v[120:123], v[72:75], v[196:199], v[120:123]
	v_mfma_f32_16x16x32_bf16 v[146:149], v[68:71], v[84:87], v[146:149]
	v_mfma_f32_16x16x32_bf16 v[116:119], v[76:79], v[84:87], v[116:119]
	v_mfma_f32_16x16x32_bf16 v[158:161], v[68:71], v[92:95], v[158:161]
	v_mfma_f32_16x16x32_bf16 v[124:127], v[76:79], v[92:95], v[124:127]
	v_mfma_f32_16x16x32_bf16 v[154:157], v[68:71], v[192:195], v[154:157]
	v_mfma_f32_16x16x32_bf16 v[112:115], v[76:79], v[192:195], v[112:115]
	v_mfma_f32_16x16x32_bf16 v[150:153], v[68:71], v[200:203], v[150:153]
	v_mfma_f32_16x16x32_bf16 v[120:123], v[76:79], v[200:203], v[120:123]
	s_barrier
	s_add_i32 s27, 0, 0x14000
	s_add_i32 s56, s57, s74
	ds_read_b128 v[204:207], v217 offset:16384
	ds_read_b128 v[222:225], v217 offset:17408
	ds_read_b128 v[228:231], v217 offset:18432
	ds_read_b128 v[232:235], v217 offset:19456
	s_mov_b32 m0, s56
	global_load_lds_dwordx4 v144, s[82:83]
	s_add_i32 m0, s56, 0x2000
	s_nop 0
	global_load_lds_dwordx4 v162, s[82:83]
	s_waitcnt lgkmcnt(0)
	s_barrier
	v_mfma_f32_16x16x32_bf16 v[140:143], v[204:207], v[80:83], v[140:143]
	v_mfma_f32_16x16x32_bf16 v[80:83], v[228:231], v[80:83], v[108:111]
	v_mfma_f32_16x16x32_bf16 v[140:143], v[222:225], v[84:87], v[140:143]
	v_mfma_f32_16x16x32_bf16 v[80:83], v[232:235], v[84:87], v[80:83]
	v_mfma_f32_16x16x32_bf16 v[84:87], v[204:207], v[88:91], v[136:139]
	v_mfma_f32_16x16x32_bf16 v[88:91], v[228:231], v[88:91], v[104:107]
	v_mfma_f32_16x16x32_bf16 v[100:103], v[228:231], v[188:191], v[100:103]
	v_mfma_f32_16x16x32_bf16 v[104:107], v[204:207], v[196:199], v[128:131]
	v_mfma_f32_16x16x32_bf16 v[96:99], v[228:231], v[196:199], v[96:99]
	v_mfma_f32_16x16x32_bf16 v[84:87], v[222:225], v[92:95], v[84:87]
	v_mfma_f32_16x16x32_bf16 v[88:91], v[232:235], v[92:95], v[88:91]
	v_mfma_f32_16x16x32_bf16 v[92:95], v[204:207], v[188:191], v[132:135]
	v_mfma_f32_16x16x32_bf16 v[100:103], v[232:235], v[192:195], v[100:103]
	v_mfma_f32_16x16x32_bf16 v[128:131], v[222:225], v[200:203], v[104:107]
	v_mfma_f32_16x16x32_bf16 v[96:99], v[232:235], v[200:203], v[96:99]
	v_mfma_f32_16x16x32_bf16 v[92:95], v[222:225], v[192:195], v[92:95]
	s_barrier
	s_mov_b32 m0, s75
	ds_read_b128 v[104:107], v220 offset:16384
	ds_read_b128 v[108:111], v220 offset:17408
	ds_read_b128 v[132:135], v220 offset:18432
	ds_read_b128 v[136:139], v220 offset:19456
	ds_read_b128 v[188:191], v220 offset:20480
	ds_read_b128 v[192:195], v220 offset:21504
	ds_read_b128 v[196:199], v220 offset:22528
	ds_read_b128 v[200:203], v220 offset:23552
	global_load_lds_dwordx4 v144, vcc
	s_mov_b32 m0, s85
	s_nop 0
	global_load_lds_dwordx4 v162, vcc
	s_waitcnt lgkmcnt(0)
	s_waitcnt vmcnt(8)
	s_barrier
	v_mfma_f32_16x16x32_bf16 v[48:51], v[64:67], v[104:107], v[48:51]
	v_mfma_f32_16x16x32_bf16 v[20:23], v[72:75], v[104:107], v[20:23]
	v_mfma_f32_16x16x32_bf16 v[60:63], v[64:67], v[132:135], v[60:63]
	v_mfma_f32_16x16x32_bf16 v[28:31], v[72:75], v[132:135], v[28:31]
	v_mfma_f32_16x16x32_bf16 v[56:59], v[64:67], v[188:191], v[56:59]
	v_mfma_f32_16x16x32_bf16 v[16:19], v[72:75], v[188:191], v[16:19]
	v_mfma_f32_16x16x32_bf16 v[52:55], v[64:67], v[196:199], v[52:55]
	v_mfma_f32_16x16x32_bf16 v[24:27], v[72:75], v[196:199], v[24:27]
	v_mfma_f32_16x16x32_bf16 v[48:51], v[68:71], v[108:111], v[48:51]
	v_mfma_f32_16x16x32_bf16 v[20:23], v[76:79], v[108:111], v[20:23]
	v_mfma_f32_16x16x32_bf16 v[60:63], v[68:71], v[136:139], v[60:63]
	v_mfma_f32_16x16x32_bf16 v[28:31], v[76:79], v[136:139], v[28:31]
	v_mfma_f32_16x16x32_bf16 v[56:59], v[68:71], v[192:195], v[56:59]
	v_mfma_f32_16x16x32_bf16 v[16:19], v[76:79], v[192:195], v[16:19]
	v_mfma_f32_16x16x32_bf16 v[52:55], v[68:71], v[200:203], v[52:55]
	v_mfma_f32_16x16x32_bf16 v[24:27], v[76:79], v[200:203], v[24:27]
	s_add_u32 s56, s82, 0x40000
	s_addc_u32 s57, s83, 0
	s_add_i32 s27, s27, s74
	s_mov_b32 m0, s27
	s_nop 0
	global_load_lds_dwordx4 v144, s[56:57]
	s_add_i32 m0, s27, 0x2000
	s_nop 0
	global_load_lds_dwordx4 v162, s[56:57]
	s_waitcnt vmcnt(6)
	v_mfma_f32_16x16x32_bf16 v[44:47], v[204:207], v[104:107], v[44:47]
	v_mfma_f32_16x16x32_bf16 v[12:15], v[228:231], v[104:107], v[12:15]
	v_mfma_f32_16x16x32_bf16 v[40:43], v[204:207], v[132:135], v[40:43]
	v_mfma_f32_16x16x32_bf16 v[8:11], v[228:231], v[132:135], v[8:11]
	v_mfma_f32_16x16x32_bf16 v[36:39], v[204:207], v[188:191], v[36:39]
	v_mfma_f32_16x16x32_bf16 v[4:7], v[228:231], v[188:191], v[4:7]
	v_mfma_f32_16x16x32_bf16 v[32:35], v[204:207], v[196:199], v[32:35]
	v_mfma_f32_16x16x32_bf16 v[0:3], v[228:231], v[196:199], v[0:3]
	v_mfma_f32_16x16x32_bf16 v[44:47], v[222:225], v[108:111], v[44:47]
	v_mfma_f32_16x16x32_bf16 v[12:15], v[232:235], v[108:111], v[12:15]
	v_mfma_f32_16x16x32_bf16 v[40:43], v[222:225], v[136:139], v[40:43]
	v_mfma_f32_16x16x32_bf16 v[8:11], v[232:235], v[136:139], v[8:11]
	v_mfma_f32_16x16x32_bf16 v[36:39], v[222:225], v[192:195], v[36:39]
	v_mfma_f32_16x16x32_bf16 v[4:7], v[232:235], v[192:195], v[4:7]
	v_mfma_f32_16x16x32_bf16 v[32:35], v[222:225], v[200:203], v[32:35]
	v_mfma_f32_16x16x32_bf16 v[0:3], v[232:235], v[200:203], v[0:3]
	s_barrier
	s_add_i32 s27, 0, 0x18000
	ds_read_b128 v[64:67], v217 offset:32768
	ds_read_b128 v[68:71], v217 offset:33792
	ds_read_b128 v[72:75], v217 offset:34816
	ds_read_b128 v[76:79], v217 offset:35840
	s_add_u32 s56, vcc_lo, 0x40000
	s_addc_u32 s57, vcc_hi, 0
	s_mov_b32 m0, s98
	ds_read_b128 v[104:107], v220 offset:32768
	ds_read_b128 v[108:111], v220 offset:33792
	ds_read_b128 v[132:135], v220 offset:34816
	ds_read_b128 v[188:191], v220 offset:35840
	ds_read_b128 v[192:195], v220 offset:36864
	ds_read_b128 v[196:199], v220 offset:37888
	ds_read_b128 v[200:203], v220 offset:38912
	ds_read_b128 v[204:207], v220 offset:39936
	global_load_lds_dwordx4 v144, s[56:57]
	s_mov_b32 m0, s29
	s_nop 0
	global_load_lds_dwordx4 v162, s[56:57]
	s_waitcnt lgkmcnt(0)
	s_barrier
	v_mfma_f32_16x16x32_bf16 v[136:139], v[64:67], v[104:107], v[146:149]
	v_mfma_f32_16x16x32_bf16 v[146:149], v[68:71], v[108:111], v[136:139]
	v_mfma_f32_16x16x32_bf16 v[136:139], v[64:67], v[132:135], v[158:161]
	v_mfma_f32_16x16x32_bf16 v[158:161], v[68:71], v[188:191], v[136:139]
	v_mfma_f32_16x16x32_bf16 v[136:139], v[64:67], v[192:195], v[154:157]
	v_mfma_f32_16x16x32_bf16 v[116:119], v[72:75], v[104:107], v[116:119]
	v_mfma_f32_16x16x32_bf16 v[124:127], v[72:75], v[132:135], v[124:127]
	v_mfma_f32_16x16x32_bf16 v[154:157], v[68:71], v[196:199], v[136:139]
	v_mfma_f32_16x16x32_bf16 v[112:115], v[72:75], v[192:195], v[112:115]
	v_mfma_f32_16x16x32_bf16 v[136:139], v[64:67], v[200:203], v[150:153]
	v_mfma_f32_16x16x32_bf16 v[120:123], v[72:75], v[200:203], v[120:123]
	v_mfma_f32_16x16x32_bf16 v[116:119], v[76:79], v[108:111], v[116:119]
	v_mfma_f32_16x16x32_bf16 v[124:127], v[76:79], v[188:191], v[124:127]
	v_mfma_f32_16x16x32_bf16 v[112:115], v[76:79], v[196:199], v[112:115]
	v_mfma_f32_16x16x32_bf16 v[150:153], v[68:71], v[204:207], v[136:139]
	v_mfma_f32_16x16x32_bf16 v[120:123], v[76:79], v[204:207], v[120:123]
	s_barrier
	s_nop 0
	s_add_i32 s58, 0, 0x1c000
	s_add_i32 s27, s27, s74
	ds_read_b128 v[222:225], v217 offset:49152
	ds_read_b128 v[228:231], v217 offset:50176
	ds_read_b128 v[232:235], v217 offset:51200
	ds_read_b128 v[236:239], v217 offset:52224
	s_add_u32 s56, s82, s18
	s_addc_u32 s57, s83, s19
	s_mov_b32 m0, s27
	s_nop 0
	global_load_lds_dwordx4 v144, s[56:57]
	s_add_u32 s56, s82, s18
	s_addc_u32 s57, s83, s19
	s_add_i32 m0, s27, 0x2000
	s_nop 0
	global_load_lds_dwordx4 v162, s[56:57]
	s_waitcnt lgkmcnt(0)
	s_barrier
	v_mfma_f32_16x16x32_bf16 v[136:139], v[222:225], v[104:107], v[140:143]
	v_mfma_f32_16x16x32_bf16 v[80:83], v[232:235], v[104:107], v[80:83]
	v_mfma_f32_16x16x32_bf16 v[140:143], v[228:231], v[108:111], v[136:139]
	v_mfma_f32_16x16x32_bf16 v[108:111], v[236:239], v[108:111], v[80:83]
	v_mfma_f32_16x16x32_bf16 v[80:83], v[222:225], v[132:135], v[84:87]
	v_mfma_f32_16x16x32_bf16 v[136:139], v[228:231], v[188:191], v[80:83]
	v_mfma_f32_16x16x32_bf16 v[80:83], v[232:235], v[132:135], v[88:91]
	v_mfma_f32_16x16x32_bf16 v[104:107], v[236:239], v[188:191], v[80:83]
	v_mfma_f32_16x16x32_bf16 v[80:83], v[222:225], v[192:195], v[92:95]
	v_mfma_f32_16x16x32_bf16 v[132:135], v[228:231], v[196:199], v[80:83]
	v_mfma_f32_16x16x32_bf16 v[80:83], v[232:235], v[192:195], v[100:103]
	v_mfma_f32_16x16x32_bf16 v[100:103], v[236:239], v[196:199], v[80:83]
	v_mfma_f32_16x16x32_bf16 v[80:83], v[222:225], v[200:203], v[128:131]
	v_mfma_f32_16x16x32_bf16 v[128:131], v[228:231], v[204:207], v[80:83]
	v_mfma_f32_16x16x32_bf16 v[80:83], v[232:235], v[200:203], v[96:99]
	v_mfma_f32_16x16x32_bf16 v[96:99], v[236:239], v[204:207], v[80:83]
	s_barrier
	s_nop 0
	s_mov_b32 m0, s31
	s_add_u32 s56, vcc_lo, s18
	s_addc_u32 s57, vcc_hi, s19
	s_nop 2
	ds_read_b128 v[80:83], v220 offset:49152
	ds_read_b128 v[84:87], v220 offset:50176
	ds_read_b128 v[88:91], v220 offset:51200
	ds_read_b128 v[92:95], v220 offset:52224
	ds_read_b128 v[188:191], v220 offset:53248
	ds_read_b128 v[192:195], v220 offset:54272
	ds_read_b128 v[196:199], v220 offset:55296
	ds_read_b128 v[200:203], v220 offset:56320
	global_load_lds_dwordx4 v144, s[56:57]
	s_add_u32 s56, vcc_lo, s18
	s_addc_u32 s57, vcc_hi, s19
	s_mov_b32 m0, s34
	s_nop 0
	global_load_lds_dwordx4 v162, s[56:57]
	s_waitcnt lgkmcnt(0)
	s_waitcnt vmcnt(8)
	s_barrier
	v_mfma_f32_16x16x32_bf16 v[48:51], v[64:67], v[80:83], v[48:51]
	v_mfma_f32_16x16x32_bf16 v[20:23], v[72:75], v[80:83], v[20:23]
	v_mfma_f32_16x16x32_bf16 v[60:63], v[64:67], v[88:91], v[60:63]
	v_mfma_f32_16x16x32_bf16 v[28:31], v[72:75], v[88:91], v[28:31]
	v_mfma_f32_16x16x32_bf16 v[56:59], v[64:67], v[188:191], v[56:59]
	v_mfma_f32_16x16x32_bf16 v[16:19], v[72:75], v[188:191], v[16:19]
	v_mfma_f32_16x16x32_bf16 v[52:55], v[64:67], v[196:199], v[52:55]
	v_mfma_f32_16x16x32_bf16 v[24:27], v[72:75], v[196:199], v[24:27]
	v_mfma_f32_16x16x32_bf16 v[48:51], v[68:71], v[84:87], v[48:51]
	v_mfma_f32_16x16x32_bf16 v[20:23], v[76:79], v[84:87], v[20:23]
	v_mfma_f32_16x16x32_bf16 v[60:63], v[68:71], v[92:95], v[60:63]
	v_mfma_f32_16x16x32_bf16 v[28:31], v[76:79], v[92:95], v[28:31]
	v_mfma_f32_16x16x32_bf16 v[56:59], v[68:71], v[192:195], v[56:59]
	v_mfma_f32_16x16x32_bf16 v[16:19], v[76:79], v[192:195], v[16:19]
	v_mfma_f32_16x16x32_bf16 v[52:55], v[68:71], v[200:203], v[52:55]
	v_mfma_f32_16x16x32_bf16 v[24:27], v[76:79], v[200:203], v[24:27]
	s_add_u32 s56, s82, 0x40080
	s_addc_u32 s57, s83, 0
	s_add_i32 s27, s58, s74
	s_mov_b32 m0, s27
	s_nop 0
	global_load_lds_dwordx4 v144, s[56:57]
	s_add_i32 m0, s27, 0x2000
	s_nop 0
	global_load_lds_dwordx4 v162, s[56:57]
	s_waitcnt vmcnt(6)
	v_mfma_f32_16x16x32_bf16 v[44:47], v[222:225], v[80:83], v[44:47]
	v_mfma_f32_16x16x32_bf16 v[12:15], v[232:235], v[80:83], v[12:15]
	v_mfma_f32_16x16x32_bf16 v[40:43], v[222:225], v[88:91], v[40:43]
	v_mfma_f32_16x16x32_bf16 v[8:11], v[232:235], v[88:91], v[8:11]
	v_mfma_f32_16x16x32_bf16 v[36:39], v[222:225], v[188:191], v[36:39]
	v_mfma_f32_16x16x32_bf16 v[4:7], v[232:235], v[188:191], v[4:7]
	v_mfma_f32_16x16x32_bf16 v[32:35], v[222:225], v[196:199], v[32:35]
	v_mfma_f32_16x16x32_bf16 v[0:3], v[232:235], v[196:199], v[0:3]
	v_mfma_f32_16x16x32_bf16 v[44:47], v[228:231], v[84:87], v[44:47]
	v_mfma_f32_16x16x32_bf16 v[12:15], v[236:239], v[84:87], v[12:15]
	v_mfma_f32_16x16x32_bf16 v[40:43], v[228:231], v[92:95], v[40:43]
	v_mfma_f32_16x16x32_bf16 v[8:11], v[236:239], v[92:95], v[8:11]
	v_mfma_f32_16x16x32_bf16 v[36:39], v[228:231], v[192:195], v[36:39]
	v_mfma_f32_16x16x32_bf16 v[4:7], v[236:239], v[192:195], v[4:7]
	v_mfma_f32_16x16x32_bf16 v[32:35], v[228:231], v[200:203], v[32:35]
	v_mfma_f32_16x16x32_bf16 v[0:3], v[236:239], v[200:203], v[0:3]
	s_barrier
	s_add_i32 s37, s37, 2
	s_add_u32 s86, s86, 0x100
	s_addc_u32 s87, s87, 0
	s_add_u32 s33, s33, 0x100
	s_addc_u32 s36, s36, 0
	s_cmp_gt_u32 s37, 13
	s_cbranch_scc0 .LBB0_125
	s_lshl_b32 s1, s84, 8
	v_readlane_b32 s10, v254, 61
	s_add_i32 s1, s1, s10
	v_or_b32_e32 v198, s1, v216
	s_add_i32 s10, s1, 0x80
	v_or_b32_e32 v168, s10, v216
	v_lshl_or_b32 v188, s0, 7, v219
	v_lshlrev_b32_e32 v190, 2, v188
	v_lshlrev_b32_e32 v189, 1, v188
	s_ashr_i32 s11, s1, 5
	s_movk_i32 s10, 0xb00
	s_movk_i32 s20, 0x1600
	s_mov_b32 s101, 0xbfb8aa3b
	s_cmp_eq_u32 s84, s100
	s_cbranch_scc1 .Ldepi_w
	v_ashrrev_i32_e32 v199, 31, v198
	v_ashrrev_i32_e32 v169, 31, v168
	v_lshl_add_u64 v[170:171], v[198:199], 3, s[48:49]
	v_lshl_add_u64 v[172:173], v[168:169], 3, s[48:49]
	global_load_dwordx2 v[176:177], v[170:171], off
	global_load_dwordx2 v[202:203], v[170:171], off offset:128
	global_load_dwordx2 v[206:207], v[170:171], off offset:256
	global_load_dwordx2 v[222:223], v[170:171], off offset:384
	global_load_dwordx2 v[200:201], v[172:173], off
	global_load_dwordx2 v[196:197], v[172:173], off offset:128
	global_load_dwordx2 v[194:195], v[172:173], off offset:256
	global_load_dwordx2 v[192:193], v[172:173], off offset:384

.LBB0_195:
	s_add_u32 s42, s78, 0x80
	s_addc_u32 s43, s79, 0
	s_add_u32 s33, s44, 0x100
	s_addc_u32 s37, s45, 0
	s_mov_b32 s27, 0
	s_waitcnt lgkmcnt(0)
	s_add_i32 s56, s27, 2
	s_add_u32 s44, s42, 0x80
	s_addc_u32 s45, s43, 0
	s_add_i32 s57, 0, 0x10000
	ds_read_b128 v[128:131], v207
	ds_read_b128 v[132:135], v207 offset:1024
	ds_read_b128 v[136:139], v207 offset:2048
	ds_read_b128 v[140:143], v207 offset:3072
	s_cmp_eq_u32 s82, s27
	s_cselect_b32 s45, s77, s45
	s_cselect_b32 s44, s76, s44
	s_cselect_b32 s79, s1, s37
	s_cselect_b32 s78, s0, s33
	v_lshl_add_u64 v[176:177], s[42:43], 0, v[190:191]
	s_add_i32 m0, s85, 0xc000
	ds_read_b128 v[146:149], v217
	ds_read_b128 v[150:153], v217 offset:1024
	ds_read_b128 v[154:157], v217 offset:2048
	ds_read_b128 v[158:161], v217 offset:3072
	ds_read_b128 v[162:165], v217 offset:4096
	ds_read_b128 v[166:169], v217 offset:5120
	ds_read_b128 v[194:197], v217 offset:6144
	ds_read_b128 v[198:201], v217 offset:7168
	global_load_lds_dwordx4 v[176:177], off
	v_lshl_add_u64 v[176:177], s[42:43], 0, v[192:193]
	s_add_i32 m0, s85, 0xe000
	s_nop 0
	global_load_lds_dwordx4 v[176:177], off
	s_waitcnt lgkmcnt(0)
	s_barrier
	v_mfma_f32_16x16x32_bf16 v[124:127], v[128:131], v[146:149], 0
	v_mfma_f32_16x16x32_bf16 v[120:123], v[136:139], v[146:149], 0
	v_mfma_f32_16x16x32_bf16 v[108:111], v[128:131], v[154:157], 0
	v_mfma_f32_16x16x32_bf16 v[104:107], v[136:139], v[154:157], 0
	v_mfma_f32_16x16x32_bf16 v[92:95], v[128:131], v[162:165], 0
	v_mfma_f32_16x16x32_bf16 v[88:91], v[136:139], v[162:165], 0
	v_mfma_f32_16x16x32_bf16 v[76:79], v[128:131], v[194:197], 0
	v_mfma_f32_16x16x32_bf16 v[72:75], v[136:139], v[194:197], 0
	v_mfma_f32_16x16x32_bf16 v[124:127], v[132:135], v[150:153], v[124:127]
	v_mfma_f32_16x16x32_bf16 v[120:123], v[140:143], v[150:153], v[120:123]
	v_mfma_f32_16x16x32_bf16 v[108:111], v[132:135], v[158:161], v[108:111]
	v_mfma_f32_16x16x32_bf16 v[104:107], v[140:143], v[158:161], v[104:107]
	v_mfma_f32_16x16x32_bf16 v[92:95], v[132:135], v[166:169], v[92:95]
	v_mfma_f32_16x16x32_bf16 v[88:91], v[140:143], v[166:169], v[88:91]
	v_mfma_f32_16x16x32_bf16 v[76:79], v[132:135], v[198:201], v[76:79]
	v_mfma_f32_16x16x32_bf16 v[72:75], v[140:143], v[198:201], v[72:75]
	s_barrier
	s_add_i32 s27, 0, 0x14000
	s_add_i32 s57, s57, s84
	ds_read_b128 v[202:205], v207 offset:16384
	ds_read_b128 v[218:221], v207 offset:17408
	ds_read_b128 v[222:225], v207 offset:18432
	ds_read_b128 v[228:231], v207 offset:19456
	v_lshl_add_u64 v[176:177], s[78:79], 0, v[144:145]
	s_mov_b32 m0, s57
	v_lshl_add_u64 v[232:233], s[78:79], 0, v[188:189]
	global_load_lds_dwordx4 v[176:177], off
	s_add_i32 m0, s57, 0x2000
	s_nop 0
	global_load_lds_dwordx4 v[232:233], off
	s_waitcnt lgkmcnt(0)
	s_barrier
	v_mfma_f32_16x16x32_bf16 v[116:119], v[202:205], v[146:149], 0
	v_mfma_f32_16x16x32_bf16 v[112:115], v[222:225], v[146:149], 0
	v_mfma_f32_16x16x32_bf16 v[100:103], v[202:205], v[154:157], 0
	v_mfma_f32_16x16x32_bf16 v[96:99], v[222:225], v[154:157], 0
	v_mfma_f32_16x16x32_bf16 v[84:87], v[202:205], v[162:165], 0
	v_mfma_f32_16x16x32_bf16 v[80:83], v[222:225], v[162:165], 0
	v_mfma_f32_16x16x32_bf16 v[68:71], v[202:205], v[194:197], 0
	v_mfma_f32_16x16x32_bf16 v[64:67], v[222:225], v[194:197], 0
	v_mfma_f32_16x16x32_bf16 v[116:119], v[218:221], v[150:153], v[116:119]
	v_mfma_f32_16x16x32_bf16 v[112:115], v[228:231], v[150:153], v[112:115]
	v_mfma_f32_16x16x32_bf16 v[100:103], v[218:221], v[158:161], v[100:103]
	v_mfma_f32_16x16x32_bf16 v[96:99], v[228:231], v[158:161], v[96:99]
	v_mfma_f32_16x16x32_bf16 v[84:87], v[218:221], v[166:169], v[84:87]
	v_mfma_f32_16x16x32_bf16 v[80:83], v[228:231], v[166:169], v[80:83]
	v_mfma_f32_16x16x32_bf16 v[68:71], v[218:221], v[198:201], v[68:71]
	v_mfma_f32_16x16x32_bf16 v[64:67], v[228:231], v[198:201], v[64:67]
	s_barrier
	s_mov_b32 m0, s85
	v_lshl_add_u64 v[234:235], s[44:45], 0, v[144:145]
	ds_read_b128 v[146:149], v217 offset:16384
	ds_read_b128 v[150:153], v217 offset:17408
	ds_read_b128 v[154:157], v217 offset:18432
	ds_read_b128 v[158:161], v217 offset:19456
	ds_read_b128 v[162:165], v217 offset:20480
	ds_read_b128 v[166:169], v217 offset:21504
	ds_read_b128 v[194:197], v217 offset:22528
	ds_read_b128 v[198:201], v217 offset:23552
	global_load_lds_dwordx4 v[234:235], off
	v_lshl_add_u64 v[236:237], s[44:45], 0, v[188:189]
	s_mov_b32 m0, s86
	s_nop 0
	global_load_lds_dwordx4 v[236:237], off
	s_waitcnt lgkmcnt(0)
	s_waitcnt vmcnt(8)
	s_barrier
	v_mfma_f32_16x16x32_bf16 v[60:63], v[128:131], v[146:149], 0
	v_mfma_f32_16x16x32_bf16 v[56:59], v[136:139], v[146:149], 0
	v_mfma_f32_16x16x32_bf16 v[44:47], v[128:131], v[154:157], 0
	v_mfma_f32_16x16x32_bf16 v[40:43], v[136:139], v[154:157], 0
	v_mfma_f32_16x16x32_bf16 v[28:31], v[128:131], v[162:165], 0
	v_mfma_f32_16x16x32_bf16 v[24:27], v[136:139], v[162:165], 0
	v_mfma_f32_16x16x32_bf16 v[12:15], v[128:131], v[194:197], 0
	v_mfma_f32_16x16x32_bf16 v[8:11], v[136:139], v[194:197], 0
	v_mfma_f32_16x16x32_bf16 v[60:63], v[132:135], v[150:153], v[60:63]
	v_mfma_f32_16x16x32_bf16 v[56:59], v[140:143], v[150:153], v[56:59]
	v_mfma_f32_16x16x32_bf16 v[44:47], v[132:135], v[158:161], v[44:47]
	v_mfma_f32_16x16x32_bf16 v[40:43], v[140:143], v[158:161], v[40:43]
	v_mfma_f32_16x16x32_bf16 v[28:31], v[132:135], v[166:169], v[28:31]
	v_mfma_f32_16x16x32_bf16 v[24:27], v[140:143], v[166:169], v[24:27]
	v_mfma_f32_16x16x32_bf16 v[12:15], v[132:135], v[198:201], v[12:15]
	v_mfma_f32_16x16x32_bf16 v[8:11], v[140:143], v[198:201], v[8:11]
	s_add_u32 s58, s78, s98
	s_addc_u32 s59, s79, 0
	s_add_i32 s27, s27, s84
	v_lshl_add_u64 v[238:239], s[58:59], 0, v[144:145]
	s_mov_b32 m0, s27
	v_lshl_add_u64 v[240:241], s[58:59], 0, v[188:189]
	global_load_lds_dwordx4 v[238:239], off
	s_add_i32 m0, s27, 0x2000
	s_nop 0
	global_load_lds_dwordx4 v[240:241], off
	s_waitcnt vmcnt(6)
	v_mfma_f32_16x16x32_bf16 v[52:55], v[202:205], v[146:149], 0
	v_mfma_f32_16x16x32_bf16 v[48:51], v[222:225], v[146:149], 0
	v_mfma_f32_16x16x32_bf16 v[36:39], v[202:205], v[154:157], 0
	v_mfma_f32_16x16x32_bf16 v[32:35], v[222:225], v[154:157], 0
	v_mfma_f32_16x16x32_bf16 v[20:23], v[202:205], v[162:165], 0
	v_mfma_f32_16x16x32_bf16 v[16:19], v[222:225], v[162:165], 0
	v_mfma_f32_16x16x32_bf16 v[4:7], v[202:205], v[194:197], 0
	v_mfma_f32_16x16x32_bf16 v[0:3], v[222:225], v[194:197], 0
	v_mfma_f32_16x16x32_bf16 v[52:55], v[218:221], v[150:153], v[52:55]
	v_mfma_f32_16x16x32_bf16 v[48:51], v[228:231], v[150:153], v[48:51]
	v_mfma_f32_16x16x32_bf16 v[36:39], v[218:221], v[158:161], v[36:39]
	v_mfma_f32_16x16x32_bf16 v[32:35], v[228:231], v[158:161], v[32:35]
	v_mfma_f32_16x16x32_bf16 v[20:23], v[218:221], v[166:169], v[20:23]
	v_mfma_f32_16x16x32_bf16 v[16:19], v[228:231], v[166:169], v[16:19]
	v_mfma_f32_16x16x32_bf16 v[4:7], v[218:221], v[198:201], v[4:7]
	v_mfma_f32_16x16x32_bf16 v[0:3], v[228:231], v[198:201], v[0:3]
	s_barrier
	s_nop 0
	s_add_i32 s27, 0, 0x18000
	ds_read_b128 v[128:131], v207 offset:32768
	ds_read_b128 v[132:135], v207 offset:33792
	ds_read_b128 v[136:139], v207 offset:34816
	ds_read_b128 v[140:143], v207 offset:35840
	s_add_u32 s44, s44, s98
	s_addc_u32 s45, s45, 0
	s_mov_b32 m0, s87
	ds_read_b128 v[146:149], v217 offset:32768
	ds_read_b128 v[150:153], v217 offset:33792
	ds_read_b128 v[154:157], v217 offset:34816
	ds_read_b128 v[158:161], v217 offset:35840
	ds_read_b128 v[162:165], v217 offset:36864
	ds_read_b128 v[166:169], v217 offset:37888
	ds_read_b128 v[194:197], v217 offset:38912
	ds_read_b128 v[198:201], v217 offset:39936
	global_load_lds_dwordx4 v144, s[44:45]
	s_mov_b32 m0, s80
	s_nop 0
	global_load_lds_dwordx4 v188, s[44:45]
	s_waitcnt lgkmcnt(0)
	s_barrier
	v_mfma_f32_16x16x32_bf16 v[124:127], v[128:131], v[146:149], v[124:127]
	v_mfma_f32_16x16x32_bf16 v[120:123], v[136:139], v[146:149], v[120:123]
	v_mfma_f32_16x16x32_bf16 v[108:111], v[128:131], v[154:157], v[108:111]
	v_mfma_f32_16x16x32_bf16 v[104:107], v[136:139], v[154:157], v[104:107]
	v_mfma_f32_16x16x32_bf16 v[92:95], v[128:131], v[162:165], v[92:95]
	v_mfma_f32_16x16x32_bf16 v[88:91], v[136:139], v[162:165], v[88:91]
	v_mfma_f32_16x16x32_bf16 v[76:79], v[128:131], v[194:197], v[76:79]
	v_mfma_f32_16x16x32_bf16 v[72:75], v[136:139], v[194:197], v[72:75]
	v_mfma_f32_16x16x32_bf16 v[124:127], v[132:135], v[150:153], v[124:127]
	v_mfma_f32_16x16x32_bf16 v[120:123], v[140:143], v[150:153], v[120:123]
	v_mfma_f32_16x16x32_bf16 v[108:111], v[132:135], v[158:161], v[108:111]
	v_mfma_f32_16x16x32_bf16 v[104:107], v[140:143], v[158:161], v[104:107]
	v_mfma_f32_16x16x32_bf16 v[92:95], v[132:135], v[166:169], v[92:95]
	v_mfma_f32_16x16x32_bf16 v[88:91], v[140:143], v[166:169], v[88:91]
	v_mfma_f32_16x16x32_bf16 v[76:79], v[132:135], v[198:201], v[76:79]
	v_mfma_f32_16x16x32_bf16 v[72:75], v[140:143], v[198:201], v[72:75]
	s_barrier
	s_add_i32 s44, 0, 0x1c000
	s_add_i32 s27, s27, s84
	v_lshl_add_u64 v[176:177], v[176:177], 0, s[18:19]
	s_mov_b32 m0, s27
	ds_read_b128 v[202:205], v207 offset:49152
	ds_read_b128 v[218:221], v207 offset:50176
	ds_read_b128 v[222:225], v207 offset:51200
	ds_read_b128 v[228:231], v207 offset:52224
	global_load_lds_dwordx4 v[176:177], off
	v_lshl_add_u64 v[176:177], v[232:233], 0, s[18:19]
	s_add_i32 m0, s27, 0x2000
	s_nop 0
	global_load_lds_dwordx4 v[176:177], off
	s_waitcnt lgkmcnt(0)
	s_barrier
	v_mfma_f32_16x16x32_bf16 v[116:119], v[202:205], v[146:149], v[116:119]
	v_mfma_f32_16x16x32_bf16 v[112:115], v[222:225], v[146:149], v[112:115]
	v_mfma_f32_16x16x32_bf16 v[100:103], v[202:205], v[154:157], v[100:103]
	v_mfma_f32_16x16x32_bf16 v[96:99], v[222:225], v[154:157], v[96:99]
	v_mfma_f32_16x16x32_bf16 v[84:87], v[202:205], v[162:165], v[84:87]
	v_mfma_f32_16x16x32_bf16 v[80:83], v[222:225], v[162:165], v[80:83]
	v_mfma_f32_16x16x32_bf16 v[68:71], v[202:205], v[194:197], v[68:71]
	v_mfma_f32_16x16x32_bf16 v[64:67], v[222:225], v[194:197], v[64:67]
	v_mfma_f32_16x16x32_bf16 v[116:119], v[218:221], v[150:153], v[116:119]
	v_mfma_f32_16x16x32_bf16 v[112:115], v[228:231], v[150:153], v[112:115]
	v_mfma_f32_16x16x32_bf16 v[100:103], v[218:221], v[158:161], v[100:103]
	v_mfma_f32_16x16x32_bf16 v[96:99], v[228:231], v[158:161], v[96:99]
	v_mfma_f32_16x16x32_bf16 v[84:87], v[218:221], v[166:169], v[84:87]
	v_mfma_f32_16x16x32_bf16 v[80:83], v[228:231], v[166:169], v[80:83]
	v_mfma_f32_16x16x32_bf16 v[68:71], v[218:221], v[198:201], v[68:71]
	v_mfma_f32_16x16x32_bf16 v[64:67], v[228:231], v[198:201], v[64:67]
	s_barrier
	s_mov_b32 m0, s30
	v_lshl_add_u64 v[176:177], v[234:235], 0, s[18:19]
	ds_read_b128 v[146:149], v217 offset:49152
	ds_read_b128 v[150:153], v217 offset:50176
	ds_read_b128 v[154:157], v217 offset:51200
	ds_read_b128 v[158:161], v217 offset:52224
	ds_read_b128 v[162:165], v217 offset:53248
	ds_read_b128 v[166:169], v217 offset:54272
	ds_read_b128 v[194:197], v217 offset:55296
	ds_read_b128 v[198:201], v217 offset:56320
	global_load_lds_dwordx4 v[176:177], off
	v_lshl_add_u64 v[176:177], v[236:237], 0, s[18:19]
	s_mov_b32 m0, s31
	s_nop 0
	global_load_lds_dwordx4 v[176:177], off
	s_waitcnt lgkmcnt(0)
	s_waitcnt vmcnt(8)
	s_barrier
	v_mfma_f32_16x16x32_bf16 v[60:63], v[128:131], v[146:149], v[60:63]
	v_mfma_f32_16x16x32_bf16 v[56:59], v[136:139], v[146:149], v[56:59]
	v_mfma_f32_16x16x32_bf16 v[44:47], v[128:131], v[154:157], v[44:47]
	v_mfma_f32_16x16x32_bf16 v[40:43], v[136:139], v[154:157], v[40:43]
	v_mfma_f32_16x16x32_bf16 v[28:31], v[128:131], v[162:165], v[28:31]
	v_mfma_f32_16x16x32_bf16 v[24:27], v[136:139], v[162:165], v[24:27]
	v_mfma_f32_16x16x32_bf16 v[12:15], v[128:131], v[194:197], v[12:15]
	v_mfma_f32_16x16x32_bf16 v[8:11], v[136:139], v[194:197], v[8:11]
	v_mfma_f32_16x16x32_bf16 v[60:63], v[132:135], v[150:153], v[60:63]
	v_mfma_f32_16x16x32_bf16 v[56:59], v[140:143], v[150:153], v[56:59]
	v_mfma_f32_16x16x32_bf16 v[44:47], v[132:135], v[158:161], v[44:47]
	v_mfma_f32_16x16x32_bf16 v[40:43], v[140:143], v[158:161], v[40:43]
	v_mfma_f32_16x16x32_bf16 v[28:31], v[132:135], v[166:169], v[28:31]
	v_mfma_f32_16x16x32_bf16 v[24:27], v[140:143], v[166:169], v[24:27]
	v_mfma_f32_16x16x32_bf16 v[12:15], v[132:135], v[198:201], v[12:15]
	v_mfma_f32_16x16x32_bf16 v[8:11], v[140:143], v[198:201], v[8:11]
	s_nop 0
	s_add_i32 s27, s44, s84
	v_lshl_add_u64 v[128:129], v[238:239], 0, s[18:19]
	s_mov_b32 m0, s27
	s_nop 0
	global_load_lds_dwordx4 v[128:129], off
	v_lshl_add_u64 v[128:129], v[240:241], 0, s[18:19]
	s_add_i32 m0, s27, 0x2000
	s_nop 0
	global_load_lds_dwordx4 v[128:129], off
	s_waitcnt vmcnt(6)
	v_mfma_f32_16x16x32_bf16 v[52:55], v[202:205], v[146:149], v[52:55]
	v_mfma_f32_16x16x32_bf16 v[48:51], v[222:225], v[146:149], v[48:51]
	v_mfma_f32_16x16x32_bf16 v[36:39], v[202:205], v[154:157], v[36:39]
	v_mfma_f32_16x16x32_bf16 v[32:35], v[222:225], v[154:157], v[32:35]
	v_mfma_f32_16x16x32_bf16 v[20:23], v[202:205], v[162:165], v[20:23]
	v_mfma_f32_16x16x32_bf16 v[16:19], v[222:225], v[162:165], v[16:19]
	v_mfma_f32_16x16x32_bf16 v[4:7], v[202:205], v[194:197], v[4:7]
	v_mfma_f32_16x16x32_bf16 v[0:3], v[222:225], v[194:197], v[0:3]
	v_mfma_f32_16x16x32_bf16 v[52:55], v[218:221], v[150:153], v[52:55]
	v_mfma_f32_16x16x32_bf16 v[48:51], v[228:231], v[150:153], v[48:51]
	v_mfma_f32_16x16x32_bf16 v[36:39], v[218:221], v[158:161], v[36:39]
	v_mfma_f32_16x16x32_bf16 v[32:35], v[228:231], v[158:161], v[32:35]
	v_mfma_f32_16x16x32_bf16 v[20:23], v[218:221], v[166:169], v[20:23]
	v_mfma_f32_16x16x32_bf16 v[16:19], v[228:231], v[166:169], v[16:19]
	v_mfma_f32_16x16x32_bf16 v[4:7], v[218:221], v[198:201], v[4:7]
	v_mfma_f32_16x16x32_bf16 v[0:3], v[228:231], v[198:201], v[0:3]
	s_barrier
	s_add_u32 s42, s42, 0x100
	s_addc_u32 s43, s43, 0
	s_add_u32 s33, s33, 0x100
	s_addc_u32 s37, s37, 0
	s_cmp_ge_u32 s56, s34
	s_mov_b32 s27, s56
.LBB0_196:
	s_add_i32 s56, s27, 2
	s_add_u32 s44, s42, 0x80
	s_addc_u32 s45, s43, 0
	s_add_i32 s57, 0, 0x10000
	ds_read_b128 v[128:131], v207
	ds_read_b128 v[132:135], v207 offset:1024
	ds_read_b128 v[136:139], v207 offset:2048
	ds_read_b128 v[140:143], v207 offset:3072
	s_cmp_eq_u32 s82, s27
	s_cselect_b32 s45, s77, s45
	s_cselect_b32 s44, s76, s44
	s_cselect_b32 s79, s1, s37
	s_cselect_b32 s78, s0, s33
	v_lshl_add_u64 v[176:177], s[42:43], 0, v[190:191]
	s_add_i32 m0, s85, 0xc000
	ds_read_b128 v[146:149], v217
	ds_read_b128 v[150:153], v217 offset:1024
	ds_read_b128 v[154:157], v217 offset:2048
	ds_read_b128 v[158:161], v217 offset:3072
	ds_read_b128 v[162:165], v217 offset:4096
	ds_read_b128 v[166:169], v217 offset:5120
	ds_read_b128 v[194:197], v217 offset:6144
	ds_read_b128 v[198:201], v217 offset:7168
	global_load_lds_dwordx4 v[176:177], off
	v_lshl_add_u64 v[176:177], s[42:43], 0, v[192:193]
	s_add_i32 m0, s85, 0xe000
	s_nop 0
	global_load_lds_dwordx4 v[176:177], off
	s_waitcnt lgkmcnt(0)
	s_barrier
	v_mfma_f32_16x16x32_bf16 v[124:127], v[128:131], v[146:149], v[124:127]
	v_mfma_f32_16x16x32_bf16 v[120:123], v[136:139], v[146:149], v[120:123]
	v_mfma_f32_16x16x32_bf16 v[108:111], v[128:131], v[154:157], v[108:111]
	v_mfma_f32_16x16x32_bf16 v[104:107], v[136:139], v[154:157], v[104:107]
	v_mfma_f32_16x16x32_bf16 v[92:95], v[128:131], v[162:165], v[92:95]
	v_mfma_f32_16x16x32_bf16 v[88:91], v[136:139], v[162:165], v[88:91]
	v_mfma_f32_16x16x32_bf16 v[76:79], v[128:131], v[194:197], v[76:79]
	v_mfma_f32_16x16x32_bf16 v[72:75], v[136:139], v[194:197], v[72:75]
	v_mfma_f32_16x16x32_bf16 v[124:127], v[132:135], v[150:153], v[124:127]
	v_mfma_f32_16x16x32_bf16 v[120:123], v[140:143], v[150:153], v[120:123]
	v_mfma_f32_16x16x32_bf16 v[108:111], v[132:135], v[158:161], v[108:111]
	v_mfma_f32_16x16x32_bf16 v[104:107], v[140:143], v[158:161], v[104:107]
	v_mfma_f32_16x16x32_bf16 v[92:95], v[132:135], v[166:169], v[92:95]
	v_mfma_f32_16x16x32_bf16 v[88:91], v[140:143], v[166:169], v[88:91]
	v_mfma_f32_16x16x32_bf16 v[76:79], v[132:135], v[198:201], v[76:79]
	v_mfma_f32_16x16x32_bf16 v[72:75], v[140:143], v[198:201], v[72:75]
	s_barrier
	s_add_i32 s27, 0, 0x14000
	s_add_i32 s57, s57, s84
	ds_read_b128 v[202:205], v207 offset:16384
	ds_read_b128 v[218:221], v207 offset:17408
	ds_read_b128 v[222:225], v207 offset:18432
	ds_read_b128 v[228:231], v207 offset:19456
	v_lshl_add_u64 v[176:177], s[78:79], 0, v[144:145]
	s_mov_b32 m0, s57
	v_lshl_add_u64 v[232:233], s[78:79], 0, v[188:189]
	global_load_lds_dwordx4 v[176:177], off
	s_add_i32 m0, s57, 0x2000
	s_nop 0
	global_load_lds_dwordx4 v[232:233], off
	s_waitcnt lgkmcnt(0)
	s_barrier
	v_mfma_f32_16x16x32_bf16 v[116:119], v[202:205], v[146:149], v[116:119]
	v_mfma_f32_16x16x32_bf16 v[112:115], v[222:225], v[146:149], v[112:115]
	v_mfma_f32_16x16x32_bf16 v[100:103], v[202:205], v[154:157], v[100:103]
	v_mfma_f32_16x16x32_bf16 v[96:99], v[222:225], v[154:157], v[96:99]
	v_mfma_f32_16x16x32_bf16 v[84:87], v[202:205], v[162:165], v[84:87]
	v_mfma_f32_16x16x32_bf16 v[80:83], v[222:225], v[162:165], v[80:83]
	v_mfma_f32_16x16x32_bf16 v[68:71], v[202:205], v[194:197], v[68:71]
	v_mfma_f32_16x16x32_bf16 v[64:67], v[222:225], v[194:197], v[64:67]
	v_mfma_f32_16x16x32_bf16 v[116:119], v[218:221], v[150:153], v[116:119]
	v_mfma_f32_16x16x32_bf16 v[112:115], v[228:231], v[150:153], v[112:115]
	v_mfma_f32_16x16x32_bf16 v[100:103], v[218:221], v[158:161], v[100:103]
	v_mfma_f32_16x16x32_bf16 v[96:99], v[228:231], v[158:161], v[96:99]
	v_mfma_f32_16x16x32_bf16 v[84:87], v[218:221], v[166:169], v[84:87]
	v_mfma_f32_16x16x32_bf16 v[80:83], v[228:231], v[166:169], v[80:83]
	v_mfma_f32_16x16x32_bf16 v[68:71], v[218:221], v[198:201], v[68:71]
	v_mfma_f32_16x16x32_bf16 v[64:67], v[228:231], v[198:201], v[64:67]
	s_barrier
	s_mov_b32 m0, s85
	v_lshl_add_u64 v[234:235], s[44:45], 0, v[144:145]
	ds_read_b128 v[146:149], v217 offset:16384
	ds_read_b128 v[150:153], v217 offset:17408
	ds_read_b128 v[154:157], v217 offset:18432
	ds_read_b128 v[158:161], v217 offset:19456
	ds_read_b128 v[162:165], v217 offset:20480
	ds_read_b128 v[166:169], v217 offset:21504
	ds_read_b128 v[194:197], v217 offset:22528
	ds_read_b128 v[198:201], v217 offset:23552
	global_load_lds_dwordx4 v[234:235], off
	v_lshl_add_u64 v[236:237], s[44:45], 0, v[188:189]
	s_mov_b32 m0, s86
	s_nop 0
	global_load_lds_dwordx4 v[236:237], off
	s_waitcnt lgkmcnt(0)
	s_waitcnt vmcnt(8)
	s_barrier
	v_mfma_f32_16x16x32_bf16 v[60:63], v[128:131], v[146:149], v[60:63]
	v_mfma_f32_16x16x32_bf16 v[56:59], v[136:139], v[146:149], v[56:59]
	v_mfma_f32_16x16x32_bf16 v[44:47], v[128:131], v[154:157], v[44:47]
	v_mfma_f32_16x16x32_bf16 v[40:43], v[136:139], v[154:157], v[40:43]
	v_mfma_f32_16x16x32_bf16 v[28:31], v[128:131], v[162:165], v[28:31]
	v_mfma_f32_16x16x32_bf16 v[24:27], v[136:139], v[162:165], v[24:27]
	v_mfma_f32_16x16x32_bf16 v[12:15], v[128:131], v[194:197], v[12:15]
	v_mfma_f32_16x16x32_bf16 v[8:11], v[136:139], v[194:197], v[8:11]
	v_mfma_f32_16x16x32_bf16 v[60:63], v[132:135], v[150:153], v[60:63]
	v_mfma_f32_16x16x32_bf16 v[56:59], v[140:143], v[150:153], v[56:59]
	v_mfma_f32_16x16x32_bf16 v[44:47], v[132:135], v[158:161], v[44:47]
	v_mfma_f32_16x16x32_bf16 v[40:43], v[140:143], v[158:161], v[40:43]
	v_mfma_f32_16x16x32_bf16 v[28:31], v[132:135], v[166:169], v[28:31]
	v_mfma_f32_16x16x32_bf16 v[24:27], v[140:143], v[166:169], v[24:27]
	v_mfma_f32_16x16x32_bf16 v[12:15], v[132:135], v[198:201], v[12:15]
	v_mfma_f32_16x16x32_bf16 v[8:11], v[140:143], v[198:201], v[8:11]
	s_add_u32 s58, s78, s98
	s_addc_u32 s59, s79, 0
	s_add_i32 s27, s27, s84
	v_lshl_add_u64 v[238:239], s[58:59], 0, v[144:145]
	s_mov_b32 m0, s27
	v_lshl_add_u64 v[240:241], s[58:59], 0, v[188:189]
	global_load_lds_dwordx4 v[238:239], off
	s_add_i32 m0, s27, 0x2000
	s_nop 0
	global_load_lds_dwordx4 v[240:241], off
	s_waitcnt vmcnt(6)
	v_mfma_f32_16x16x32_bf16 v[52:55], v[202:205], v[146:149], v[52:55]
	v_mfma_f32_16x16x32_bf16 v[48:51], v[222:225], v[146:149], v[48:51]
	v_mfma_f32_16x16x32_bf16 v[36:39], v[202:205], v[154:157], v[36:39]
	v_mfma_f32_16x16x32_bf16 v[32:35], v[222:225], v[154:157], v[32:35]
	v_mfma_f32_16x16x32_bf16 v[20:23], v[202:205], v[162:165], v[20:23]
	v_mfma_f32_16x16x32_bf16 v[16:19], v[222:225], v[162:165], v[16:19]
	v_mfma_f32_16x16x32_bf16 v[4:7], v[202:205], v[194:197], v[4:7]
	v_mfma_f32_16x16x32_bf16 v[0:3], v[222:225], v[194:197], v[0:3]
	v_mfma_f32_16x16x32_bf16 v[52:55], v[218:221], v[150:153], v[52:55]
	v_mfma_f32_16x16x32_bf16 v[48:51], v[228:231], v[150:153], v[48:51]
	v_mfma_f32_16x16x32_bf16 v[36:39], v[218:221], v[158:161], v[36:39]
	v_mfma_f32_16x16x32_bf16 v[32:35], v[228:231], v[158:161], v[32:35]
	v_mfma_f32_16x16x32_bf16 v[20:23], v[218:221], v[166:169], v[20:23]
	v_mfma_f32_16x16x32_bf16 v[16:19], v[228:231], v[166:169], v[16:19]
	v_mfma_f32_16x16x32_bf16 v[4:7], v[218:221], v[198:201], v[4:7]
	v_mfma_f32_16x16x32_bf16 v[0:3], v[228:231], v[198:201], v[0:3]
	s_barrier
	s_nop 0
	s_add_i32 s27, 0, 0x18000
	ds_read_b128 v[128:131], v207 offset:32768
	ds_read_b128 v[132:135], v207 offset:33792
	ds_read_b128 v[136:139], v207 offset:34816
	ds_read_b128 v[140:143], v207 offset:35840
	s_add_u32 s44, s44, s98
	s_addc_u32 s45, s45, 0
	s_mov_b32 m0, s87
	ds_read_b128 v[146:149], v217 offset:32768
	ds_read_b128 v[150:153], v217 offset:33792
	ds_read_b128 v[154:157], v217 offset:34816
	ds_read_b128 v[158:161], v217 offset:35840
	ds_read_b128 v[162:165], v217 offset:36864
	ds_read_b128 v[166:169], v217 offset:37888
	ds_read_b128 v[194:197], v217 offset:38912
	ds_read_b128 v[198:201], v217 offset:39936
	global_load_lds_dwordx4 v144, s[44:45]
	s_mov_b32 m0, s80
	s_nop 0
	global_load_lds_dwordx4 v188, s[44:45]
	s_waitcnt lgkmcnt(0)
	s_barrier
	v_mfma_f32_16x16x32_bf16 v[124:127], v[128:131], v[146:149], v[124:127]
	v_mfma_f32_16x16x32_bf16 v[120:123], v[136:139], v[146:149], v[120:123]
	v_mfma_f32_16x16x32_bf16 v[108:111], v[128:131], v[154:157], v[108:111]
	v_mfma_f32_16x16x32_bf16 v[104:107], v[136:139], v[154:157], v[104:107]
	v_mfma_f32_16x16x32_bf16 v[92:95], v[128:131], v[162:165], v[92:95]
	v_mfma_f32_16x16x32_bf16 v[88:91], v[136:139], v[162:165], v[88:91]
	v_mfma_f32_16x16x32_bf16 v[76:79], v[128:131], v[194:197], v[76:79]
	v_mfma_f32_16x16x32_bf16 v[72:75], v[136:139], v[194:197], v[72:75]
	v_mfma_f32_16x16x32_bf16 v[124:127], v[132:135], v[150:153], v[124:127]
	v_mfma_f32_16x16x32_bf16 v[120:123], v[140:143], v[150:153], v[120:123]
	v_mfma_f32_16x16x32_bf16 v[108:111], v[132:135], v[158:161], v[108:111]
	v_mfma_f32_16x16x32_bf16 v[104:107], v[140:143], v[158:161], v[104:107]
	v_mfma_f32_16x16x32_bf16 v[92:95], v[132:135], v[166:169], v[92:95]
	v_mfma_f32_16x16x32_bf16 v[88:91], v[140:143], v[166:169], v[88:91]
	v_mfma_f32_16x16x32_bf16 v[76:79], v[132:135], v[198:201], v[76:79]
	v_mfma_f32_16x16x32_bf16 v[72:75], v[140:143], v[198:201], v[72:75]
	s_barrier
	s_add_i32 s44, 0, 0x1c000
	s_add_i32 s27, s27, s84
	v_lshl_add_u64 v[176:177], v[176:177], 0, s[18:19]
	s_mov_b32 m0, s27
	ds_read_b128 v[202:205], v207 offset:49152
	ds_read_b128 v[218:221], v207 offset:50176
	ds_read_b128 v[222:225], v207 offset:51200
	ds_read_b128 v[228:231], v207 offset:52224
	global_load_lds_dwordx4 v[176:177], off
	v_lshl_add_u64 v[176:177], v[232:233], 0, s[18:19]
	s_add_i32 m0, s27, 0x2000
	s_nop 0
	global_load_lds_dwordx4 v[176:177], off
	s_waitcnt lgkmcnt(0)
	s_barrier
	v_mfma_f32_16x16x32_bf16 v[116:119], v[202:205], v[146:149], v[116:119]
	v_mfma_f32_16x16x32_bf16 v[112:115], v[222:225], v[146:149], v[112:115]
	v_mfma_f32_16x16x32_bf16 v[100:103], v[202:205], v[154:157], v[100:103]
	v_mfma_f32_16x16x32_bf16 v[96:99], v[222:225], v[154:157], v[96:99]
	v_mfma_f32_16x16x32_bf16 v[84:87], v[202:205], v[162:165], v[84:87]
	v_mfma_f32_16x16x32_bf16 v[80:83], v[222:225], v[162:165], v[80:83]
	v_mfma_f32_16x16x32_bf16 v[68:71], v[202:205], v[194:197], v[68:71]
	v_mfma_f32_16x16x32_bf16 v[64:67], v[222:225], v[194:197], v[64:67]
	v_mfma_f32_16x16x32_bf16 v[116:119], v[218:221], v[150:153], v[116:119]
	v_mfma_f32_16x16x32_bf16 v[112:115], v[228:231], v[150:153], v[112:115]
	v_mfma_f32_16x16x32_bf16 v[100:103], v[218:221], v[158:161], v[100:103]
	v_mfma_f32_16x16x32_bf16 v[96:99], v[228:231], v[158:161], v[96:99]
	v_mfma_f32_16x16x32_bf16 v[84:87], v[218:221], v[166:169], v[84:87]
	v_mfma_f32_16x16x32_bf16 v[80:83], v[228:231], v[166:169], v[80:83]
	v_mfma_f32_16x16x32_bf16 v[68:71], v[218:221], v[198:201], v[68:71]
	v_mfma_f32_16x16x32_bf16 v[64:67], v[228:231], v[198:201], v[64:67]
	s_barrier
	s_mov_b32 m0, s30
	v_lshl_add_u64 v[176:177], v[234:235], 0, s[18:19]
	ds_read_b128 v[146:149], v217 offset:49152
	ds_read_b128 v[150:153], v217 offset:50176
	ds_read_b128 v[154:157], v217 offset:51200
	ds_read_b128 v[158:161], v217 offset:52224
	ds_read_b128 v[162:165], v217 offset:53248
	ds_read_b128 v[166:169], v217 offset:54272
	ds_read_b128 v[194:197], v217 offset:55296
	ds_read_b128 v[198:201], v217 offset:56320
	global_load_lds_dwordx4 v[176:177], off
	v_lshl_add_u64 v[176:177], v[236:237], 0, s[18:19]
	s_mov_b32 m0, s31
	s_nop 0
	global_load_lds_dwordx4 v[176:177], off
	s_waitcnt lgkmcnt(0)
	s_waitcnt vmcnt(8)
	s_barrier
	v_mfma_f32_16x16x32_bf16 v[60:63], v[128:131], v[146:149], v[60:63]
	v_mfma_f32_16x16x32_bf16 v[56:59], v[136:139], v[146:149], v[56:59]
	v_mfma_f32_16x16x32_bf16 v[44:47], v[128:131], v[154:157], v[44:47]
	v_mfma_f32_16x16x32_bf16 v[40:43], v[136:139], v[154:157], v[40:43]
	v_mfma_f32_16x16x32_bf16 v[28:31], v[128:131], v[162:165], v[28:31]
	v_mfma_f32_16x16x32_bf16 v[24:27], v[136:139], v[162:165], v[24:27]
	v_mfma_f32_16x16x32_bf16 v[12:15], v[128:131], v[194:197], v[12:15]
	v_mfma_f32_16x16x32_bf16 v[8:11], v[136:139], v[194:197], v[8:11]
	v_mfma_f32_16x16x32_bf16 v[60:63], v[132:135], v[150:153], v[60:63]
	v_mfma_f32_16x16x32_bf16 v[56:59], v[140:143], v[150:153], v[56:59]
	v_mfma_f32_16x16x32_bf16 v[44:47], v[132:135], v[158:161], v[44:47]
	v_mfma_f32_16x16x32_bf16 v[40:43], v[140:143], v[158:161], v[40:43]
	v_mfma_f32_16x16x32_bf16 v[28:31], v[132:135], v[166:169], v[28:31]
	v_mfma_f32_16x16x32_bf16 v[24:27], v[140:143], v[166:169], v[24:27]
	v_mfma_f32_16x16x32_bf16 v[12:15], v[132:135], v[198:201], v[12:15]
	v_mfma_f32_16x16x32_bf16 v[8:11], v[140:143], v[198:201], v[8:11]
	s_nop 0
	s_add_i32 s27, s44, s84
	v_lshl_add_u64 v[128:129], v[238:239], 0, s[18:19]
	s_mov_b32 m0, s27
	s_nop 0
	global_load_lds_dwordx4 v[128:129], off
	v_lshl_add_u64 v[128:129], v[240:241], 0, s[18:19]
	s_add_i32 m0, s27, 0x2000
	s_nop 0
	global_load_lds_dwordx4 v[128:129], off
	s_waitcnt vmcnt(6)
	v_mfma_f32_16x16x32_bf16 v[52:55], v[202:205], v[146:149], v[52:55]
	v_mfma_f32_16x16x32_bf16 v[48:51], v[222:225], v[146:149], v[48:51]
	v_mfma_f32_16x16x32_bf16 v[36:39], v[202:205], v[154:157], v[36:39]
	v_mfma_f32_16x16x32_bf16 v[32:35], v[222:225], v[154:157], v[32:35]
	v_mfma_f32_16x16x32_bf16 v[20:23], v[202:205], v[162:165], v[20:23]
	v_mfma_f32_16x16x32_bf16 v[16:19], v[222:225], v[162:165], v[16:19]
	v_mfma_f32_16x16x32_bf16 v[4:7], v[202:205], v[194:197], v[4:7]
	v_mfma_f32_16x16x32_bf16 v[0:3], v[222:225], v[194:197], v[0:3]
	v_mfma_f32_16x16x32_bf16 v[52:55], v[218:221], v[150:153], v[52:55]
	v_mfma_f32_16x16x32_bf16 v[48:51], v[228:231], v[150:153], v[48:51]
	v_mfma_f32_16x16x32_bf16 v[36:39], v[218:221], v[158:161], v[36:39]
	v_mfma_f32_16x16x32_bf16 v[32:35], v[228:231], v[158:161], v[32:35]
	v_mfma_f32_16x16x32_bf16 v[20:23], v[218:221], v[166:169], v[20:23]
	v_mfma_f32_16x16x32_bf16 v[16:19], v[228:231], v[166:169], v[16:19]
	v_mfma_f32_16x16x32_bf16 v[4:7], v[218:221], v[198:201], v[4:7]
	v_mfma_f32_16x16x32_bf16 v[0:3], v[228:231], v[198:201], v[0:3]
	s_barrier
	s_add_u32 s42, s42, 0x100
	s_addc_u32 s43, s43, 0
	s_add_u32 s33, s33, 0x100
	s_addc_u32 s37, s37, 0
	s_cmp_ge_u32 s56, s34
	s_mov_b32 s27, s56
	s_cbranch_scc0 .LBB0_196
	v_lshl_add_u32 v194, s11, 8, v206
	v_ashrrev_i32_e32 v195, 31, v194
	v_lshl_or_b32 v196, s10, 8, v216
	v_lshlrev_b64 v[128:129], 11, v[194:195]
	v_ashrrev_i32_e32 v197, 31, v196
	s_and_b64 vcc, exec, s[92:93]
	v_or_b32_e32 v198, 16, v194
	v_lshl_add_u64 v[200:201], s[54:55], 0, v[128:129]
	s_cbranch_vccz .LBB0_215
	v_lshlrev_b64 v[128:129], 12, v[194:195]
	v_lshl_add_u64 v[128:129], s[50:51], 0, v[128:129]
	v_lshlrev_b64 v[130:131], 2, v[196:197]
	v_lshl_add_u64 v[128:129], v[128:129], 0, v[130:131]
	global_load_dwordx4 v[146:149], v[128:129], off offset:16
	global_load_dwordx4 v[150:153], v[128:129], off
	global_load_dwordx4 v[154:157], v[128:129], off offset:528
	global_load_dwordx4 v[158:161], v[128:129], off offset:512
	v_ashrrev_i32_e32 v199, 31, v198
	v_lshlrev_b64 v[128:129], 12, v[198:199]
	v_lshl_add_u64 v[128:129], s[50:51], 0, v[128:129]
	v_lshl_add_u64 v[132:133], v[128:129], 0, v[130:131]
	global_load_dwordx4 v[136:139], v[132:133], off offset:16
	global_load_dwordx4 v[140:143], v[132:133], off
	global_load_dwordx4 v[128:131], v[132:133], off offset:528
	s_nop 0
	global_load_dwordx4 v[132:135], v[132:133], off offset:512
	v_lshl_add_u64 v[166:167], v[196:197], 1, v[200:201]
	s_waitcnt vmcnt(0)
	v_pk_add_f32 v[164:165], v[120:121], v[146:147]
	v_pk_add_f32 v[152:153], v[126:127], v[152:153]
	v_pk_add_f32 v[150:151], v[124:125], v[150:151]
	v_pk_add_f32 v[162:163], v[122:123], v[148:149]
	v_cvt_pk_bf16_f32 v146, v150, v151
	v_cvt_pk_bf16_f32 v147, v152, v153
	v_cvt_pk_bf16_f32 v148, v164, v165
	v_pk_add_f32 v[156:157], v[114:115], v[156:157]
	v_cvt_pk_bf16_f32 v149, v162, v163
	global_store_dwordx4 v[166:167], v[146:149], off
	v_pk_add_f32 v[154:155], v[112:113], v[154:155]
	s_nop 0
	v_mul_f32_e32 v146, v151, v151
	v_mul_f32_e32 v147, v153, v153
	v_fmac_f32_e32 v146, v150, v150
	v_fmac_f32_e32 v147, v152, v152
	v_add_f32_e32 v146, v146, v147
	v_mul_f32_e32 v147, v165, v165
	v_mul_f32_e32 v148, v163, v163
	v_fmac_f32_e32 v147, v164, v164
	v_fmac_f32_e32 v148, v162, v162
	v_add_f32_e32 v147, v147, v148
	v_add_f32_e32 v162, v146, v147
	v_pk_add_f32 v[150:151], v[118:119], v[160:161]
	v_pk_add_f32 v[152:153], v[116:117], v[158:159]
	s_nop 0
	v_cvt_pk_bf16_f32 v146, v152, v153
	v_cvt_pk_bf16_f32 v147, v150, v151
	v_cvt_pk_bf16_f32 v148, v154, v155
	v_cvt_pk_bf16_f32 v149, v156, v157
	global_store_dwordx4 v[166:167], v[146:149], off offset:256
	s_nop 1
	v_mul_f32_e32 v146, v153, v153
	v_mul_f32_e32 v147, v151, v151
	v_fmac_f32_e32 v146, v152, v152
	v_fmac_f32_e32 v147, v150, v150
	v_add_f32_e32 v146, v146, v147
	v_mul_f32_e32 v147, v155, v155
	v_mul_f32_e32 v148, v157, v157
	v_fmac_f32_e32 v147, v154, v154
	v_fmac_f32_e32 v148, v156, v156
	v_add_f32_e32 v147, v147, v148
	v_and_b32_e32 v148, 64, v214
	v_add_f32_e32 v146, v146, v147
	v_xor_b32_e32 v147, 16, v214
	v_add_u32_e32 v148, 64, v148
	v_cmp_lt_i32_e32 vcc, v147, v148
	v_add_f32_e32 v146, v162, v146
	s_nop 0
	v_cndmask_b32_e32 v147, v214, v147, vcc
	v_lshlrev_b32_e32 v218, 2, v147
	ds_bpermute_b32 v147, v218, v146
	s_waitcnt lgkmcnt(0)
	v_add_f32_e32 v146, v146, v147
	v_xor_b32_e32 v147, 32, v214
	v_cmp_lt_i32_e32 vcc, v147, v148
	s_nop 1
	v_cndmask_b32_e32 v147, v214, v147, vcc
	v_lshlrev_b32_e32 v219, 2, v147
	ds_bpermute_b32 v147, v219, v146
	s_and_saveexec_b64 s[42:43], s[38:39]
	s_cbranch_execz .LBB0_200
	s_waitcnt lgkmcnt(0)
	v_add_f32_e32 v146, v146, v147
	v_fma_f32 v146, v146, s91, 0.5
	v_trunc_f32_e32 v146, v146
	v_mul_f32_e32 v147, 0x2f800000, v146
	v_floor_f32_e32 v147, v147
	v_fmac_f32_e32 v146, 0xcf800000, v147
	v_cvt_u32_f32_e32 v146, v146
	v_cvt_u32_f32_e32 v147, v147
	v_lshl_add_u64 v[148:149], v[194:195], 3, s[52:53]
	global_atomic_add_x2 v[148:149], v[146:147], off

.LBB0_325:
	s_nop 0
	s_ashr_i32 s93, s92, 31
	s_lshl_b64 s[30:31], s[92:93], 19
	s_add_u32 s94, s54, s30
	v_cmp_lt_i64_e32 vcc, s[50:51], v[186:187]
	s_addc_u32 s95, s55, s31
	s_and_b64 s[30:31], vcc, exec
	s_cselect_b32 s1, s95, s53
	s_cselect_b32 s11, s94, s52
	s_ashr_i32 s9, s8, 31
	s_lshl_b64 s[30:31], s[8:9], 19
	s_add_u32 s28, s80, s30
	s_addc_u32 s29, s78, s31
	s_and_b64 s[30:31], vcc, exec
	s_cselect_b32 s25, s29, s73
	s_cselect_b32 s30, s28, s72
	s_add_u32 s52, s52, 0x40080
	s_addc_u32 s53, s53, 0
	s_add_u32 s31, s72, 0x100
	s_addc_u32 s33, s73, 0
	s_mov_b32 s34, -2
	s_add_u32 s27, s52, 0xfffc0080
	s_addc_u32 s35, s53, -1
	s_add_i32 s36, 0, 0x10000
	ds_read_b128 v[128:131], v216
	ds_read_b128 v[132:135], v216 offset:1024
	ds_read_b128 v[136:139], v216 offset:2048
	ds_read_b128 v[140:143], v216 offset:3072
	s_cmp_eq_u32 s34, 12
	s_cselect_b32 s75, s1, s35
	s_cselect_b32 s74, s11, s27
	s_cselect_b32 s73, s25, s33
	s_cselect_b32 s72, s30, s31
	s_add_i32 m0, s83, 0xc000
	ds_read_b128 v[156:159], v217
	ds_read_b128 v[160:163], v217 offset:1024
	ds_read_b128 v[164:167], v217 offset:2048
	ds_read_b128 v[188:191], v217 offset:3072
	ds_read_b128 v[192:195], v217 offset:4096
	ds_read_b128 v[196:199], v217 offset:5120
	ds_read_b128 v[200:203], v217 offset:6144
	ds_read_b128 v[204:207], v217 offset:7168
	global_load_lds_dwordx4 v152, s[52:53]
	s_add_i32 m0, s83, 0xe000
	s_nop 0
	global_load_lds_dwordx4 v154, s[52:53]
	s_waitcnt lgkmcnt(0)
	s_barrier
	v_mfma_f32_16x16x32_bf16 v[124:127], v[128:131], v[156:159], 0
	v_mfma_f32_16x16x32_bf16 v[120:123], v[136:139], v[156:159], 0
	v_mfma_f32_16x16x32_bf16 v[108:111], v[128:131], v[164:167], 0
	v_mfma_f32_16x16x32_bf16 v[104:107], v[136:139], v[164:167], 0
	v_mfma_f32_16x16x32_bf16 v[92:95], v[128:131], v[192:195], 0
	v_mfma_f32_16x16x32_bf16 v[88:91], v[136:139], v[192:195], 0
	v_mfma_f32_16x16x32_bf16 v[76:79], v[128:131], v[200:203], 0
	v_mfma_f32_16x16x32_bf16 v[72:75], v[136:139], v[200:203], 0
	v_mfma_f32_16x16x32_bf16 v[124:127], v[132:135], v[160:163], v[124:127]
	v_mfma_f32_16x16x32_bf16 v[120:123], v[140:143], v[160:163], v[120:123]
	v_mfma_f32_16x16x32_bf16 v[108:111], v[132:135], v[188:191], v[108:111]
	v_mfma_f32_16x16x32_bf16 v[104:107], v[140:143], v[188:191], v[104:107]
	v_mfma_f32_16x16x32_bf16 v[92:95], v[132:135], v[196:199], v[92:95]
	v_mfma_f32_16x16x32_bf16 v[88:91], v[140:143], v[196:199], v[88:91]
	v_mfma_f32_16x16x32_bf16 v[76:79], v[132:135], v[204:207], v[76:79]
	v_mfma_f32_16x16x32_bf16 v[72:75], v[140:143], v[204:207], v[72:75]
	s_barrier
	s_add_i32 s27, 0, 0x14000
	s_add_i32 s35, s36, s81
	s_mov_b32 m0, s35
	ds_read_b128 v[220:223], v216 offset:16384
	ds_read_b128 v[228:231], v216 offset:17408
	ds_read_b128 v[232:235], v216 offset:18432
	ds_read_b128 v[236:239], v216 offset:19456
	global_load_lds_dwordx4 v148, s[72:73]
	s_add_i32 m0, s35, 0x2000
	s_nop 0
	global_load_lds_dwordx4 v146, s[72:73]
	s_waitcnt lgkmcnt(0)
	s_barrier
	v_mfma_f32_16x16x32_bf16 v[116:119], v[220:223], v[156:159], 0
	v_mfma_f32_16x16x32_bf16 v[112:115], v[232:235], v[156:159], 0
	v_mfma_f32_16x16x32_bf16 v[100:103], v[220:223], v[164:167], 0
	v_mfma_f32_16x16x32_bf16 v[96:99], v[232:235], v[164:167], 0
	v_mfma_f32_16x16x32_bf16 v[84:87], v[220:223], v[192:195], 0
	v_mfma_f32_16x16x32_bf16 v[80:83], v[232:235], v[192:195], 0
	v_mfma_f32_16x16x32_bf16 v[68:71], v[220:223], v[200:203], 0
	v_mfma_f32_16x16x32_bf16 v[64:67], v[232:235], v[200:203], 0
	v_mfma_f32_16x16x32_bf16 v[116:119], v[228:231], v[160:163], v[116:119]
	v_mfma_f32_16x16x32_bf16 v[112:115], v[236:239], v[160:163], v[112:115]
	v_mfma_f32_16x16x32_bf16 v[100:103], v[228:231], v[188:191], v[100:103]
	v_mfma_f32_16x16x32_bf16 v[96:99], v[236:239], v[188:191], v[96:99]
	v_mfma_f32_16x16x32_bf16 v[84:87], v[228:231], v[196:199], v[84:87]
	v_mfma_f32_16x16x32_bf16 v[80:83], v[236:239], v[196:199], v[80:83]
	v_mfma_f32_16x16x32_bf16 v[68:71], v[228:231], v[204:207], v[68:71]
	v_mfma_f32_16x16x32_bf16 v[64:67], v[236:239], v[204:207], v[64:67]
	s_barrier
	s_mov_b32 m0, s83
	ds_read_b128 v[156:159], v217 offset:16384
	ds_read_b128 v[160:163], v217 offset:17408
	ds_read_b128 v[164:167], v217 offset:18432
	ds_read_b128 v[188:191], v217 offset:19456
	ds_read_b128 v[192:195], v217 offset:20480
	ds_read_b128 v[196:199], v217 offset:21504
	ds_read_b128 v[200:203], v217 offset:22528
	ds_read_b128 v[204:207], v217 offset:23552
	global_load_lds_dwordx4 v148, s[74:75]
	s_mov_b32 m0, s84
	s_nop 0
	global_load_lds_dwordx4 v146, s[74:75]
	s_waitcnt lgkmcnt(0)
	s_waitcnt vmcnt(8)
	s_barrier
	v_mfma_f32_16x16x32_bf16 v[60:63], v[128:131], v[156:159], 0
	v_mfma_f32_16x16x32_bf16 v[56:59], v[136:139], v[156:159], 0
	v_mfma_f32_16x16x32_bf16 v[44:47], v[128:131], v[164:167], 0
	v_mfma_f32_16x16x32_bf16 v[40:43], v[136:139], v[164:167], 0
	v_mfma_f32_16x16x32_bf16 v[28:31], v[128:131], v[192:195], 0
	v_mfma_f32_16x16x32_bf16 v[24:27], v[136:139], v[192:195], 0
	v_mfma_f32_16x16x32_bf16 v[12:15], v[128:131], v[200:203], 0
	v_mfma_f32_16x16x32_bf16 v[8:11], v[136:139], v[200:203], 0
	v_mfma_f32_16x16x32_bf16 v[60:63], v[132:135], v[160:163], v[60:63]
	v_mfma_f32_16x16x32_bf16 v[56:59], v[140:143], v[160:163], v[56:59]
	v_mfma_f32_16x16x32_bf16 v[44:47], v[132:135], v[188:191], v[44:47]
	v_mfma_f32_16x16x32_bf16 v[40:43], v[140:143], v[188:191], v[40:43]
	v_mfma_f32_16x16x32_bf16 v[28:31], v[132:135], v[196:199], v[28:31]
	v_mfma_f32_16x16x32_bf16 v[24:27], v[140:143], v[196:199], v[24:27]
	v_mfma_f32_16x16x32_bf16 v[12:15], v[132:135], v[204:207], v[12:15]
	v_mfma_f32_16x16x32_bf16 v[8:11], v[140:143], v[204:207], v[8:11]
	s_add_u32 s36, s72, 0x40000
	s_addc_u32 s37, s73, 0
	s_add_i32 s27, s27, s81
	s_mov_b32 m0, s27
	s_nop 0
	global_load_lds_dwordx4 v148, s[36:37]
	s_add_i32 m0, s27, 0x2000
	s_nop 0
	global_load_lds_dwordx4 v146, s[36:37]
	s_waitcnt vmcnt(6)
	v_mfma_f32_16x16x32_bf16 v[52:55], v[220:223], v[156:159], 0
	v_mfma_f32_16x16x32_bf16 v[48:51], v[232:235], v[156:159], 0
	v_mfma_f32_16x16x32_bf16 v[36:39], v[220:223], v[164:167], 0
	v_mfma_f32_16x16x32_bf16 v[32:35], v[232:235], v[164:167], 0
	v_mfma_f32_16x16x32_bf16 v[20:23], v[220:223], v[192:195], 0
	v_mfma_f32_16x16x32_bf16 v[16:19], v[232:235], v[192:195], 0
	v_mfma_f32_16x16x32_bf16 v[4:7], v[220:223], v[200:203], 0
	v_mfma_f32_16x16x32_bf16 v[0:3], v[232:235], v[200:203], 0
	v_mfma_f32_16x16x32_bf16 v[52:55], v[228:231], v[160:163], v[52:55]
	v_mfma_f32_16x16x32_bf16 v[48:51], v[236:239], v[160:163], v[48:51]
	v_mfma_f32_16x16x32_bf16 v[36:39], v[228:231], v[188:191], v[36:39]
	v_mfma_f32_16x16x32_bf16 v[32:35], v[236:239], v[188:191], v[32:35]
	v_mfma_f32_16x16x32_bf16 v[20:23], v[228:231], v[196:199], v[20:23]
	v_mfma_f32_16x16x32_bf16 v[16:19], v[236:239], v[196:199], v[16:19]
	v_mfma_f32_16x16x32_bf16 v[4:7], v[228:231], v[204:207], v[4:7]
	v_mfma_f32_16x16x32_bf16 v[0:3], v[236:239], v[204:207], v[0:3]
	s_barrier
	s_add_i32 s27, 0, 0x18000
	ds_read_b128 v[128:131], v216 offset:32768
	ds_read_b128 v[132:135], v216 offset:33792
	ds_read_b128 v[136:139], v216 offset:34816
	ds_read_b128 v[140:143], v216 offset:35840
	s_add_u32 s36, s74, 0x40000
	s_addc_u32 s37, s75, 0
	s_mov_b32 m0, s85
	ds_read_b128 v[156:159], v217 offset:32768
	ds_read_b128 v[160:163], v217 offset:33792
	ds_read_b128 v[164:167], v217 offset:34816
	ds_read_b128 v[188:191], v217 offset:35840
	ds_read_b128 v[192:195], v217 offset:36864
	ds_read_b128 v[196:199], v217 offset:37888
	ds_read_b128 v[200:203], v217 offset:38912
	ds_read_b128 v[204:207], v217 offset:39936
	global_load_lds_dwordx4 v148, s[36:37]
	s_mov_b32 m0, s86
	s_nop 0
	global_load_lds_dwordx4 v146, s[36:37]
	s_waitcnt lgkmcnt(0)
	s_barrier
	v_mfma_f32_16x16x32_bf16 v[124:127], v[128:131], v[156:159], v[124:127]
	v_mfma_f32_16x16x32_bf16 v[120:123], v[136:139], v[156:159], v[120:123]
	v_mfma_f32_16x16x32_bf16 v[108:111], v[128:131], v[164:167], v[108:111]
	v_mfma_f32_16x16x32_bf16 v[104:107], v[136:139], v[164:167], v[104:107]
	v_mfma_f32_16x16x32_bf16 v[92:95], v[128:131], v[192:195], v[92:95]
	v_mfma_f32_16x16x32_bf16 v[88:91], v[136:139], v[192:195], v[88:91]
	v_mfma_f32_16x16x32_bf16 v[76:79], v[128:131], v[200:203], v[76:79]
	v_mfma_f32_16x16x32_bf16 v[72:75], v[136:139], v[200:203], v[72:75]
	v_mfma_f32_16x16x32_bf16 v[124:127], v[132:135], v[160:163], v[124:127]
	v_mfma_f32_16x16x32_bf16 v[120:123], v[140:143], v[160:163], v[120:123]
	v_mfma_f32_16x16x32_bf16 v[108:111], v[132:135], v[188:191], v[108:111]
	v_mfma_f32_16x16x32_bf16 v[104:107], v[140:143], v[188:191], v[104:107]
	v_mfma_f32_16x16x32_bf16 v[92:95], v[132:135], v[196:199], v[92:95]
	v_mfma_f32_16x16x32_bf16 v[88:91], v[140:143], v[196:199], v[88:91]
	v_mfma_f32_16x16x32_bf16 v[76:79], v[132:135], v[204:207], v[76:79]
	v_mfma_f32_16x16x32_bf16 v[72:75], v[140:143], v[204:207], v[72:75]
	s_barrier
	s_add_i32 s35, 0, 0x1c000
	s_add_i32 s27, s27, s81
	s_add_u32 s36, s72, s18
	s_addc_u32 s37, s73, s19
	s_mov_b32 m0, s27
	ds_read_b128 v[220:223], v216 offset:49152
	ds_read_b128 v[228:231], v216 offset:50176
	ds_read_b128 v[232:235], v216 offset:51200
	ds_read_b128 v[236:239], v216 offset:52224
	global_load_lds_dwordx4 v148, s[36:37]
	s_add_u32 s36, s72, s18
	s_addc_u32 s37, s73, s19
	s_add_i32 m0, s27, 0x2000
	s_nop 0
	global_load_lds_dwordx4 v146, s[36:37]
	s_waitcnt lgkmcnt(0)
	s_barrier
	v_mfma_f32_16x16x32_bf16 v[116:119], v[220:223], v[156:159], v[116:119]
	v_mfma_f32_16x16x32_bf16 v[112:115], v[232:235], v[156:159], v[112:115]
	v_mfma_f32_16x16x32_bf16 v[100:103], v[220:223], v[164:167], v[100:103]
	v_mfma_f32_16x16x32_bf16 v[96:99], v[232:235], v[164:167], v[96:99]
	v_mfma_f32_16x16x32_bf16 v[84:87], v[220:223], v[192:195], v[84:87]
	v_mfma_f32_16x16x32_bf16 v[80:83], v[232:235], v[192:195], v[80:83]
	v_mfma_f32_16x16x32_bf16 v[68:71], v[220:223], v[200:203], v[68:71]
	v_mfma_f32_16x16x32_bf16 v[64:67], v[232:235], v[200:203], v[64:67]
	v_mfma_f32_16x16x32_bf16 v[116:119], v[228:231], v[160:163], v[116:119]
	v_mfma_f32_16x16x32_bf16 v[112:115], v[236:239], v[160:163], v[112:115]
	v_mfma_f32_16x16x32_bf16 v[100:103], v[228:231], v[188:191], v[100:103]
	v_mfma_f32_16x16x32_bf16 v[96:99], v[236:239], v[188:191], v[96:99]
	v_mfma_f32_16x16x32_bf16 v[84:87], v[228:231], v[196:199], v[84:87]
	v_mfma_f32_16x16x32_bf16 v[80:83], v[236:239], v[196:199], v[80:83]
	v_mfma_f32_16x16x32_bf16 v[68:71], v[228:231], v[204:207], v[68:71]
	v_mfma_f32_16x16x32_bf16 v[64:67], v[236:239], v[204:207], v[64:67]
	s_barrier
	s_mov_b32 m0, s87
	s_add_u32 s36, s74, s18
	s_addc_u32 s37, s75, s19
	ds_read_b128 v[156:159], v217 offset:49152
	ds_read_b128 v[160:163], v217 offset:50176
	ds_read_b128 v[164:167], v217 offset:51200
	ds_read_b128 v[188:191], v217 offset:52224
	ds_read_b128 v[192:195], v217 offset:53248
	ds_read_b128 v[196:199], v217 offset:54272
	ds_read_b128 v[200:203], v217 offset:55296
	ds_read_b128 v[204:207], v217 offset:56320
	global_load_lds_dwordx4 v148, s[36:37]
	s_add_u32 s36, s74, s18
	s_addc_u32 s37, s75, s19
	s_mov_b32 m0, s79
	s_nop 0
	global_load_lds_dwordx4 v146, s[36:37]
	s_waitcnt lgkmcnt(0)
	s_waitcnt vmcnt(8)
	s_barrier
	v_mfma_f32_16x16x32_bf16 v[60:63], v[128:131], v[156:159], v[60:63]
	v_mfma_f32_16x16x32_bf16 v[56:59], v[136:139], v[156:159], v[56:59]
	v_mfma_f32_16x16x32_bf16 v[44:47], v[128:131], v[164:167], v[44:47]
	v_mfma_f32_16x16x32_bf16 v[40:43], v[136:139], v[164:167], v[40:43]
	v_mfma_f32_16x16x32_bf16 v[28:31], v[128:131], v[192:195], v[28:31]
	v_mfma_f32_16x16x32_bf16 v[24:27], v[136:139], v[192:195], v[24:27]
	v_mfma_f32_16x16x32_bf16 v[12:15], v[128:131], v[200:203], v[12:15]
	v_mfma_f32_16x16x32_bf16 v[8:11], v[136:139], v[200:203], v[8:11]
	v_mfma_f32_16x16x32_bf16 v[60:63], v[132:135], v[160:163], v[60:63]
	v_mfma_f32_16x16x32_bf16 v[56:59], v[140:143], v[160:163], v[56:59]
	v_mfma_f32_16x16x32_bf16 v[44:47], v[132:135], v[188:191], v[44:47]
	v_mfma_f32_16x16x32_bf16 v[40:43], v[140:143], v[188:191], v[40:43]
	v_mfma_f32_16x16x32_bf16 v[28:31], v[132:135], v[196:199], v[28:31]
	v_mfma_f32_16x16x32_bf16 v[24:27], v[140:143], v[196:199], v[24:27]
	v_mfma_f32_16x16x32_bf16 v[12:15], v[132:135], v[204:207], v[12:15]
	v_mfma_f32_16x16x32_bf16 v[8:11], v[140:143], v[204:207], v[8:11]
	s_add_u32 s36, s72, 0x40080
	s_addc_u32 s37, s73, 0
	s_add_i32 s27, s35, s81
	s_mov_b32 m0, s27
	s_nop 0
	global_load_lds_dwordx4 v148, s[36:37]
	s_add_i32 m0, s27, 0x2000
	s_nop 0
	global_load_lds_dwordx4 v146, s[36:37]
	s_waitcnt vmcnt(6)
	v_mfma_f32_16x16x32_bf16 v[52:55], v[220:223], v[156:159], v[52:55]
	v_mfma_f32_16x16x32_bf16 v[48:51], v[232:235], v[156:159], v[48:51]
	v_mfma_f32_16x16x32_bf16 v[36:39], v[220:223], v[164:167], v[36:39]
	v_mfma_f32_16x16x32_bf16 v[32:35], v[232:235], v[164:167], v[32:35]
	v_mfma_f32_16x16x32_bf16 v[20:23], v[220:223], v[192:195], v[20:23]
	v_mfma_f32_16x16x32_bf16 v[16:19], v[232:235], v[192:195], v[16:19]
	v_mfma_f32_16x16x32_bf16 v[4:7], v[220:223], v[200:203], v[4:7]
	v_mfma_f32_16x16x32_bf16 v[0:3], v[232:235], v[200:203], v[0:3]
	v_mfma_f32_16x16x32_bf16 v[52:55], v[228:231], v[160:163], v[52:55]
	v_mfma_f32_16x16x32_bf16 v[48:51], v[236:239], v[160:163], v[48:51]
	v_mfma_f32_16x16x32_bf16 v[36:39], v[228:231], v[188:191], v[36:39]
	v_mfma_f32_16x16x32_bf16 v[32:35], v[236:239], v[188:191], v[32:35]
	v_mfma_f32_16x16x32_bf16 v[20:23], v[228:231], v[196:199], v[20:23]
	v_mfma_f32_16x16x32_bf16 v[16:19], v[236:239], v[196:199], v[16:19]
	v_mfma_f32_16x16x32_bf16 v[4:7], v[228:231], v[204:207], v[4:7]
	v_mfma_f32_16x16x32_bf16 v[0:3], v[236:239], v[204:207], v[0:3]
	s_barrier
	s_add_i32 s34, s34, 2
	s_add_u32 s52, s52, 0x100
	s_addc_u32 s53, s53, 0
	s_add_u32 s31, s31, 0x100
	s_addc_u32 s33, s33, 0
	s_cmp_gt_u32 s34, 13
.LBB0_326:
	s_nop 0
	s_add_u32 s27, s52, 0xfffc0080
	s_addc_u32 s35, s53, -1
	s_add_i32 s36, 0, 0x10000
	ds_read_b128 v[128:131], v216
	ds_read_b128 v[132:135], v216 offset:1024
	ds_read_b128 v[136:139], v216 offset:2048
	ds_read_b128 v[140:143], v216 offset:3072
	s_cmp_eq_u32 s34, 12
	s_cselect_b32 s75, s1, s35
	s_cselect_b32 s74, s11, s27
	s_cselect_b32 s73, s25, s33
	s_cselect_b32 s72, s30, s31
	s_add_i32 m0, s83, 0xc000
	ds_read_b128 v[156:159], v217
	ds_read_b128 v[160:163], v217 offset:1024
	ds_read_b128 v[164:167], v217 offset:2048
	ds_read_b128 v[188:191], v217 offset:3072
	ds_read_b128 v[192:195], v217 offset:4096
	ds_read_b128 v[196:199], v217 offset:5120
	ds_read_b128 v[200:203], v217 offset:6144
	ds_read_b128 v[204:207], v217 offset:7168
	global_load_lds_dwordx4 v152, s[52:53]
	s_add_i32 m0, s83, 0xe000
	s_nop 0
	global_load_lds_dwordx4 v154, s[52:53]
	s_waitcnt lgkmcnt(0)
	s_barrier
	v_mfma_f32_16x16x32_bf16 v[124:127], v[128:131], v[156:159], v[124:127]
	v_mfma_f32_16x16x32_bf16 v[120:123], v[136:139], v[156:159], v[120:123]
	v_mfma_f32_16x16x32_bf16 v[108:111], v[128:131], v[164:167], v[108:111]
	v_mfma_f32_16x16x32_bf16 v[104:107], v[136:139], v[164:167], v[104:107]
	v_mfma_f32_16x16x32_bf16 v[92:95], v[128:131], v[192:195], v[92:95]
	v_mfma_f32_16x16x32_bf16 v[88:91], v[136:139], v[192:195], v[88:91]
	v_mfma_f32_16x16x32_bf16 v[76:79], v[128:131], v[200:203], v[76:79]
	v_mfma_f32_16x16x32_bf16 v[72:75], v[136:139], v[200:203], v[72:75]
	v_mfma_f32_16x16x32_bf16 v[124:127], v[132:135], v[160:163], v[124:127]
	v_mfma_f32_16x16x32_bf16 v[120:123], v[140:143], v[160:163], v[120:123]
	v_mfma_f32_16x16x32_bf16 v[108:111], v[132:135], v[188:191], v[108:111]
	v_mfma_f32_16x16x32_bf16 v[104:107], v[140:143], v[188:191], v[104:107]
	v_mfma_f32_16x16x32_bf16 v[92:95], v[132:135], v[196:199], v[92:95]
	v_mfma_f32_16x16x32_bf16 v[88:91], v[140:143], v[196:199], v[88:91]
	v_mfma_f32_16x16x32_bf16 v[76:79], v[132:135], v[204:207], v[76:79]
	v_mfma_f32_16x16x32_bf16 v[72:75], v[140:143], v[204:207], v[72:75]
	s_barrier
	s_add_i32 s27, 0, 0x14000
	s_add_i32 s35, s36, s81
	s_mov_b32 m0, s35
	ds_read_b128 v[220:223], v216 offset:16384
	ds_read_b128 v[228:231], v216 offset:17408
	ds_read_b128 v[232:235], v216 offset:18432
	ds_read_b128 v[236:239], v216 offset:19456
	global_load_lds_dwordx4 v148, s[72:73]
	s_add_i32 m0, s35, 0x2000
	s_nop 0
	global_load_lds_dwordx4 v146, s[72:73]
	s_waitcnt lgkmcnt(0)
	s_barrier
	v_mfma_f32_16x16x32_bf16 v[116:119], v[220:223], v[156:159], v[116:119]
	v_mfma_f32_16x16x32_bf16 v[112:115], v[232:235], v[156:159], v[112:115]
	v_mfma_f32_16x16x32_bf16 v[100:103], v[220:223], v[164:167], v[100:103]
	v_mfma_f32_16x16x32_bf16 v[96:99], v[232:235], v[164:167], v[96:99]
	v_mfma_f32_16x16x32_bf16 v[84:87], v[220:223], v[192:195], v[84:87]
	v_mfma_f32_16x16x32_bf16 v[80:83], v[232:235], v[192:195], v[80:83]
	v_mfma_f32_16x16x32_bf16 v[68:71], v[220:223], v[200:203], v[68:71]
	v_mfma_f32_16x16x32_bf16 v[64:67], v[232:235], v[200:203], v[64:67]
	v_mfma_f32_16x16x32_bf16 v[116:119], v[228:231], v[160:163], v[116:119]
	v_mfma_f32_16x16x32_bf16 v[112:115], v[236:239], v[160:163], v[112:115]
	v_mfma_f32_16x16x32_bf16 v[100:103], v[228:231], v[188:191], v[100:103]
	v_mfma_f32_16x16x32_bf16 v[96:99], v[236:239], v[188:191], v[96:99]
	v_mfma_f32_16x16x32_bf16 v[84:87], v[228:231], v[196:199], v[84:87]
	v_mfma_f32_16x16x32_bf16 v[80:83], v[236:239], v[196:199], v[80:83]
	v_mfma_f32_16x16x32_bf16 v[68:71], v[228:231], v[204:207], v[68:71]
	v_mfma_f32_16x16x32_bf16 v[64:67], v[236:239], v[204:207], v[64:67]
	s_barrier
	s_mov_b32 m0, s83
	ds_read_b128 v[156:159], v217 offset:16384
	ds_read_b128 v[160:163], v217 offset:17408
	ds_read_b128 v[164:167], v217 offset:18432
	ds_read_b128 v[188:191], v217 offset:19456
	ds_read_b128 v[192:195], v217 offset:20480
	ds_read_b128 v[196:199], v217 offset:21504
	ds_read_b128 v[200:203], v217 offset:22528
	ds_read_b128 v[204:207], v217 offset:23552
	global_load_lds_dwordx4 v148, s[74:75]
	s_mov_b32 m0, s84
	s_nop 0
	global_load_lds_dwordx4 v146, s[74:75]
	s_waitcnt lgkmcnt(0)
	s_waitcnt vmcnt(8)
	s_barrier
	v_mfma_f32_16x16x32_bf16 v[60:63], v[128:131], v[156:159], v[60:63]
	v_mfma_f32_16x16x32_bf16 v[56:59], v[136:139], v[156:159], v[56:59]
	v_mfma_f32_16x16x32_bf16 v[44:47], v[128:131], v[164:167], v[44:47]
	v_mfma_f32_16x16x32_bf16 v[40:43], v[136:139], v[164:167], v[40:43]
	v_mfma_f32_16x16x32_bf16 v[28:31], v[128:131], v[192:195], v[28:31]
	v_mfma_f32_16x16x32_bf16 v[24:27], v[136:139], v[192:195], v[24:27]
	v_mfma_f32_16x16x32_bf16 v[12:15], v[128:131], v[200:203], v[12:15]
	v_mfma_f32_16x16x32_bf16 v[8:11], v[136:139], v[200:203], v[8:11]
	v_mfma_f32_16x16x32_bf16 v[60:63], v[132:135], v[160:163], v[60:63]
	v_mfma_f32_16x16x32_bf16 v[56:59], v[140:143], v[160:163], v[56:59]
	v_mfma_f32_16x16x32_bf16 v[44:47], v[132:135], v[188:191], v[44:47]
	v_mfma_f32_16x16x32_bf16 v[40:43], v[140:143], v[188:191], v[40:43]
	v_mfma_f32_16x16x32_bf16 v[28:31], v[132:135], v[196:199], v[28:31]
	v_mfma_f32_16x16x32_bf16 v[24:27], v[140:143], v[196:199], v[24:27]
	v_mfma_f32_16x16x32_bf16 v[12:15], v[132:135], v[204:207], v[12:15]
	v_mfma_f32_16x16x32_bf16 v[8:11], v[140:143], v[204:207], v[8:11]
	s_add_u32 s36, s72, 0x40000
	s_addc_u32 s37, s73, 0
	s_add_i32 s27, s27, s81
	s_mov_b32 m0, s27
	s_nop 0
	global_load_lds_dwordx4 v148, s[36:37]
	s_add_i32 m0, s27, 0x2000
	s_nop 0
	global_load_lds_dwordx4 v146, s[36:37]
	s_waitcnt vmcnt(6)
	v_mfma_f32_16x16x32_bf16 v[52:55], v[220:223], v[156:159], v[52:55]
	v_mfma_f32_16x16x32_bf16 v[48:51], v[232:235], v[156:159], v[48:51]
	v_mfma_f32_16x16x32_bf16 v[36:39], v[220:223], v[164:167], v[36:39]
	v_mfma_f32_16x16x32_bf16 v[32:35], v[232:235], v[164:167], v[32:35]
	v_mfma_f32_16x16x32_bf16 v[20:23], v[220:223], v[192:195], v[20:23]
	v_mfma_f32_16x16x32_bf16 v[16:19], v[232:235], v[192:195], v[16:19]
	v_mfma_f32_16x16x32_bf16 v[4:7], v[220:223], v[200:203], v[4:7]
	v_mfma_f32_16x16x32_bf16 v[0:3], v[232:235], v[200:203], v[0:3]
	v_mfma_f32_16x16x32_bf16 v[52:55], v[228:231], v[160:163], v[52:55]
	v_mfma_f32_16x16x32_bf16 v[48:51], v[236:239], v[160:163], v[48:51]
	v_mfma_f32_16x16x32_bf16 v[36:39], v[228:231], v[188:191], v[36:39]
	v_mfma_f32_16x16x32_bf16 v[32:35], v[236:239], v[188:191], v[32:35]
	v_mfma_f32_16x16x32_bf16 v[20:23], v[228:231], v[196:199], v[20:23]
	v_mfma_f32_16x16x32_bf16 v[16:19], v[236:239], v[196:199], v[16:19]
	v_mfma_f32_16x16x32_bf16 v[4:7], v[228:231], v[204:207], v[4:7]
	v_mfma_f32_16x16x32_bf16 v[0:3], v[236:239], v[204:207], v[0:3]
	s_barrier
	s_add_i32 s27, 0, 0x18000
	ds_read_b128 v[128:131], v216 offset:32768
	ds_read_b128 v[132:135], v216 offset:33792
	ds_read_b128 v[136:139], v216 offset:34816
	ds_read_b128 v[140:143], v216 offset:35840
	s_add_u32 s36, s74, 0x40000
	s_addc_u32 s37, s75, 0
	s_mov_b32 m0, s85
	ds_read_b128 v[156:159], v217 offset:32768
	ds_read_b128 v[160:163], v217 offset:33792
	ds_read_b128 v[164:167], v217 offset:34816
	ds_read_b128 v[188:191], v217 offset:35840
	ds_read_b128 v[192:195], v217 offset:36864
	ds_read_b128 v[196:199], v217 offset:37888
	ds_read_b128 v[200:203], v217 offset:38912
	ds_read_b128 v[204:207], v217 offset:39936
	global_load_lds_dwordx4 v148, s[36:37]
	s_mov_b32 m0, s86
	s_nop 0
	global_load_lds_dwordx4 v146, s[36:37]
	s_waitcnt lgkmcnt(0)
	s_barrier
	v_mfma_f32_16x16x32_bf16 v[124:127], v[128:131], v[156:159], v[124:127]
	v_mfma_f32_16x16x32_bf16 v[120:123], v[136:139], v[156:159], v[120:123]
	v_mfma_f32_16x16x32_bf16 v[108:111], v[128:131], v[164:167], v[108:111]
	v_mfma_f32_16x16x32_bf16 v[104:107], v[136:139], v[164:167], v[104:107]
	v_mfma_f32_16x16x32_bf16 v[92:95], v[128:131], v[192:195], v[92:95]
	v_mfma_f32_16x16x32_bf16 v[88:91], v[136:139], v[192:195], v[88:91]
	v_mfma_f32_16x16x32_bf16 v[76:79], v[128:131], v[200:203], v[76:79]
	v_mfma_f32_16x16x32_bf16 v[72:75], v[136:139], v[200:203], v[72:75]
	v_mfma_f32_16x16x32_bf16 v[124:127], v[132:135], v[160:163], v[124:127]
	v_mfma_f32_16x16x32_bf16 v[120:123], v[140:143], v[160:163], v[120:123]
	v_mfma_f32_16x16x32_bf16 v[108:111], v[132:135], v[188:191], v[108:111]
	v_mfma_f32_16x16x32_bf16 v[104:107], v[140:143], v[188:191], v[104:107]
	v_mfma_f32_16x16x32_bf16 v[92:95], v[132:135], v[196:199], v[92:95]
	v_mfma_f32_16x16x32_bf16 v[88:91], v[140:143], v[196:199], v[88:91]
	v_mfma_f32_16x16x32_bf16 v[76:79], v[132:135], v[204:207], v[76:79]
	v_mfma_f32_16x16x32_bf16 v[72:75], v[140:143], v[204:207], v[72:75]
	s_barrier
	s_add_i32 s35, 0, 0x1c000
	s_add_i32 s27, s27, s81
	s_add_u32 s36, s72, s18
	s_addc_u32 s37, s73, s19
	s_mov_b32 m0, s27
	ds_read_b128 v[220:223], v216 offset:49152
	ds_read_b128 v[228:231], v216 offset:50176
	ds_read_b128 v[232:235], v216 offset:51200
	ds_read_b128 v[236:239], v216 offset:52224
	global_load_lds_dwordx4 v148, s[36:37]
	s_add_u32 s36, s72, s18
	s_addc_u32 s37, s73, s19
	s_add_i32 m0, s27, 0x2000
	s_nop 0
	global_load_lds_dwordx4 v146, s[36:37]
	s_waitcnt lgkmcnt(0)
	s_barrier
	v_mfma_f32_16x16x32_bf16 v[116:119], v[220:223], v[156:159], v[116:119]
	v_mfma_f32_16x16x32_bf16 v[112:115], v[232:235], v[156:159], v[112:115]
	v_mfma_f32_16x16x32_bf16 v[100:103], v[220:223], v[164:167], v[100:103]
	v_mfma_f32_16x16x32_bf16 v[96:99], v[232:235], v[164:167], v[96:99]
	v_mfma_f32_16x16x32_bf16 v[84:87], v[220:223], v[192:195], v[84:87]
	v_mfma_f32_16x16x32_bf16 v[80:83], v[232:235], v[192:195], v[80:83]
	v_mfma_f32_16x16x32_bf16 v[68:71], v[220:223], v[200:203], v[68:71]
	v_mfma_f32_16x16x32_bf16 v[64:67], v[232:235], v[200:203], v[64:67]
	v_mfma_f32_16x16x32_bf16 v[116:119], v[228:231], v[160:163], v[116:119]
	v_mfma_f32_16x16x32_bf16 v[112:115], v[236:239], v[160:163], v[112:115]
	v_mfma_f32_16x16x32_bf16 v[100:103], v[228:231], v[188:191], v[100:103]
	v_mfma_f32_16x16x32_bf16 v[96:99], v[236:239], v[188:191], v[96:99]
	v_mfma_f32_16x16x32_bf16 v[84:87], v[228:231], v[196:199], v[84:87]
	v_mfma_f32_16x16x32_bf16 v[80:83], v[236:239], v[196:199], v[80:83]
	v_mfma_f32_16x16x32_bf16 v[68:71], v[228:231], v[204:207], v[68:71]
	v_mfma_f32_16x16x32_bf16 v[64:67], v[236:239], v[204:207], v[64:67]
	s_barrier
	s_mov_b32 m0, s87
	s_add_u32 s36, s74, s18
	s_addc_u32 s37, s75, s19
	ds_read_b128 v[156:159], v217 offset:49152
	ds_read_b128 v[160:163], v217 offset:50176
	ds_read_b128 v[164:167], v217 offset:51200
	ds_read_b128 v[188:191], v217 offset:52224
	ds_read_b128 v[192:195], v217 offset:53248
	ds_read_b128 v[196:199], v217 offset:54272
	ds_read_b128 v[200:203], v217 offset:55296
	ds_read_b128 v[204:207], v217 offset:56320
	global_load_lds_dwordx4 v148, s[36:37]
	s_add_u32 s36, s74, s18
	s_addc_u32 s37, s75, s19
	s_mov_b32 m0, s79
	s_nop 0
	global_load_lds_dwordx4 v146, s[36:37]
	s_waitcnt lgkmcnt(0)
	s_waitcnt vmcnt(8)
	s_barrier
	v_mfma_f32_16x16x32_bf16 v[60:63], v[128:131], v[156:159], v[60:63]
	v_mfma_f32_16x16x32_bf16 v[56:59], v[136:139], v[156:159], v[56:59]
	v_mfma_f32_16x16x32_bf16 v[44:47], v[128:131], v[164:167], v[44:47]
	v_mfma_f32_16x16x32_bf16 v[40:43], v[136:139], v[164:167], v[40:43]
	v_mfma_f32_16x16x32_bf16 v[28:31], v[128:131], v[192:195], v[28:31]
	v_mfma_f32_16x16x32_bf16 v[24:27], v[136:139], v[192:195], v[24:27]
	v_mfma_f32_16x16x32_bf16 v[12:15], v[128:131], v[200:203], v[12:15]
	v_mfma_f32_16x16x32_bf16 v[8:11], v[136:139], v[200:203], v[8:11]
	v_mfma_f32_16x16x32_bf16 v[60:63], v[132:135], v[160:163], v[60:63]
	v_mfma_f32_16x16x32_bf16 v[56:59], v[140:143], v[160:163], v[56:59]
	v_mfma_f32_16x16x32_bf16 v[44:47], v[132:135], v[188:191], v[44:47]
	v_mfma_f32_16x16x32_bf16 v[40:43], v[140:143], v[188:191], v[40:43]
	v_mfma_f32_16x16x32_bf16 v[28:31], v[132:135], v[196:199], v[28:31]
	v_mfma_f32_16x16x32_bf16 v[24:27], v[140:143], v[196:199], v[24:27]
	v_mfma_f32_16x16x32_bf16 v[12:15], v[132:135], v[204:207], v[12:15]
	v_mfma_f32_16x16x32_bf16 v[8:11], v[140:143], v[204:207], v[8:11]
	s_add_u32 s36, s72, 0x40080
	s_addc_u32 s37, s73, 0
	s_add_i32 s27, s35, s81
	s_mov_b32 m0, s27
	s_nop 0
	global_load_lds_dwordx4 v148, s[36:37]
	s_add_i32 m0, s27, 0x2000
	s_nop 0
	global_load_lds_dwordx4 v146, s[36:37]
	s_waitcnt vmcnt(6)
	v_mfma_f32_16x16x32_bf16 v[52:55], v[220:223], v[156:159], v[52:55]
	v_mfma_f32_16x16x32_bf16 v[48:51], v[232:235], v[156:159], v[48:51]
	v_mfma_f32_16x16x32_bf16 v[36:39], v[220:223], v[164:167], v[36:39]
	v_mfma_f32_16x16x32_bf16 v[32:35], v[232:235], v[164:167], v[32:35]
	v_mfma_f32_16x16x32_bf16 v[20:23], v[220:223], v[192:195], v[20:23]
	v_mfma_f32_16x16x32_bf16 v[16:19], v[232:235], v[192:195], v[16:19]
	v_mfma_f32_16x16x32_bf16 v[4:7], v[220:223], v[200:203], v[4:7]
	v_mfma_f32_16x16x32_bf16 v[0:3], v[232:235], v[200:203], v[0:3]
	v_mfma_f32_16x16x32_bf16 v[52:55], v[228:231], v[160:163], v[52:55]
	v_mfma_f32_16x16x32_bf16 v[48:51], v[236:239], v[160:163], v[48:51]
	v_mfma_f32_16x16x32_bf16 v[36:39], v[228:231], v[188:191], v[36:39]
	v_mfma_f32_16x16x32_bf16 v[32:35], v[236:239], v[188:191], v[32:35]
	v_mfma_f32_16x16x32_bf16 v[20:23], v[228:231], v[196:199], v[20:23]
	v_mfma_f32_16x16x32_bf16 v[16:19], v[236:239], v[196:199], v[16:19]
	v_mfma_f32_16x16x32_bf16 v[4:7], v[228:231], v[204:207], v[4:7]
	v_mfma_f32_16x16x32_bf16 v[0:3], v[236:239], v[204:207], v[0:3]
	s_barrier
	s_add_i32 s34, s34, 2
	s_add_u32 s52, s52, 0x100
	s_addc_u32 s53, s53, 0
	s_add_u32 s31, s31, 0x100
	s_addc_u32 s33, s33, 0
	s_cmp_gt_u32 s34, 13
	s_cbranch_scc0 .LBB0_326
	v_lshl_add_u32 v128, s0, 8, v151
	v_readlane_b32 s0, v252, 36
	v_ashrrev_i32_e32 v129, 31, v128
	v_readlane_b32 s1, v252, 37
	v_or_b32_e32 v132, 16, v128
	v_or_b32_e32 v136, 32, v128
	v_lshl_add_u64 v[130:131], v[128:129], 3, s[0:1]
	v_ashrrev_i32_e32 v133, 31, v132
	v_ashrrev_i32_e32 v137, 31, v136
	v_or_b32_e32 v140, 48, v128
	v_lshl_add_u64 v[134:135], v[132:133], 3, s[0:1]
	v_lshl_add_u64 v[138:139], v[136:137], 3, s[0:1]
	v_ashrrev_i32_e32 v141, 31, v140
	global_load_dwordx2 v[202:203], v[130:131], off
	global_load_dwordx2 v[200:201], v[134:135], off
	global_load_dwordx2 v[192:193], v[138:139], off
	global_load_dwordx2 v[166:167], v[130:131], off offset:1024
	v_add_u32_e32 v164, 0x90, v128
	v_add_u32_e32 v158, 0xa0, v128
	v_add_u32_e32 v156, 0xb0, v128
	v_lshl_add_u64 v[142:143], v[140:141], 3, s[0:1]
	v_ashrrev_i32_e32 v165, 31, v164
	v_ashrrev_i32_e32 v159, 31, v158
	v_ashrrev_i32_e32 v157, 31, v156
	v_lshl_add_u64 v[130:131], v[164:165], 3, s[0:1]
	v_lshl_add_u64 v[134:135], v[158:159], 3, s[0:1]
	v_lshl_add_u64 v[138:139], v[156:157], 3, s[0:1]
	global_load_dwordx2 v[196:197], v[142:143], off
	global_load_dwordx2 v[188:189], v[130:131], off
	global_load_dwordx2 v[162:163], v[134:135], off
	global_load_dwordx2 v[160:161], v[138:139], off
	v_add_u32_e32 v168, 0x80, v128
	s_mov_b64 s[0:1], -1
	s_cmp_gt_u32 s10, 1
	v_lshlrev_b32_e32 v144, 1, v150
	v_ashrrev_i32_e32 v169, 31, v168
	v_lshlrev_b64 v[204:205], 10, v[128:129]
	v_lshlrev_b64 v[198:199], 10, v[132:133]
	v_lshlrev_b64 v[194:195], 10, v[136:137]
	v_lshlrev_b64 v[190:191], 10, v[140:141]
	s_waitcnt vmcnt(0)
	v_ffbh_u32_e32 v222, v203
	v_ffbh_u32_e32 v221, v201
	v_ffbh_u32_e32 v220, v193
	v_ffbh_u32_e32 v219, v197
	s_cbranch_scc0 .LBB0_329
	s_cmp_lt_u32 s10, 4
	s_cselect_b64 vcc, -1, 0
	v_readlane_b32 s56, v254, 23
	s_and_b64 s[0:1], vcc, exec
	v_readlane_b32 s70, v254, 37
	v_readlane_b32 s36, v252, 15
	v_readlane_b32 s71, v254, 38
	v_readlane_b32 s37, v252, 16
	s_cselect_b32 s0, s70, s36
	s_mov_b32 s11, 0x4400000
	v_readlane_b32 s30, v254, 62
	s_cselect_b32 s1, s71, s37
	s_cselect_b32 s11, s11, 0x4800000
	v_readlane_b32 s31, v254, 63
	s_add_u32 s0, s0, s30
	s_addc_u32 s1, s1, s31
	global_load_dwordx4 v[136:139], v218, s[0:1] offset:16
	global_load_dwordx4 v[140:143], v218, s[0:1]
	global_load_dwordx4 v[128:131], v218, s[0:1] offset:144
	global_load_dwordx4 v[132:135], v218, s[0:1] offset:128
	v_and_b32_e32 v177, 64, v214
	v_xor_b32_e32 v176, 16, v214
	v_add_u32_e32 v177, 64, v177
	v_cndmask_b32_e32 v223, 1.0, v215, vcc
	v_cmp_lt_i32_e32 vcc, v176, v177
	v_readlane_b32 s9, v254, 52
	s_add_u32 s11, s9, s11
	v_cndmask_b32_e32 v176, v214, v176, vcc
	v_lshlrev_b32_e32 v225, 2, v176
	v_xor_b32_e32 v176, 32, v214
	v_cmp_lt_i32_e32 vcc, v176, v177
	v_readlane_b32 s9, v254, 61
	s_addc_u32 s25, s9, 0
	v_cndmask_b32_e32 v176, v214, v176, vcc
	v_lshlrev_b32_e32 v224, 2, v176
	v_min_u32_e32 v176, 32, v222
	v_lshlrev_b64 v[228:229], v176, v[202:203]
	v_min_u32_e32 v177, 1, v228
	v_or_b32_e32 v177, v229, v177
	v_cvt_f32_u32_e32 v177, v177
	v_sub_u32_e32 v176, 32, v176
	s_lshl_b32 s0, s10, 9
	s_and_b32 s0, s0, 0x200
	v_ldexp_f32 v176, v177, v176
	v_mul_f32_e32 v176, 0x35800000, v176
	v_fmamk_f32 v176, v176, 0x3a800000, v210
	s_add_u32 s0, s11, s0
	v_rsq_f32_e32 v176, v176
	s_addc_u32 s1, s25, 0
	v_lshl_add_u64 v[206:207], s[0:1], 0, v[144:145]
	v_readlane_b32 s48, v252, 27
	v_mov_b32_e32 v228, v176
	v_pk_mul_f32 v[230:231], v[124:125], v[228:229] op_sel_hi:[1,0]
	v_pk_mul_f32 v[232:233], v[126:127], v[228:229] op_sel_hi:[1,0]
	v_pk_mul_f32 v[236:237], v[230:231], v[230:231]
	v_pk_mul_f32 v[234:235], v[232:233], v[232:233]
	v_pk_mul_f32 v[250:251], v[114:115], v[228:229] op_sel_hi:[1,0]
	v_pk_mov_b32 v[238:239], v[236:237], v[234:235] op_sel:[1,0]
	v_mov_b32_e32 v237, v235
	v_pk_add_f32 v[234:235], v[238:239], v[236:237]
	v_pk_mul_f32 v[236:237], v[120:121], v[228:229] op_sel_hi:[1,0]
	v_pk_mul_f32 v[238:239], v[122:123], v[228:229] op_sel_hi:[1,0]
	v_pk_mul_f32 v[242:243], v[236:237], v[236:237]
	v_pk_mul_f32 v[240:241], v[238:239], v[238:239]
	v_pk_add_f32 v[234:235], v[234:235], v[234:235] op_sel_hi:[0,1]
	v_pk_mov_b32 v[244:245], v[242:243], v[240:241] op_sel:[1,0]
	v_mov_b32_e32 v243, v241
	v_pk_add_f32 v[240:241], v[244:245], v[242:243]
	v_pk_mul_f32 v[244:245], v[116:117], v[228:229] op_sel_hi:[1,0]
	v_pk_mul_f32 v[242:243], v[118:119], v[228:229] op_sel_hi:[1,0]
	v_mul_f32_e32 v234, v244, v244
	v_pk_fma_f32 v[246:247], v[244:245], v[244:245], v[234:235] op_sel_hi:[1,1,0]
	v_mul_f32_e32 v234, v242, v242
	v_pk_add_f32 v[240:241], v[240:241], v[240:241] op_sel_hi:[0,1]
	v_pk_fma_f32 v[248:249], v[242:243], v[242:243], v[234:235] op_sel_hi:[1,1,0]
	v_pk_mul_f32 v[176:177], v[112:113], v[228:229] op_sel_hi:[1,0]
	v_mul_f32_e32 v234, v250, v250
	v_mul_f32_e32 v246, v176, v176
	v_mul_f32_e32 v248, v177, v177
	v_mul_f32_e32 v240, v251, v251
	v_pk_add_f32 v[228:229], v[246:247], v[248:249]
	v_pk_add_f32 v[234:235], v[234:235], v[240:241]
	v_lshl_add_u64 v[240:241], v[206:207], 0, v[204:205]
	v_pk_add_f32 v[228:229], v[228:229], v[234:235]
	v_readlane_b32 s57, v254, 24
	v_add_f32_e32 v228, v228, v229
	ds_bpermute_b32 v229, v225, v228
	v_readlane_b32 s58, v254, 25
	v_readlane_b32 s59, v254, 26
	v_readlane_b32 s60, v254, 27
	v_readlane_b32 s61, v254, 28
	s_waitcnt lgkmcnt(0)
	v_add_f32_e32 v228, v228, v229
	ds_bpermute_b32 v229, v224, v228
	v_readlane_b32 s62, v254, 29
	v_readlane_b32 s63, v254, 30
	v_readlane_b32 s64, v254, 31
	v_readlane_b32 s65, v254, 32
	s_waitcnt lgkmcnt(0)
	v_add_f32_e32 v228, v228, v229
	v_fmamk_f32 v228, v228, 0x3c800000, v210
	v_readlane_b32 s66, v254, 33
	v_rsq_f32_e32 v228, v228
	v_readlane_b32 s67, v254, 34
	v_readlane_b32 s68, v254, 35
	v_readlane_b32 s69, v254, 36
	v_mul_f32_e32 v234, v223, v228
	v_pk_mul_f32 v[228:229], v[230:231], v[234:235] op_sel_hi:[1,0]
	v_pk_mul_f32 v[230:231], v[232:233], v[234:235] op_sel_hi:[1,0]
	s_waitcnt vmcnt(2)
	v_pk_mul_f32 v[228:229], v[140:141], v[228:229]
	v_pk_mul_f32 v[230:231], v[142:143], v[230:231]
	v_pk_mul_f32 v[232:233], v[236:237], v[234:235] op_sel_hi:[1,0]
	v_pk_mul_f32 v[236:237], v[238:239], v[234:235] op_sel_hi:[1,0]
	v_cvt_pk_bf16_f32 v228, v228, v229
	v_cvt_pk_bf16_f32 v229, v230, v231
	v_pk_mul_f32 v[232:233], v[136:137], v[232:233]
	v_pk_mul_f32 v[236:237], v[138:139], v[236:237]
	v_cvt_pk_bf16_f32 v230, v232, v233
	v_pk_mul_f32 v[176:177], v[176:177], v[234:235] op_sel_hi:[1,0]
	v_cvt_pk_bf16_f32 v231, v236, v237
	global_store_dwordx4 v[240:241], v[228:231], off
	v_pk_mul_f32 v[232:233], v[250:251], v[234:235] op_sel_hi:[1,0]
	s_waitcnt vmcnt(2)
	v_pk_mul_f32 v[176:177], v[128:129], v[176:177]
	v_pk_mul_f32 v[228:229], v[244:245], v[234:235] op_sel_hi:[1,0]
	v_pk_mul_f32 v[230:231], v[242:243], v[234:235] op_sel_hi:[1,0]
	s_waitcnt vmcnt(1)
	v_pk_mul_f32 v[228:229], v[132:133], v[228:229]
	v_pk_mul_f32 v[230:231], v[134:135], v[230:231]
	v_cvt_pk_bf16_f32 v228, v228, v229
	v_pk_mul_f32 v[232:233], v[130:131], v[232:233]
	v_cvt_pk_bf16_f32 v229, v230, v231
	v_cvt_pk_bf16_f32 v230, v176, v177
	s_nop 1
	v_readlane_b32 s38, v252, 17
	v_cvt_pk_bf16_f32 v231, v232, v233
	s_nop 1
	global_store_dwordx4 v[240:241], v[228:231], off offset:64
	v_readlane_b32 s39, v252, 18
	v_readlane_b32 s40, v252, 19
	v_min_u32_e32 v228, 32, v221
	v_lshlrev_b64 v[176:177], v228, v[200:201]
	v_min_u32_e32 v176, 1, v176
	v_or_b32_e32 v176, v177, v176
	v_cvt_f32_u32_e32 v176, v176
	v_sub_u32_e32 v177, 32, v228
	v_readlane_b32 s41, v252, 20
	v_readlane_b32 s42, v252, 21
	v_ldexp_f32 v176, v176, v177
	v_mul_f32_e32 v176, 0x35800000, v176
	v_fmamk_f32 v176, v176, 0x3a800000, v210
	v_readlane_b32 s43, v252, 22
	v_rsq_f32_e32 v176, v176
	v_readlane_b32 s44, v252, 23
	v_readlane_b32 s45, v252, 24
	v_readlane_b32 s46, v252, 25
	v_pk_mul_f32 v[228:229], v[108:109], v[176:177] op_sel_hi:[1,0]
	v_pk_mul_f32 v[230:231], v[110:111], v[176:177] op_sel_hi:[1,0]
	v_pk_mul_f32 v[234:235], v[228:229], v[228:229]
	v_pk_mul_f32 v[232:233], v[230:231], v[230:231]
	v_pk_mul_f32 v[248:249], v[98:99], v[176:177] op_sel_hi:[1,0]
	v_pk_mov_b32 v[236:237], v[234:235], v[232:233] op_sel:[1,0]
	v_mov_b32_e32 v235, v233
	v_pk_add_f32 v[232:233], v[236:237], v[234:235]
	v_pk_mul_f32 v[234:235], v[104:105], v[176:177] op_sel_hi:[1,0]
	v_pk_mul_f32 v[236:237], v[106:107], v[176:177] op_sel_hi:[1,0]
	v_pk_mul_f32 v[240:241], v[234:235], v[234:235]
	v_pk_mul_f32 v[238:239], v[236:237], v[236:237]
	v_pk_add_f32 v[232:233], v[232:233], v[232:233] op_sel_hi:[0,1]
	v_pk_mov_b32 v[242:243], v[240:241], v[238:239] op_sel:[1,0]
	v_mov_b32_e32 v241, v239
	v_pk_add_f32 v[238:239], v[242:243], v[240:241]
	v_pk_mul_f32 v[242:243], v[100:101], v[176:177] op_sel_hi:[1,0]
	v_pk_mul_f32 v[240:241], v[102:103], v[176:177] op_sel_hi:[1,0]
	v_mul_f32_e32 v232, v242, v242
	v_pk_fma_f32 v[244:245], v[242:243], v[242:243], v[232:233] op_sel_hi:[1,1,0]
	v_mul_f32_e32 v232, v240, v240
	v_pk_add_f32 v[238:239], v[238:239], v[238:239] op_sel_hi:[0,1]
	v_pk_fma_f32 v[246:247], v[240:241], v[240:241], v[232:233] op_sel_hi:[1,1,0]
	v_pk_mul_f32 v[176:177], v[96:97], v[176:177] op_sel_hi:[1,0]
	v_mul_f32_e32 v232, v248, v248
	v_mul_f32_e32 v244, v176, v176
	v_mul_f32_e32 v246, v177, v177
	v_mul_f32_e32 v238, v249, v249
	v_pk_add_f32 v[244:245], v[244:245], v[246:247]
	v_pk_add_f32 v[232:233], v[232:233], v[238:239]
	v_lshl_add_u64 v[238:239], v[206:207], 0, v[198:199]
	v_pk_add_f32 v[232:233], v[244:245], v[232:233]
	v_readlane_b32 s47, v252, 26
	v_add_f32_e32 v232, v232, v233
	ds_bpermute_b32 v233, v225, v232
	v_readlane_b32 s49, v252, 28
	v_readlane_b32 s50, v252, 29
	v_readlane_b32 s51, v252, 30
	v_readlane_b32 s48, v252, 40
	s_waitcnt lgkmcnt(0)
	v_add_f32_e32 v232, v232, v233
	ds_bpermute_b32 v233, v224, v232
	s_mov_b64 s[0:1], 0
	s_waitcnt lgkmcnt(0)
	v_add_f32_e32 v232, v232, v233
	v_fmamk_f32 v232, v232, 0x3c800000, v210
	s_nop 0
	v_rsq_f32_e32 v232, v232
	s_nop 0
	v_mul_f32_e32 v232, v223, v232
	v_pk_mul_f32 v[228:229], v[228:229], v[232:233] op_sel_hi:[1,0]
	v_pk_mul_f32 v[230:231], v[230:231], v[232:233] op_sel_hi:[1,0]
	v_pk_mul_f32 v[228:229], v[140:141], v[228:229]
	v_pk_mul_f32 v[230:231], v[142:143], v[230:231]
	v_pk_mul_f32 v[234:235], v[234:235], v[232:233] op_sel_hi:[1,0]
	v_pk_mul_f32 v[236:237], v[236:237], v[232:233] op_sel_hi:[1,0]
	v_cvt_pk_bf16_f32 v228, v228, v229
	v_cvt_pk_bf16_f32 v229, v230, v231
	v_pk_mul_f32 v[234:235], v[136:137], v[234:235]
	v_pk_mul_f32 v[236:237], v[138:139], v[236:237]
	v_cvt_pk_bf16_f32 v230, v234, v235
	v_pk_mul_f32 v[176:177], v[176:177], v[232:233] op_sel_hi:[1,0]
	v_cvt_pk_bf16_f32 v231, v236, v237
	global_store_dwordx4 v[238:239], v[228:231], off
	v_pk_mul_f32 v[176:177], v[128:129], v[176:177]
	s_nop 0
	v_pk_mul_f32 v[228:229], v[242:243], v[232:233] op_sel_hi:[1,0]
	v_pk_mul_f32 v[230:231], v[240:241], v[232:233] op_sel_hi:[1,0]
	v_pk_mul_f32 v[228:229], v[132:133], v[228:229]
	v_pk_mul_f32 v[230:231], v[134:135], v[230:231]
	v_pk_mul_f32 v[232:233], v[248:249], v[232:233] op_sel_hi:[1,0]
	v_cvt_pk_bf16_f32 v228, v228, v229
	v_cvt_pk_bf16_f32 v229, v230, v231
	v_cvt_pk_bf16_f32 v230, v176, v177
	s_nop 0
	v_pk_mul_f32 v[232:233], v[130:131], v[232:233]
	s_nop 0
	v_cvt_pk_bf16_f32 v231, v232, v233
	global_store_dwordx4 v[238:239], v[228:231], off offset:64
	s_nop 1
	v_min_u32_e32 v228, 32, v220
	v_lshlrev_b64 v[176:177], v228, v[192:193]
	v_min_u32_e32 v176, 1, v176
	v_or_b32_e32 v176, v177, v176
	v_cvt_f32_u32_e32 v176, v176
	v_sub_u32_e32 v177, 32, v228
	v_ldexp_f32 v176, v176, v177
	v_mul_f32_e32 v176, 0x35800000, v176
	v_fmamk_f32 v176, v176, 0x3a800000, v210
	s_nop 0
	v_rsq_f32_e32 v176, v176
	s_nop 0
	v_pk_mul_f32 v[228:229], v[92:93], v[176:177] op_sel_hi:[1,0]
	v_pk_mul_f32 v[230:231], v[94:95], v[176:177] op_sel_hi:[1,0]
	v_pk_mul_f32 v[234:235], v[228:229], v[228:229]
	v_pk_mul_f32 v[232:233], v[230:231], v[230:231]
	v_pk_mul_f32 v[248:249], v[82:83], v[176:177] op_sel_hi:[1,0]
	v_pk_mov_b32 v[236:237], v[234:235], v[232:233] op_sel:[1,0]
	v_mov_b32_e32 v235, v233
	v_pk_add_f32 v[232:233], v[236:237], v[234:235]
	v_pk_mul_f32 v[234:235], v[88:89], v[176:177] op_sel_hi:[1,0]
	v_pk_mul_f32 v[236:237], v[90:91], v[176:177] op_sel_hi:[1,0]
	v_pk_mul_f32 v[240:241], v[234:235], v[234:235]
	v_pk_mul_f32 v[238:239], v[236:237], v[236:237]
	v_pk_add_f32 v[232:233], v[232:233], v[232:233] op_sel_hi:[0,1]
	v_pk_mov_b32 v[242:243], v[240:241], v[238:239] op_sel:[1,0]
	v_mov_b32_e32 v241, v239
	v_pk_add_f32 v[238:239], v[242:243], v[240:241]
	v_pk_mul_f32 v[242:243], v[84:85], v[176:177] op_sel_hi:[1,0]
	v_pk_mul_f32 v[240:241], v[86:87], v[176:177] op_sel_hi:[1,0]
	v_mul_f32_e32 v232, v242, v242
	v_pk_fma_f32 v[244:245], v[242:243], v[242:243], v[232:233] op_sel_hi:[1,1,0]
	v_mul_f32_e32 v232, v240, v240
	v_pk_add_f32 v[238:239], v[238:239], v[238:239] op_sel_hi:[0,1]
	v_pk_fma_f32 v[246:247], v[240:241], v[240:241], v[232:233] op_sel_hi:[1,1,0]
	v_pk_mul_f32 v[176:177], v[80:81], v[176:177] op_sel_hi:[1,0]
	v_mul_f32_e32 v232, v248, v248
	v_mul_f32_e32 v244, v176, v176
	v_mul_f32_e32 v246, v177, v177
	v_mul_f32_e32 v238, v249, v249
	v_pk_add_f32 v[244:245], v[244:245], v[246:247]
	v_pk_add_f32 v[232:233], v[232:233], v[238:239]
	v_lshl_add_u64 v[238:239], v[206:207], 0, v[194:195]
	v_pk_add_f32 v[232:233], v[244:245], v[232:233]
	s_nop 0
	v_add_f32_e32 v232, v232, v233
	ds_bpermute_b32 v233, v225, v232
	s_waitcnt lgkmcnt(0)
	v_add_f32_e32 v232, v232, v233
	ds_bpermute_b32 v233, v224, v232
	s_waitcnt lgkmcnt(0)
	v_add_f32_e32 v232, v232, v233
	v_fmamk_f32 v232, v232, 0x3c800000, v210
	s_nop 0
	v_rsq_f32_e32 v232, v232
	s_nop 0
	v_mul_f32_e32 v232, v223, v232
	v_pk_mul_f32 v[228:229], v[228:229], v[232:233] op_sel_hi:[1,0]
	v_pk_mul_f32 v[230:231], v[230:231], v[232:233] op_sel_hi:[1,0]
	v_pk_mul_f32 v[228:229], v[140:141], v[228:229]
	v_pk_mul_f32 v[230:231], v[142:143], v[230:231]
	v_pk_mul_f32 v[234:235], v[234:235], v[232:233] op_sel_hi:[1,0]
	v_pk_mul_f32 v[236:237], v[236:237], v[232:233] op_sel_hi:[1,0]
	v_cvt_pk_bf16_f32 v228, v228, v229
	v_cvt_pk_bf16_f32 v229, v230, v231
	v_pk_mul_f32 v[234:235], v[136:137], v[234:235]
	v_pk_mul_f32 v[236:237], v[138:139], v[236:237]
	v_cvt_pk_bf16_f32 v230, v234, v235
	v_pk_mul_f32 v[176:177], v[176:177], v[232:233] op_sel_hi:[1,0]
	v_cvt_pk_bf16_f32 v231, v236, v237
	global_store_dwordx4 v[238:239], v[228:231], off
	v_pk_mul_f32 v[176:177], v[128:129], v[176:177]
	s_nop 0
	v_pk_mul_f32 v[228:229], v[242:243], v[232:233] op_sel_hi:[1,0]
	v_pk_mul_f32 v[230:231], v[240:241], v[232:233] op_sel_hi:[1,0]
	v_pk_mul_f32 v[228:229], v[132:133], v[228:229]
	v_pk_mul_f32 v[230:231], v[134:135], v[230:231]
	v_pk_mul_f32 v[232:233], v[248:249], v[232:233] op_sel_hi:[1,0]
	v_cvt_pk_bf16_f32 v228, v228, v229
	v_cvt_pk_bf16_f32 v229, v230, v231
	v_cvt_pk_bf16_f32 v230, v176, v177
	s_nop 0
	v_pk_mul_f32 v[232:233], v[130:131], v[232:233]
	s_nop 0
	v_cvt_pk_bf16_f32 v231, v232, v233
	global_store_dwordx4 v[238:239], v[228:231], off offset:64
	s_nop 1
	v_min_u32_e32 v228, 32, v219
	v_lshlrev_b64 v[176:177], v228, v[196:197]
	v_min_u32_e32 v176, 1, v176
	v_or_b32_e32 v176, v177, v176
	v_cvt_f32_u32_e32 v176, v176
	v_sub_u32_e32 v177, 32, v228
	v_ldexp_f32 v176, v176, v177
	v_mul_f32_e32 v176, 0x35800000, v176
	v_fmamk_f32 v176, v176, 0x3a800000, v210
	s_nop 0
	v_rsq_f32_e32 v176, v176
	s_nop 0
	v_pk_mul_f32 v[228:229], v[76:77], v[176:177] op_sel_hi:[1,0]
	v_pk_mul_f32 v[230:231], v[78:79], v[176:177] op_sel_hi:[1,0]
	v_pk_mul_f32 v[234:235], v[228:229], v[228:229]
	v_pk_mul_f32 v[232:233], v[230:231], v[230:231]
	v_pk_mul_f32 v[248:249], v[66:67], v[176:177] op_sel_hi:[1,0]
	v_pk_mov_b32 v[236:237], v[234:235], v[232:233] op_sel:[1,0]
	v_mov_b32_e32 v235, v233
	v_pk_add_f32 v[232:233], v[236:237], v[234:235]
	v_pk_mul_f32 v[234:235], v[72:73], v[176:177] op_sel_hi:[1,0]
	v_pk_mul_f32 v[236:237], v[74:75], v[176:177] op_sel_hi:[1,0]
	v_pk_mul_f32 v[240:241], v[234:235], v[234:235]
	v_pk_mul_f32 v[238:239], v[236:237], v[236:237]
	v_pk_add_f32 v[232:233], v[232:233], v[232:233] op_sel_hi:[0,1]
	v_pk_mov_b32 v[242:243], v[240:241], v[238:239] op_sel:[1,0]
	v_mov_b32_e32 v241, v239
	v_pk_add_f32 v[238:239], v[242:243], v[240:241]
	v_pk_mul_f32 v[242:243], v[68:69], v[176:177] op_sel_hi:[1,0]
	v_pk_mul_f32 v[240:241], v[70:71], v[176:177] op_sel_hi:[1,0]
	v_mul_f32_e32 v232, v242, v242
	v_pk_fma_f32 v[244:245], v[242:243], v[242:243], v[232:233] op_sel_hi:[1,1,0]
	v_mul_f32_e32 v232, v240, v240
	v_pk_add_f32 v[238:239], v[238:239], v[238:239] op_sel_hi:[0,1]
	v_pk_fma_f32 v[246:247], v[240:241], v[240:241], v[232:233] op_sel_hi:[1,1,0]
	v_pk_mul_f32 v[176:177], v[64:65], v[176:177] op_sel_hi:[1,0]
	v_mul_f32_e32 v232, v248, v248
	v_mul_f32_e32 v244, v176, v176
	v_mul_f32_e32 v246, v177, v177
	v_mul_f32_e32 v238, v249, v249
	v_pk_add_f32 v[244:245], v[244:245], v[246:247]
	v_pk_add_f32 v[232:233], v[232:233], v[238:239]
	v_lshl_add_u64 v[238:239], v[206:207], 0, v[190:191]
	v_pk_add_f32 v[232:233], v[244:245], v[232:233]
	s_nop 0
	v_add_f32_e32 v232, v232, v233
	ds_bpermute_b32 v233, v225, v232
	s_waitcnt lgkmcnt(0)
	v_add_f32_e32 v232, v232, v233
	ds_bpermute_b32 v233, v224, v232
	s_waitcnt lgkmcnt(0)
	v_add_f32_e32 v232, v232, v233
	v_fmamk_f32 v232, v232, 0x3c800000, v210
	s_nop 0
	v_rsq_f32_e32 v232, v232
	s_nop 0
	v_mul_f32_e32 v232, v223, v232
	v_pk_mul_f32 v[228:229], v[228:229], v[232:233] op_sel_hi:[1,0]
	v_pk_mul_f32 v[230:231], v[230:231], v[232:233] op_sel_hi:[1,0]
	v_pk_mul_f32 v[228:229], v[140:141], v[228:229]
	v_pk_mul_f32 v[230:231], v[142:143], v[230:231]
	v_pk_mul_f32 v[234:235], v[234:235], v[232:233] op_sel_hi:[1,0]
	v_pk_mul_f32 v[236:237], v[236:237], v[232:233] op_sel_hi:[1,0]
	v_pk_mul_f32 v[234:235], v[136:137], v[234:235]
	v_pk_mul_f32 v[236:237], v[138:139], v[236:237]
	v_cvt_pk_bf16_f32 v228, v228, v229
	v_cvt_pk_bf16_f32 v229, v230, v231
	v_cvt_pk_bf16_f32 v230, v234, v235
	v_pk_mul_f32 v[176:177], v[176:177], v[232:233] op_sel_hi:[1,0]
	v_cvt_pk_bf16_f32 v231, v236, v237
	global_store_dwordx4 v[238:239], v[228:231], off
	v_pk_mul_f32 v[176:177], v[128:129], v[176:177]
	s_nop 0
	v_pk_mul_f32 v[228:229], v[242:243], v[232:233] op_sel_hi:[1,0]
	v_pk_mul_f32 v[230:231], v[240:241], v[232:233] op_sel_hi:[1,0]
	v_pk_mul_f32 v[228:229], v[132:133], v[228:229]
	v_pk_mul_f32 v[230:231], v[134:135], v[230:231]
	v_pk_mul_f32 v[232:233], v[248:249], v[232:233] op_sel_hi:[1,0]
	v_cvt_pk_bf16_f32 v228, v228, v229
	v_cvt_pk_bf16_f32 v229, v230, v231
	v_cvt_pk_bf16_f32 v230, v176, v177
	v_ffbh_u32_e32 v176, v167
	v_pk_mul_f32 v[232:233], v[130:131], v[232:233]
	s_nop 0
	v_cvt_pk_bf16_f32 v231, v232, v233
	global_store_dwordx4 v[238:239], v[228:231], off offset:64
	s_nop 1
	v_min_u32_e32 v228, 32, v176
	v_lshlrev_b64 v[176:177], v228, v[166:167]
	v_min_u32_e32 v176, 1, v176
	v_or_b32_e32 v176, v177, v176
	v_cvt_f32_u32_e32 v176, v176
	v_sub_u32_e32 v177, 32, v228
	v_ldexp_f32 v176, v176, v177
	v_mul_f32_e32 v176, 0x35800000, v176
	v_fmamk_f32 v176, v176, 0x3a800000, v210
	s_nop 0
	v_rsq_f32_e32 v176, v176
	s_nop 0
	v_pk_mul_f32 v[228:229], v[60:61], v[176:177] op_sel_hi:[1,0]
	v_pk_mul_f32 v[230:231], v[62:63], v[176:177] op_sel_hi:[1,0]
	v_pk_mul_f32 v[234:235], v[228:229], v[228:229]
	v_pk_mul_f32 v[232:233], v[230:231], v[230:231]
	v_pk_mul_f32 v[248:249], v[50:51], v[176:177] op_sel_hi:[1,0]
	v_pk_mov_b32 v[236:237], v[234:235], v[232:233] op_sel:[1,0]
	v_mov_b32_e32 v235, v233
	v_pk_add_f32 v[232:233], v[236:237], v[234:235]
	v_pk_mul_f32 v[234:235], v[56:57], v[176:177] op_sel_hi:[1,0]
	v_pk_mul_f32 v[236:237], v[58:59], v[176:177] op_sel_hi:[1,0]
	v_pk_mul_f32 v[240:241], v[234:235], v[234:235]
	v_pk_mul_f32 v[238:239], v[236:237], v[236:237]
	v_pk_add_f32 v[232:233], v[232:233], v[232:233] op_sel_hi:[0,1]
	v_pk_mov_b32 v[242:243], v[240:241], v[238:239] op_sel:[1,0]
	v_mov_b32_e32 v241, v239
	v_pk_add_f32 v[238:239], v[242:243], v[240:241]
	v_pk_mul_f32 v[242:243], v[52:53], v[176:177] op_sel_hi:[1,0]
	v_pk_mul_f32 v[240:241], v[54:55], v[176:177] op_sel_hi:[1,0]
	v_mul_f32_e32 v232, v242, v242
	v_pk_fma_f32 v[244:245], v[242:243], v[242:243], v[232:233] op_sel_hi:[1,1,0]
	v_mul_f32_e32 v232, v240, v240
	v_pk_add_f32 v[238:239], v[238:239], v[238:239] op_sel_hi:[0,1]
	v_pk_fma_f32 v[246:247], v[240:241], v[240:241], v[232:233] op_sel_hi:[1,1,0]
	v_pk_mul_f32 v[176:177], v[48:49], v[176:177] op_sel_hi:[1,0]
	v_mul_f32_e32 v232, v248, v248
	v_mul_f32_e32 v244, v176, v176
	v_mul_f32_e32 v246, v177, v177
	v_mul_f32_e32 v238, v249, v249
	v_pk_add_f32 v[244:245], v[244:245], v[246:247]
	v_pk_add_f32 v[232:233], v[232:233], v[238:239]
	v_lshlrev_b64 v[238:239], 10, v[168:169]
	v_pk_add_f32 v[232:233], v[244:245], v[232:233]
	v_lshl_add_u64 v[238:239], v[206:207], 0, v[238:239]
	v_add_f32_e32 v232, v232, v233
	ds_bpermute_b32 v233, v225, v232
	s_waitcnt lgkmcnt(0)
	v_add_f32_e32 v232, v232, v233
	ds_bpermute_b32 v233, v224, v232
	s_waitcnt lgkmcnt(0)
	v_add_f32_e32 v232, v232, v233
	v_fmamk_f32 v232, v232, 0x3c800000, v210
	s_nop 0
	v_rsq_f32_e32 v232, v232
	s_nop 0
	v_mul_f32_e32 v232, v223, v232
	v_pk_mul_f32 v[228:229], v[228:229], v[232:233] op_sel_hi:[1,0]
	v_pk_mul_f32 v[230:231], v[230:231], v[232:233] op_sel_hi:[1,0]
	v_pk_mul_f32 v[228:229], v[140:141], v[228:229]
	v_pk_mul_f32 v[230:231], v[142:143], v[230:231]
	v_pk_mul_f32 v[234:235], v[234:235], v[232:233] op_sel_hi:[1,0]
	v_pk_mul_f32 v[236:237], v[236:237], v[232:233] op_sel_hi:[1,0]
	v_pk_mul_f32 v[234:235], v[136:137], v[234:235]
	v_pk_mul_f32 v[236:237], v[138:139], v[236:237]
	v_cvt_pk_bf16_f32 v228, v228, v229
	v_cvt_pk_bf16_f32 v229, v230, v231
	v_cvt_pk_bf16_f32 v230, v234, v235
	v_pk_mul_f32 v[176:177], v[176:177], v[232:233] op_sel_hi:[1,0]
	v_cvt_pk_bf16_f32 v231, v236, v237
	global_store_dwordx4 v[238:239], v[228:231], off
	v_pk_mul_f32 v[176:177], v[128:129], v[176:177]
	s_nop 0
	v_pk_mul_f32 v[228:229], v[242:243], v[232:233] op_sel_hi:[1,0]
	v_pk_mul_f32 v[230:231], v[240:241], v[232:233] op_sel_hi:[1,0]
	v_pk_mul_f32 v[228:229], v[132:133], v[228:229]
	v_pk_mul_f32 v[230:231], v[134:135], v[230:231]
	v_pk_mul_f32 v[232:233], v[248:249], v[232:233] op_sel_hi:[1,0]
	v_cvt_pk_bf16_f32 v228, v228, v229
	v_cvt_pk_bf16_f32 v229, v230, v231
	v_cvt_pk_bf16_f32 v230, v176, v177
	v_ffbh_u32_e32 v176, v189
	v_pk_mul_f32 v[232:233], v[130:131], v[232:233]
	s_nop 0
	v_cvt_pk_bf16_f32 v231, v232, v233
	global_store_dwordx4 v[238:239], v[228:231], off offset:64
	s_nop 1
	v_min_u32_e32 v228, 32, v176
	v_lshlrev_b64 v[176:177], v228, v[188:189]
	v_min_u32_e32 v176, 1, v176
	v_or_b32_e32 v176, v177, v176
	v_cvt_f32_u32_e32 v176, v176
	v_sub_u32_e32 v177, 32, v228
	v_ldexp_f32 v176, v176, v177
	v_mul_f32_e32 v176, 0x35800000, v176
	v_fmamk_f32 v176, v176, 0x3a800000, v210
	s_nop 0
	v_rsq_f32_e32 v176, v176
	s_nop 0
	v_pk_mul_f32 v[228:229], v[44:45], v[176:177] op_sel_hi:[1,0]
	v_pk_mul_f32 v[230:231], v[46:47], v[176:177] op_sel_hi:[1,0]
	v_pk_mul_f32 v[234:235], v[228:229], v[228:229]
	v_pk_mul_f32 v[232:233], v[230:231], v[230:231]
	v_pk_mul_f32 v[248:249], v[34:35], v[176:177] op_sel_hi:[1,0]
	v_pk_mov_b32 v[236:237], v[234:235], v[232:233] op_sel:[1,0]
	v_mov_b32_e32 v235, v233
	v_pk_add_f32 v[232:233], v[236:237], v[234:235]
	v_pk_mul_f32 v[234:235], v[40:41], v[176:177] op_sel_hi:[1,0]
	v_pk_mul_f32 v[236:237], v[42:43], v[176:177] op_sel_hi:[1,0]
	v_pk_mul_f32 v[240:241], v[234:235], v[234:235]
	v_pk_mul_f32 v[238:239], v[236:237], v[236:237]
	v_pk_add_f32 v[232:233], v[232:233], v[232:233] op_sel_hi:[0,1]
	v_pk_mov_b32 v[242:243], v[240:241], v[238:239] op_sel:[1,0]
	v_mov_b32_e32 v241, v239
	v_pk_add_f32 v[238:239], v[242:243], v[240:241]
	v_pk_mul_f32 v[242:243], v[36:37], v[176:177] op_sel_hi:[1,0]
	v_pk_mul_f32 v[240:241], v[38:39], v[176:177] op_sel_hi:[1,0]
	v_mul_f32_e32 v232, v242, v242
	v_pk_fma_f32 v[244:245], v[242:243], v[242:243], v[232:233] op_sel_hi:[1,1,0]
	v_mul_f32_e32 v232, v240, v240
	v_pk_add_f32 v[238:239], v[238:239], v[238:239] op_sel_hi:[0,1]
	v_pk_fma_f32 v[246:247], v[240:241], v[240:241], v[232:233] op_sel_hi:[1,1,0]
	v_pk_mul_f32 v[176:177], v[32:33], v[176:177] op_sel_hi:[1,0]
	v_mul_f32_e32 v232, v248, v248
	v_mul_f32_e32 v244, v176, v176
	v_mul_f32_e32 v246, v177, v177
	v_mul_f32_e32 v238, v249, v249
	v_pk_add_f32 v[244:245], v[244:245], v[246:247]
	v_pk_add_f32 v[232:233], v[232:233], v[238:239]
	v_lshlrev_b64 v[238:239], 10, v[164:165]
	v_pk_add_f32 v[232:233], v[244:245], v[232:233]
	v_lshl_add_u64 v[238:239], v[206:207], 0, v[238:239]
	v_add_f32_e32 v232, v232, v233
	ds_bpermute_b32 v233, v225, v232
	s_waitcnt lgkmcnt(0)
	v_add_f32_e32 v232, v232, v233
	ds_bpermute_b32 v233, v224, v232
	s_waitcnt lgkmcnt(0)
	v_add_f32_e32 v232, v232, v233
	v_fmamk_f32 v232, v232, 0x3c800000, v210
	s_nop 0
	v_rsq_f32_e32 v232, v232
	s_nop 0
	v_mul_f32_e32 v232, v223, v232
	v_pk_mul_f32 v[228:229], v[228:229], v[232:233] op_sel_hi:[1,0]
	v_pk_mul_f32 v[230:231], v[230:231], v[232:233] op_sel_hi:[1,0]
	v_pk_mul_f32 v[228:229], v[140:141], v[228:229]
	v_pk_mul_f32 v[230:231], v[142:143], v[230:231]
	v_pk_mul_f32 v[234:235], v[234:235], v[232:233] op_sel_hi:[1,0]
	v_pk_mul_f32 v[236:237], v[236:237], v[232:233] op_sel_hi:[1,0]
	v_pk_mul_f32 v[234:235], v[136:137], v[234:235]
	v_pk_mul_f32 v[236:237], v[138:139], v[236:237]
	v_cvt_pk_bf16_f32 v228, v228, v229
	v_cvt_pk_bf16_f32 v229, v230, v231
	v_cvt_pk_bf16_f32 v230, v234, v235
	v_pk_mul_f32 v[176:177], v[176:177], v[232:233] op_sel_hi:[1,0]
	v_cvt_pk_bf16_f32 v231, v236, v237
	global_store_dwordx4 v[238:239], v[228:231], off
	v_pk_mul_f32 v[176:177], v[128:129], v[176:177]
	s_nop 0
	v_pk_mul_f32 v[228:229], v[242:243], v[232:233] op_sel_hi:[1,0]
	v_pk_mul_f32 v[230:231], v[240:241], v[232:233] op_sel_hi:[1,0]
	v_pk_mul_f32 v[228:229], v[132:133], v[228:229]
	v_pk_mul_f32 v[230:231], v[134:135], v[230:231]
	v_pk_mul_f32 v[232:233], v[248:249], v[232:233] op_sel_hi:[1,0]
	v_cvt_pk_bf16_f32 v228, v228, v229
	v_cvt_pk_bf16_f32 v229, v230, v231
	v_cvt_pk_bf16_f32 v230, v176, v177
	v_ffbh_u32_e32 v176, v163
	v_pk_mul_f32 v[232:233], v[130:131], v[232:233]
	s_nop 0
	v_cvt_pk_bf16_f32 v231, v232, v233
	global_store_dwordx4 v[238:239], v[228:231], off offset:64
	s_nop 1
	v_min_u32_e32 v228, 32, v176
	v_lshlrev_b64 v[176:177], v228, v[162:163]
	v_min_u32_e32 v176, 1, v176
	v_or_b32_e32 v176, v177, v176
	v_cvt_f32_u32_e32 v176, v176
	v_sub_u32_e32 v177, 32, v228
	v_ldexp_f32 v176, v176, v177
	v_mul_f32_e32 v176, 0x35800000, v176
	v_fmamk_f32 v176, v176, 0x3a800000, v210
	s_nop 0
	v_rsq_f32_e32 v176, v176
	s_nop 0
	v_pk_mul_f32 v[228:229], v[28:29], v[176:177] op_sel_hi:[1,0]
	v_pk_mul_f32 v[230:231], v[30:31], v[176:177] op_sel_hi:[1,0]
	v_pk_mul_f32 v[234:235], v[228:229], v[228:229]
	v_pk_mul_f32 v[232:233], v[230:231], v[230:231]
	v_pk_mul_f32 v[248:249], v[18:19], v[176:177] op_sel_hi:[1,0]
	v_pk_mov_b32 v[236:237], v[234:235], v[232:233] op_sel:[1,0]
	v_mov_b32_e32 v235, v233
	v_pk_add_f32 v[232:233], v[236:237], v[234:235]
	v_pk_mul_f32 v[234:235], v[24:25], v[176:177] op_sel_hi:[1,0]
	v_pk_mul_f32 v[236:237], v[26:27], v[176:177] op_sel_hi:[1,0]
	v_pk_mul_f32 v[240:241], v[234:235], v[234:235]
	v_pk_mul_f32 v[238:239], v[236:237], v[236:237]
	v_pk_add_f32 v[232:233], v[232:233], v[232:233] op_sel_hi:[0,1]
	v_pk_mov_b32 v[242:243], v[240:241], v[238:239] op_sel:[1,0]
	v_mov_b32_e32 v241, v239
	v_pk_add_f32 v[238:239], v[242:243], v[240:241]
	v_pk_mul_f32 v[242:243], v[20:21], v[176:177] op_sel_hi:[1,0]
	v_pk_mul_f32 v[240:241], v[22:23], v[176:177] op_sel_hi:[1,0]
	v_mul_f32_e32 v232, v242, v242
	v_pk_fma_f32 v[244:245], v[242:243], v[242:243], v[232:233] op_sel_hi:[1,1,0]
	v_mul_f32_e32 v232, v240, v240
	v_pk_add_f32 v[238:239], v[238:239], v[238:239] op_sel_hi:[0,1]
	v_pk_fma_f32 v[246:247], v[240:241], v[240:241], v[232:233] op_sel_hi:[1,1,0]
	v_pk_mul_f32 v[176:177], v[16:17], v[176:177] op_sel_hi:[1,0]
	v_mul_f32_e32 v232, v248, v248
	v_mul_f32_e32 v244, v176, v176
	v_mul_f32_e32 v246, v177, v177
	v_mul_f32_e32 v238, v249, v249
	v_pk_add_f32 v[244:245], v[244:245], v[246:247]
	v_pk_add_f32 v[232:233], v[232:233], v[238:239]
	v_lshlrev_b64 v[238:239], 10, v[158:159]
	v_pk_add_f32 v[232:233], v[244:245], v[232:233]
	v_lshl_add_u64 v[238:239], v[206:207], 0, v[238:239]
	v_add_f32_e32 v232, v232, v233
	ds_bpermute_b32 v233, v225, v232
	s_waitcnt lgkmcnt(0)
	v_add_f32_e32 v232, v232, v233
	ds_bpermute_b32 v233, v224, v232
	s_waitcnt lgkmcnt(0)
	v_add_f32_e32 v232, v232, v233
	v_fmamk_f32 v232, v232, 0x3c800000, v210
	s_nop 0
	v_rsq_f32_e32 v232, v232
	s_nop 0
	v_mul_f32_e32 v232, v223, v232
	v_pk_mul_f32 v[228:229], v[228:229], v[232:233] op_sel_hi:[1,0]
	v_pk_mul_f32 v[230:231], v[230:231], v[232:233] op_sel_hi:[1,0]
	v_pk_mul_f32 v[228:229], v[140:141], v[228:229]
	v_pk_mul_f32 v[230:231], v[142:143], v[230:231]
	v_pk_mul_f32 v[234:235], v[234:235], v[232:233] op_sel_hi:[1,0]
	v_pk_mul_f32 v[236:237], v[236:237], v[232:233] op_sel_hi:[1,0]
	v_pk_mul_f32 v[234:235], v[136:137], v[234:235]
	v_pk_mul_f32 v[236:237], v[138:139], v[236:237]
	v_cvt_pk_bf16_f32 v228, v228, v229
	v_cvt_pk_bf16_f32 v229, v230, v231
	v_cvt_pk_bf16_f32 v230, v234, v235
	v_pk_mul_f32 v[176:177], v[176:177], v[232:233] op_sel_hi:[1,0]
	v_cvt_pk_bf16_f32 v231, v236, v237
	global_store_dwordx4 v[238:239], v[228:231], off
	v_pk_mul_f32 v[176:177], v[128:129], v[176:177]
	s_nop 0
	v_pk_mul_f32 v[228:229], v[242:243], v[232:233] op_sel_hi:[1,0]
	v_pk_mul_f32 v[230:231], v[240:241], v[232:233] op_sel_hi:[1,0]
	v_pk_mul_f32 v[228:229], v[132:133], v[228:229]
	v_pk_mul_f32 v[230:231], v[134:135], v[230:231]
	v_pk_mul_f32 v[232:233], v[248:249], v[232:233] op_sel_hi:[1,0]
	v_cvt_pk_bf16_f32 v228, v228, v229
	v_cvt_pk_bf16_f32 v229, v230, v231
	v_cvt_pk_bf16_f32 v230, v176, v177
	v_ffbh_u32_e32 v176, v161
	v_pk_mul_f32 v[232:233], v[130:131], v[232:233]
	s_nop 0
	v_cvt_pk_bf16_f32 v231, v232, v233
	global_store_dwordx4 v[238:239], v[228:231], off offset:64
	s_nop 1
	v_min_u32_e32 v228, 32, v176
	v_lshlrev_b64 v[176:177], v228, v[160:161]
	v_min_u32_e32 v176, 1, v176
	v_or_b32_e32 v176, v177, v176
	v_cvt_f32_u32_e32 v176, v176
	v_sub_u32_e32 v177, 32, v228
	v_ldexp_f32 v176, v176, v177
	v_mul_f32_e32 v176, 0x35800000, v176
	v_fmamk_f32 v176, v176, 0x3a800000, v210
	s_nop 0
	v_rsq_f32_e32 v176, v176
	s_nop 0
	v_pk_mul_f32 v[228:229], v[12:13], v[176:177] op_sel_hi:[1,0]
	v_pk_mul_f32 v[230:231], v[14:15], v[176:177] op_sel_hi:[1,0]
	v_pk_mul_f32 v[234:235], v[228:229], v[228:229]
	v_pk_mul_f32 v[232:233], v[230:231], v[230:231]
	v_pk_mul_f32 v[248:249], v[2:3], v[176:177] op_sel_hi:[1,0]
	v_pk_mov_b32 v[236:237], v[234:235], v[232:233] op_sel:[1,0]
	v_mov_b32_e32 v235, v233
	v_pk_add_f32 v[232:233], v[236:237], v[234:235]
	v_pk_mul_f32 v[234:235], v[8:9], v[176:177] op_sel_hi:[1,0]
	v_pk_mul_f32 v[236:237], v[10:11], v[176:177] op_sel_hi:[1,0]
	v_pk_mul_f32 v[240:241], v[234:235], v[234:235]
	v_pk_mul_f32 v[238:239], v[236:237], v[236:237]
	v_pk_add_f32 v[232:233], v[232:233], v[232:233] op_sel_hi:[0,1]
	v_pk_mov_b32 v[242:243], v[240:241], v[238:239] op_sel:[1,0]
	v_mov_b32_e32 v241, v239
	v_pk_add_f32 v[238:239], v[242:243], v[240:241]
	v_pk_mul_f32 v[242:243], v[4:5], v[176:177] op_sel_hi:[1,0]
	v_pk_mul_f32 v[240:241], v[6:7], v[176:177] op_sel_hi:[1,0]
	v_mul_f32_e32 v232, v242, v242
	v_pk_fma_f32 v[244:245], v[242:243], v[242:243], v[232:233] op_sel_hi:[1,1,0]
	v_mul_f32_e32 v232, v240, v240
	v_pk_add_f32 v[238:239], v[238:239], v[238:239] op_sel_hi:[0,1]
	v_pk_fma_f32 v[246:247], v[240:241], v[240:241], v[232:233] op_sel_hi:[1,1,0]
	v_pk_mul_f32 v[176:177], v[0:1], v[176:177] op_sel_hi:[1,0]
	v_mul_f32_e32 v232, v248, v248
	v_mul_f32_e32 v244, v176, v176
	v_mul_f32_e32 v246, v177, v177
	v_mul_f32_e32 v238, v249, v249
	v_pk_add_f32 v[244:245], v[244:245], v[246:247]
	v_pk_add_f32 v[232:233], v[232:233], v[238:239]
	s_nop 0
	v_pk_add_f32 v[232:233], v[244:245], v[232:233]
	s_nop 0
	v_add_f32_e32 v232, v232, v233
	ds_bpermute_b32 v225, v225, v232
	s_waitcnt lgkmcnt(0)
	v_add_f32_e32 v225, v232, v225
	ds_bpermute_b32 v224, v224, v225
	v_lshlrev_b64 v[232:233], 10, v[156:157]
	v_lshl_add_u64 v[206:207], v[206:207], 0, v[232:233]
	s_waitcnt lgkmcnt(0)
	v_add_f32_e32 v224, v225, v224
	v_fmamk_f32 v224, v224, 0x3c800000, v210
	s_nop 0
	v_rsq_f32_e32 v224, v224
	s_nop 0
	v_mul_f32_e32 v224, v223, v224
	v_pk_mul_f32 v[228:229], v[228:229], v[224:225] op_sel_hi:[1,0]
	v_pk_mul_f32 v[230:231], v[230:231], v[224:225] op_sel_hi:[1,0]
	v_pk_mul_f32 v[140:141], v[140:141], v[228:229]
	v_pk_mul_f32 v[142:143], v[142:143], v[230:231]
	v_pk_mul_f32 v[228:229], v[234:235], v[224:225] op_sel_hi:[1,0]
	v_pk_mul_f32 v[230:231], v[236:237], v[224:225] op_sel_hi:[1,0]
	s_nop 0
	v_pk_mul_f32 v[230:231], v[138:139], v[230:231]
	v_pk_mul_f32 v[138:139], v[136:137], v[228:229]
	v_cvt_pk_bf16_f32 v136, v140, v141
	v_cvt_pk_bf16_f32 v137, v142, v143
	s_nop 0
	v_cvt_pk_bf16_f32 v138, v138, v139
	v_cvt_pk_bf16_f32 v139, v230, v231
	global_store_dwordx4 v[206:207], v[136:139], off
	s_nop 1
	v_pk_mul_f32 v[136:137], v[242:243], v[224:225] op_sel_hi:[1,0]
	v_pk_mul_f32 v[138:139], v[240:241], v[224:225] op_sel_hi:[1,0]
	v_pk_mul_f32 v[132:133], v[132:133], v[136:137]
	v_pk_mul_f32 v[134:135], v[134:135], v[138:139]
	v_pk_mul_f32 v[136:137], v[176:177], v[224:225] op_sel_hi:[1,0]
	v_pk_mul_f32 v[138:139], v[248:249], v[224:225] op_sel_hi:[1,0]
	s_nop 0
	v_pk_mul_f32 v[138:139], v[130:131], v[138:139]
	v_pk_mul_f32 v[130:131], v[128:129], v[136:137]
	v_cvt_pk_bf16_f32 v128, v132, v133
	v_cvt_pk_bf16_f32 v129, v134, v135
	s_nop 0
	v_cvt_pk_bf16_f32 v130, v130, v131
	v_cvt_pk_bf16_f32 v131, v138, v139
	s_nop 1

.LBB0_350:
	s_nop 0
	s_lshl_b32 s25, s84, 1
	s_add_i32 s25, s85, s25
	s_and_b32 s85, s25, 3
	s_lshl_b32 s25, s85, 19
	s_add_u32 s92, s74, s25
	v_cmp_lt_i64_e32 vcc, s[52:53], v[180:181]
	s_addc_u32 s93, s75, 0
	s_and_b64 s[30:31], vcc, exec
	s_cselect_b32 s25, s93, s1
	s_cselect_b32 s30, s92, s0
	s_ashr_i32 s47, s46, 31
	s_lshl_b64 s[34:35], s[46:47], 19
	s_add_u32 s94, s54, s34
	s_addc_u32 s95, s55, s35
	s_and_b64 s[34:35], vcc, exec
	s_cselect_b32 s31, s95, s51
	s_cselect_b32 s33, s94, s50
	s_add_u32 s0, s0, 0x40080
	s_addc_u32 s1, s1, 0
	s_add_u32 s34, s50, 0x100
	s_addc_u32 s35, s51, 0
	s_mov_b32 s36, -2
	s_add_u32 s27, s0, 0xfffc0080
	s_addc_u32 s37, s1, -1
	s_add_i32 s47, 0, 0x10000
	ds_read_b128 v[128:131], v192
	ds_read_b128 v[132:135], v192 offset:1024
	ds_read_b128 v[136:139], v192 offset:2048
	ds_read_b128 v[140:143], v192 offset:3072
	s_cmp_eq_u32 s36, 12
	s_cselect_b32 s53, s25, s37
	s_cselect_b32 s52, s30, s27
	s_cselect_b32 s51, s31, s35
	s_cselect_b32 s50, s33, s34
	s_add_i32 m0, s77, 0xc000
	ds_read_b128 v[162:165], v194
	ds_read_b128 v[166:169], v194 offset:1024
	ds_read_b128 v[196:199], v194 offset:2048
	ds_read_b128 v[200:203], v194 offset:3072
	ds_read_b128 v[204:207], v194 offset:4096
	ds_read_b128 v[216:219], v194 offset:5120
	ds_read_b128 v[220:223], v194 offset:6144
	ds_read_b128 v[228:231], v194 offset:7168
	global_load_lds_dwordx4 v156, s[0:1]
	s_add_i32 m0, s77, 0xe000
	s_nop 0
	global_load_lds_dwordx4 v158, s[0:1]
	s_waitcnt lgkmcnt(0)
	s_barrier
	v_mfma_f32_16x16x32_bf16 v[124:127], v[128:131], v[162:165], 0
	v_mfma_f32_16x16x32_bf16 v[120:123], v[136:139], v[162:165], 0
	v_mfma_f32_16x16x32_bf16 v[116:119], v[128:131], v[196:199], 0
	v_mfma_f32_16x16x32_bf16 v[112:115], v[136:139], v[196:199], 0
	v_mfma_f32_16x16x32_bf16 v[108:111], v[128:131], v[204:207], 0
	v_mfma_f32_16x16x32_bf16 v[104:107], v[136:139], v[204:207], 0
	v_mfma_f32_16x16x32_bf16 v[100:103], v[128:131], v[220:223], 0
	v_mfma_f32_16x16x32_bf16 v[96:99], v[136:139], v[220:223], 0
	v_mfma_f32_16x16x32_bf16 v[124:127], v[132:135], v[166:169], v[124:127]
	v_mfma_f32_16x16x32_bf16 v[120:123], v[140:143], v[166:169], v[120:123]
	v_mfma_f32_16x16x32_bf16 v[116:119], v[132:135], v[200:203], v[116:119]
	v_mfma_f32_16x16x32_bf16 v[112:115], v[140:143], v[200:203], v[112:115]
	v_mfma_f32_16x16x32_bf16 v[108:111], v[132:135], v[216:219], v[108:111]
	v_mfma_f32_16x16x32_bf16 v[104:107], v[140:143], v[216:219], v[104:107]
	v_mfma_f32_16x16x32_bf16 v[100:103], v[132:135], v[228:231], v[100:103]
	v_mfma_f32_16x16x32_bf16 v[96:99], v[140:143], v[228:231], v[96:99]
	s_barrier
	s_add_i32 s27, 0, 0x14000
	s_add_i32 s37, s47, s76
	s_mov_b32 m0, s37
	ds_read_b128 v[232:235], v192 offset:16384
	ds_read_b128 v[236:239], v192 offset:17408
	ds_read_b128 v[240:243], v192 offset:18432
	ds_read_b128 v[244:247], v192 offset:19456
	global_load_lds_dwordx4 v148, s[50:51]
	s_add_i32 m0, s37, 0x2000
	s_nop 0
	global_load_lds_dwordx4 v152, s[50:51]
	s_waitcnt lgkmcnt(0)
	s_barrier
	v_mfma_f32_16x16x32_bf16 v[92:95], v[232:235], v[162:165], 0
	v_mfma_f32_16x16x32_bf16 v[88:91], v[240:243], v[162:165], 0
	v_mfma_f32_16x16x32_bf16 v[84:87], v[232:235], v[196:199], 0
	v_mfma_f32_16x16x32_bf16 v[80:83], v[240:243], v[196:199], 0
	v_mfma_f32_16x16x32_bf16 v[76:79], v[232:235], v[204:207], 0
	v_mfma_f32_16x16x32_bf16 v[72:75], v[240:243], v[204:207], 0
	v_mfma_f32_16x16x32_bf16 v[68:71], v[232:235], v[220:223], 0
	v_mfma_f32_16x16x32_bf16 v[64:67], v[240:243], v[220:223], 0
	v_mfma_f32_16x16x32_bf16 v[92:95], v[236:239], v[166:169], v[92:95]
	v_mfma_f32_16x16x32_bf16 v[88:91], v[244:247], v[166:169], v[88:91]
	v_mfma_f32_16x16x32_bf16 v[84:87], v[236:239], v[200:203], v[84:87]
	v_mfma_f32_16x16x32_bf16 v[80:83], v[244:247], v[200:203], v[80:83]
	v_mfma_f32_16x16x32_bf16 v[76:79], v[236:239], v[216:219], v[76:79]
	v_mfma_f32_16x16x32_bf16 v[72:75], v[244:247], v[216:219], v[72:75]
	v_mfma_f32_16x16x32_bf16 v[68:71], v[236:239], v[228:231], v[68:71]
	v_mfma_f32_16x16x32_bf16 v[64:67], v[244:247], v[228:231], v[64:67]
	s_barrier
	s_mov_b32 m0, s77
	v_lshl_add_u64 v[224:225], s[52:53], 0, v[146:147]
	ds_read_b128 v[162:165], v194 offset:16384
	ds_read_b128 v[166:169], v194 offset:17408
	ds_read_b128 v[196:199], v194 offset:18432
	ds_read_b128 v[200:203], v194 offset:19456
	ds_read_b128 v[204:207], v194 offset:20480
	ds_read_b128 v[216:219], v194 offset:21504
	ds_read_b128 v[220:223], v194 offset:22528
	ds_read_b128 v[228:231], v194 offset:23552
	global_load_lds_dwordx4 v[224:225], off
	v_lshl_add_u64 v[248:249], s[52:53], 0, v[150:151]
	s_mov_b32 m0, s78
	s_nop 0
	global_load_lds_dwordx4 v[248:249], off
	s_waitcnt lgkmcnt(0)
	s_waitcnt vmcnt(8)
	s_barrier
	v_mfma_f32_16x16x32_bf16 v[60:63], v[128:131], v[162:165], 0
	v_mfma_f32_16x16x32_bf16 v[56:59], v[136:139], v[162:165], 0
	v_mfma_f32_16x16x32_bf16 v[52:55], v[128:131], v[196:199], 0
	v_mfma_f32_16x16x32_bf16 v[48:51], v[136:139], v[196:199], 0
	v_mfma_f32_16x16x32_bf16 v[44:47], v[128:131], v[204:207], 0
	v_mfma_f32_16x16x32_bf16 v[40:43], v[136:139], v[204:207], 0
	v_mfma_f32_16x16x32_bf16 v[36:39], v[128:131], v[220:223], 0
	v_mfma_f32_16x16x32_bf16 v[32:35], v[136:139], v[220:223], 0
	v_mfma_f32_16x16x32_bf16 v[60:63], v[132:135], v[166:169], v[60:63]
	v_mfma_f32_16x16x32_bf16 v[56:59], v[140:143], v[166:169], v[56:59]
	v_mfma_f32_16x16x32_bf16 v[52:55], v[132:135], v[200:203], v[52:55]
	v_mfma_f32_16x16x32_bf16 v[48:51], v[140:143], v[200:203], v[48:51]
	v_mfma_f32_16x16x32_bf16 v[44:47], v[132:135], v[216:219], v[44:47]
	v_mfma_f32_16x16x32_bf16 v[40:43], v[140:143], v[216:219], v[40:43]
	v_mfma_f32_16x16x32_bf16 v[36:39], v[132:135], v[228:231], v[36:39]
	v_mfma_f32_16x16x32_bf16 v[32:35], v[140:143], v[228:231], v[32:35]
	s_add_u32 s56, s50, 0x40000
	s_addc_u32 s57, s51, 0
	s_add_i32 s27, s27, s76
	s_mov_b32 m0, s27
	s_nop 0
	global_load_lds_dwordx4 v148, s[56:57]
	s_add_i32 m0, s27, 0x2000
	s_nop 0
	global_load_lds_dwordx4 v152, s[56:57]
	s_waitcnt vmcnt(6)
	v_mfma_f32_16x16x32_bf16 v[28:31], v[232:235], v[162:165], 0
	v_mfma_f32_16x16x32_bf16 v[24:27], v[240:243], v[162:165], 0
	v_mfma_f32_16x16x32_bf16 v[20:23], v[232:235], v[196:199], 0
	v_mfma_f32_16x16x32_bf16 v[16:19], v[240:243], v[196:199], 0
	v_mfma_f32_16x16x32_bf16 v[12:15], v[232:235], v[204:207], 0
	v_mfma_f32_16x16x32_bf16 v[8:11], v[240:243], v[204:207], 0
	v_mfma_f32_16x16x32_bf16 v[4:7], v[232:235], v[220:223], 0
	v_mfma_f32_16x16x32_bf16 v[0:3], v[240:243], v[220:223], 0
	v_mfma_f32_16x16x32_bf16 v[28:31], v[236:239], v[166:169], v[28:31]
	v_mfma_f32_16x16x32_bf16 v[24:27], v[244:247], v[166:169], v[24:27]
	v_mfma_f32_16x16x32_bf16 v[20:23], v[236:239], v[200:203], v[20:23]
	v_mfma_f32_16x16x32_bf16 v[16:19], v[244:247], v[200:203], v[16:19]
	v_mfma_f32_16x16x32_bf16 v[12:15], v[236:239], v[216:219], v[12:15]
	v_mfma_f32_16x16x32_bf16 v[8:11], v[244:247], v[216:219], v[8:11]
	v_mfma_f32_16x16x32_bf16 v[4:7], v[236:239], v[228:231], v[4:7]
	v_mfma_f32_16x16x32_bf16 v[0:3], v[244:247], v[228:231], v[0:3]
	s_barrier
	s_add_i32 s27, 0, 0x18000
	ds_read_b128 v[128:131], v192 offset:32768
	ds_read_b128 v[132:135], v192 offset:33792
	ds_read_b128 v[136:139], v192 offset:34816
	ds_read_b128 v[140:143], v192 offset:35840
	s_add_u32 s52, s52, 0x40000
	s_addc_u32 s53, s53, 0
	s_mov_b32 m0, s81
	ds_read_b128 v[162:165], v194 offset:32768
	ds_read_b128 v[166:169], v194 offset:33792
	ds_read_b128 v[196:199], v194 offset:34816
	ds_read_b128 v[200:203], v194 offset:35840
	ds_read_b128 v[204:207], v194 offset:36864
	ds_read_b128 v[216:219], v194 offset:37888
	ds_read_b128 v[220:223], v194 offset:38912
	ds_read_b128 v[228:231], v194 offset:39936
	global_load_lds_dwordx4 v146, s[52:53]
	s_mov_b32 m0, s82
	s_nop 0
	global_load_lds_dwordx4 v150, s[52:53]
	s_waitcnt lgkmcnt(0)
	s_barrier
	v_mfma_f32_16x16x32_bf16 v[124:127], v[128:131], v[162:165], v[124:127]
	v_mfma_f32_16x16x32_bf16 v[120:123], v[136:139], v[162:165], v[120:123]
	v_mfma_f32_16x16x32_bf16 v[116:119], v[128:131], v[196:199], v[116:119]
	v_mfma_f32_16x16x32_bf16 v[112:115], v[136:139], v[196:199], v[112:115]
	v_mfma_f32_16x16x32_bf16 v[108:111], v[128:131], v[204:207], v[108:111]
	v_mfma_f32_16x16x32_bf16 v[104:107], v[136:139], v[204:207], v[104:107]
	v_mfma_f32_16x16x32_bf16 v[100:103], v[128:131], v[220:223], v[100:103]
	v_mfma_f32_16x16x32_bf16 v[96:99], v[136:139], v[220:223], v[96:99]
	v_mfma_f32_16x16x32_bf16 v[124:127], v[132:135], v[166:169], v[124:127]
	v_mfma_f32_16x16x32_bf16 v[120:123], v[140:143], v[166:169], v[120:123]
	v_mfma_f32_16x16x32_bf16 v[116:119], v[132:135], v[200:203], v[116:119]
	v_mfma_f32_16x16x32_bf16 v[112:115], v[140:143], v[200:203], v[112:115]
	v_mfma_f32_16x16x32_bf16 v[108:111], v[132:135], v[216:219], v[108:111]
	v_mfma_f32_16x16x32_bf16 v[104:107], v[140:143], v[216:219], v[104:107]
	v_mfma_f32_16x16x32_bf16 v[100:103], v[132:135], v[228:231], v[100:103]
	v_mfma_f32_16x16x32_bf16 v[96:99], v[140:143], v[228:231], v[96:99]
	s_barrier
	s_add_i32 s37, 0, 0x1c000
	s_add_i32 s27, s27, s76
	s_add_u32 s56, s50, s18
	s_addc_u32 s57, s51, s19
	s_mov_b32 m0, s27
	ds_read_b128 v[232:235], v192 offset:49152
	ds_read_b128 v[236:239], v192 offset:50176
	ds_read_b128 v[240:243], v192 offset:51200
	ds_read_b128 v[244:247], v192 offset:52224
	global_load_lds_dwordx4 v148, s[56:57]
	s_add_u32 s56, s50, s18
	s_addc_u32 s57, s51, s19
	s_add_i32 m0, s27, 0x2000
	s_nop 0
	global_load_lds_dwordx4 v152, s[56:57]
	s_waitcnt lgkmcnt(0)
	s_barrier
	v_mfma_f32_16x16x32_bf16 v[92:95], v[232:235], v[162:165], v[92:95]
	v_mfma_f32_16x16x32_bf16 v[88:91], v[240:243], v[162:165], v[88:91]
	v_mfma_f32_16x16x32_bf16 v[84:87], v[232:235], v[196:199], v[84:87]
	v_mfma_f32_16x16x32_bf16 v[80:83], v[240:243], v[196:199], v[80:83]
	v_mfma_f32_16x16x32_bf16 v[76:79], v[232:235], v[204:207], v[76:79]
	v_mfma_f32_16x16x32_bf16 v[72:75], v[240:243], v[204:207], v[72:75]
	v_mfma_f32_16x16x32_bf16 v[68:71], v[232:235], v[220:223], v[68:71]
	v_mfma_f32_16x16x32_bf16 v[64:67], v[240:243], v[220:223], v[64:67]
	v_mfma_f32_16x16x32_bf16 v[92:95], v[236:239], v[166:169], v[92:95]
	v_mfma_f32_16x16x32_bf16 v[88:91], v[244:247], v[166:169], v[88:91]
	v_mfma_f32_16x16x32_bf16 v[84:87], v[236:239], v[200:203], v[84:87]
	v_mfma_f32_16x16x32_bf16 v[80:83], v[244:247], v[200:203], v[80:83]
	v_mfma_f32_16x16x32_bf16 v[76:79], v[236:239], v[216:219], v[76:79]
	v_mfma_f32_16x16x32_bf16 v[72:75], v[244:247], v[216:219], v[72:75]
	v_mfma_f32_16x16x32_bf16 v[68:71], v[236:239], v[228:231], v[68:71]
	v_mfma_f32_16x16x32_bf16 v[64:67], v[244:247], v[228:231], v[64:67]
	s_barrier
	s_mov_b32 m0, s80
	v_lshl_add_u64 v[176:177], v[224:225], 0, s[18:19]
	ds_read_b128 v[162:165], v194 offset:49152
	ds_read_b128 v[166:169], v194 offset:50176
	ds_read_b128 v[196:199], v194 offset:51200
	ds_read_b128 v[200:203], v194 offset:52224
	ds_read_b128 v[204:207], v194 offset:53248
	ds_read_b128 v[216:219], v194 offset:54272
	ds_read_b128 v[220:223], v194 offset:55296
	ds_read_b128 v[228:231], v194 offset:56320
	global_load_lds_dwordx4 v[176:177], off
	v_lshl_add_u64 v[176:177], v[248:249], 0, s[18:19]
	s_mov_b32 m0, s83
	s_nop 0
	global_load_lds_dwordx4 v[176:177], off
	s_waitcnt lgkmcnt(0)
	s_waitcnt vmcnt(8)
	s_barrier
	v_mfma_f32_16x16x32_bf16 v[60:63], v[128:131], v[162:165], v[60:63]
	v_mfma_f32_16x16x32_bf16 v[56:59], v[136:139], v[162:165], v[56:59]
	v_mfma_f32_16x16x32_bf16 v[52:55], v[128:131], v[196:199], v[52:55]
	v_mfma_f32_16x16x32_bf16 v[48:51], v[136:139], v[196:199], v[48:51]
	v_mfma_f32_16x16x32_bf16 v[44:47], v[128:131], v[204:207], v[44:47]
	v_mfma_f32_16x16x32_bf16 v[40:43], v[136:139], v[204:207], v[40:43]
	v_mfma_f32_16x16x32_bf16 v[36:39], v[128:131], v[220:223], v[36:39]
	v_mfma_f32_16x16x32_bf16 v[32:35], v[136:139], v[220:223], v[32:35]
	v_mfma_f32_16x16x32_bf16 v[60:63], v[132:135], v[166:169], v[60:63]
	v_mfma_f32_16x16x32_bf16 v[56:59], v[140:143], v[166:169], v[56:59]
	v_mfma_f32_16x16x32_bf16 v[52:55], v[132:135], v[200:203], v[52:55]
	v_mfma_f32_16x16x32_bf16 v[48:51], v[140:143], v[200:203], v[48:51]
	v_mfma_f32_16x16x32_bf16 v[44:47], v[132:135], v[216:219], v[44:47]
	v_mfma_f32_16x16x32_bf16 v[40:43], v[140:143], v[216:219], v[40:43]
	v_mfma_f32_16x16x32_bf16 v[36:39], v[132:135], v[228:231], v[36:39]
	v_mfma_f32_16x16x32_bf16 v[32:35], v[140:143], v[228:231], v[32:35]
	s_add_u32 s50, s50, 0x40080
	s_addc_u32 s51, s51, 0
	s_add_i32 s27, s37, s76
	s_mov_b32 m0, s27
	s_nop 0
	global_load_lds_dwordx4 v148, s[50:51]
	s_add_i32 m0, s27, 0x2000
	s_nop 0
	global_load_lds_dwordx4 v152, s[50:51]
	s_waitcnt vmcnt(6)
	v_mfma_f32_16x16x32_bf16 v[28:31], v[232:235], v[162:165], v[28:31]
	v_mfma_f32_16x16x32_bf16 v[24:27], v[240:243], v[162:165], v[24:27]
	v_mfma_f32_16x16x32_bf16 v[20:23], v[232:235], v[196:199], v[20:23]
	v_mfma_f32_16x16x32_bf16 v[16:19], v[240:243], v[196:199], v[16:19]
	v_mfma_f32_16x16x32_bf16 v[12:15], v[232:235], v[204:207], v[12:15]
	v_mfma_f32_16x16x32_bf16 v[8:11], v[240:243], v[204:207], v[8:11]
	v_mfma_f32_16x16x32_bf16 v[4:7], v[232:235], v[220:223], v[4:7]
	v_mfma_f32_16x16x32_bf16 v[0:3], v[240:243], v[220:223], v[0:3]
	v_mfma_f32_16x16x32_bf16 v[28:31], v[236:239], v[166:169], v[28:31]
	v_mfma_f32_16x16x32_bf16 v[24:27], v[244:247], v[166:169], v[24:27]
	v_mfma_f32_16x16x32_bf16 v[20:23], v[236:239], v[200:203], v[20:23]
	v_mfma_f32_16x16x32_bf16 v[16:19], v[244:247], v[200:203], v[16:19]
	v_mfma_f32_16x16x32_bf16 v[12:15], v[236:239], v[216:219], v[12:15]
	v_mfma_f32_16x16x32_bf16 v[8:11], v[244:247], v[216:219], v[8:11]
	v_mfma_f32_16x16x32_bf16 v[4:7], v[236:239], v[228:231], v[4:7]
	v_mfma_f32_16x16x32_bf16 v[0:3], v[244:247], v[228:231], v[0:3]
	s_barrier
	s_add_i32 s36, s36, 2
	s_add_u32 s0, s0, 0x100
	s_addc_u32 s1, s1, 0
	s_add_u32 s34, s34, 0x100
	s_addc_u32 s35, s35, 0
	s_cmp_gt_u32 s36, 13
.LBB0_351:
	s_nop 0
	s_add_u32 s27, s0, 0xfffc0080
	s_addc_u32 s37, s1, -1
	s_add_i32 s47, 0, 0x10000
	ds_read_b128 v[128:131], v192
	ds_read_b128 v[132:135], v192 offset:1024
	ds_read_b128 v[136:139], v192 offset:2048
	ds_read_b128 v[140:143], v192 offset:3072
	s_cmp_eq_u32 s36, 12
	s_cselect_b32 s53, s25, s37
	s_cselect_b32 s52, s30, s27
	s_cselect_b32 s51, s31, s35
	s_cselect_b32 s50, s33, s34
	s_add_i32 m0, s77, 0xc000
	ds_read_b128 v[162:165], v194
	ds_read_b128 v[166:169], v194 offset:1024
	ds_read_b128 v[196:199], v194 offset:2048
	ds_read_b128 v[200:203], v194 offset:3072
	ds_read_b128 v[204:207], v194 offset:4096
	ds_read_b128 v[216:219], v194 offset:5120
	ds_read_b128 v[220:223], v194 offset:6144
	ds_read_b128 v[228:231], v194 offset:7168
	global_load_lds_dwordx4 v156, s[0:1]
	s_add_i32 m0, s77, 0xe000
	s_nop 0
	global_load_lds_dwordx4 v158, s[0:1]
	s_waitcnt lgkmcnt(0)
	s_barrier
	v_mfma_f32_16x16x32_bf16 v[124:127], v[128:131], v[162:165], v[124:127]
	v_mfma_f32_16x16x32_bf16 v[120:123], v[136:139], v[162:165], v[120:123]
	v_mfma_f32_16x16x32_bf16 v[116:119], v[128:131], v[196:199], v[116:119]
	v_mfma_f32_16x16x32_bf16 v[112:115], v[136:139], v[196:199], v[112:115]
	v_mfma_f32_16x16x32_bf16 v[108:111], v[128:131], v[204:207], v[108:111]
	v_mfma_f32_16x16x32_bf16 v[104:107], v[136:139], v[204:207], v[104:107]
	v_mfma_f32_16x16x32_bf16 v[100:103], v[128:131], v[220:223], v[100:103]
	v_mfma_f32_16x16x32_bf16 v[96:99], v[136:139], v[220:223], v[96:99]
	v_mfma_f32_16x16x32_bf16 v[124:127], v[132:135], v[166:169], v[124:127]
	v_mfma_f32_16x16x32_bf16 v[120:123], v[140:143], v[166:169], v[120:123]
	v_mfma_f32_16x16x32_bf16 v[116:119], v[132:135], v[200:203], v[116:119]
	v_mfma_f32_16x16x32_bf16 v[112:115], v[140:143], v[200:203], v[112:115]
	v_mfma_f32_16x16x32_bf16 v[108:111], v[132:135], v[216:219], v[108:111]
	v_mfma_f32_16x16x32_bf16 v[104:107], v[140:143], v[216:219], v[104:107]
	v_mfma_f32_16x16x32_bf16 v[100:103], v[132:135], v[228:231], v[100:103]
	v_mfma_f32_16x16x32_bf16 v[96:99], v[140:143], v[228:231], v[96:99]
	s_barrier
	s_add_i32 s27, 0, 0x14000
	s_add_i32 s37, s47, s76
	s_mov_b32 m0, s37
	ds_read_b128 v[232:235], v192 offset:16384
	ds_read_b128 v[236:239], v192 offset:17408
	ds_read_b128 v[240:243], v192 offset:18432
	ds_read_b128 v[244:247], v192 offset:19456
	global_load_lds_dwordx4 v148, s[50:51]
	s_add_i32 m0, s37, 0x2000
	s_nop 0
	global_load_lds_dwordx4 v152, s[50:51]
	s_waitcnt lgkmcnt(0)
	s_barrier
	v_mfma_f32_16x16x32_bf16 v[92:95], v[232:235], v[162:165], v[92:95]
	v_mfma_f32_16x16x32_bf16 v[88:91], v[240:243], v[162:165], v[88:91]
	v_mfma_f32_16x16x32_bf16 v[84:87], v[232:235], v[196:199], v[84:87]
	v_mfma_f32_16x16x32_bf16 v[80:83], v[240:243], v[196:199], v[80:83]
	v_mfma_f32_16x16x32_bf16 v[76:79], v[232:235], v[204:207], v[76:79]
	v_mfma_f32_16x16x32_bf16 v[72:75], v[240:243], v[204:207], v[72:75]
	v_mfma_f32_16x16x32_bf16 v[68:71], v[232:235], v[220:223], v[68:71]
	v_mfma_f32_16x16x32_bf16 v[64:67], v[240:243], v[220:223], v[64:67]
	v_mfma_f32_16x16x32_bf16 v[92:95], v[236:239], v[166:169], v[92:95]
	v_mfma_f32_16x16x32_bf16 v[88:91], v[244:247], v[166:169], v[88:91]
	v_mfma_f32_16x16x32_bf16 v[84:87], v[236:239], v[200:203], v[84:87]
	v_mfma_f32_16x16x32_bf16 v[80:83], v[244:247], v[200:203], v[80:83]
	v_mfma_f32_16x16x32_bf16 v[76:79], v[236:239], v[216:219], v[76:79]
	v_mfma_f32_16x16x32_bf16 v[72:75], v[244:247], v[216:219], v[72:75]
	v_mfma_f32_16x16x32_bf16 v[68:71], v[236:239], v[228:231], v[68:71]
	v_mfma_f32_16x16x32_bf16 v[64:67], v[244:247], v[228:231], v[64:67]
	s_barrier
	s_mov_b32 m0, s77
	v_lshl_add_u64 v[224:225], s[52:53], 0, v[146:147]
	ds_read_b128 v[162:165], v194 offset:16384
	ds_read_b128 v[166:169], v194 offset:17408
	ds_read_b128 v[196:199], v194 offset:18432
	ds_read_b128 v[200:203], v194 offset:19456
	ds_read_b128 v[204:207], v194 offset:20480
	ds_read_b128 v[216:219], v194 offset:21504
	ds_read_b128 v[220:223], v194 offset:22528
	ds_read_b128 v[228:231], v194 offset:23552
	global_load_lds_dwordx4 v[224:225], off
	v_lshl_add_u64 v[248:249], s[52:53], 0, v[150:151]
	s_mov_b32 m0, s78
	s_nop 0
	global_load_lds_dwordx4 v[248:249], off
	s_waitcnt lgkmcnt(0)
	s_waitcnt vmcnt(8)
	s_barrier
	v_mfma_f32_16x16x32_bf16 v[60:63], v[128:131], v[162:165], v[60:63]
	v_mfma_f32_16x16x32_bf16 v[56:59], v[136:139], v[162:165], v[56:59]
	v_mfma_f32_16x16x32_bf16 v[52:55], v[128:131], v[196:199], v[52:55]
	v_mfma_f32_16x16x32_bf16 v[48:51], v[136:139], v[196:199], v[48:51]
	v_mfma_f32_16x16x32_bf16 v[44:47], v[128:131], v[204:207], v[44:47]
	v_mfma_f32_16x16x32_bf16 v[40:43], v[136:139], v[204:207], v[40:43]
	v_mfma_f32_16x16x32_bf16 v[36:39], v[128:131], v[220:223], v[36:39]
	v_mfma_f32_16x16x32_bf16 v[32:35], v[136:139], v[220:223], v[32:35]
	v_mfma_f32_16x16x32_bf16 v[60:63], v[132:135], v[166:169], v[60:63]
	v_mfma_f32_16x16x32_bf16 v[56:59], v[140:143], v[166:169], v[56:59]
	v_mfma_f32_16x16x32_bf16 v[52:55], v[132:135], v[200:203], v[52:55]
	v_mfma_f32_16x16x32_bf16 v[48:51], v[140:143], v[200:203], v[48:51]
	v_mfma_f32_16x16x32_bf16 v[44:47], v[132:135], v[216:219], v[44:47]
	v_mfma_f32_16x16x32_bf16 v[40:43], v[140:143], v[216:219], v[40:43]
	v_mfma_f32_16x16x32_bf16 v[36:39], v[132:135], v[228:231], v[36:39]
	v_mfma_f32_16x16x32_bf16 v[32:35], v[140:143], v[228:231], v[32:35]
	s_add_u32 s56, s50, 0x40000
	s_addc_u32 s57, s51, 0
	s_add_i32 s27, s27, s76
	s_mov_b32 m0, s27
	s_nop 0
	global_load_lds_dwordx4 v148, s[56:57]
	s_add_i32 m0, s27, 0x2000
	s_nop 0
	global_load_lds_dwordx4 v152, s[56:57]
	s_waitcnt vmcnt(6)
	v_mfma_f32_16x16x32_bf16 v[28:31], v[232:235], v[162:165], v[28:31]
	v_mfma_f32_16x16x32_bf16 v[24:27], v[240:243], v[162:165], v[24:27]
	v_mfma_f32_16x16x32_bf16 v[20:23], v[232:235], v[196:199], v[20:23]
	v_mfma_f32_16x16x32_bf16 v[16:19], v[240:243], v[196:199], v[16:19]
	v_mfma_f32_16x16x32_bf16 v[12:15], v[232:235], v[204:207], v[12:15]
	v_mfma_f32_16x16x32_bf16 v[8:11], v[240:243], v[204:207], v[8:11]
	v_mfma_f32_16x16x32_bf16 v[4:7], v[232:235], v[220:223], v[4:7]
	v_mfma_f32_16x16x32_bf16 v[0:3], v[240:243], v[220:223], v[0:3]
	v_mfma_f32_16x16x32_bf16 v[28:31], v[236:239], v[166:169], v[28:31]
	v_mfma_f32_16x16x32_bf16 v[24:27], v[244:247], v[166:169], v[24:27]
	v_mfma_f32_16x16x32_bf16 v[20:23], v[236:239], v[200:203], v[20:23]
	v_mfma_f32_16x16x32_bf16 v[16:19], v[244:247], v[200:203], v[16:19]
	v_mfma_f32_16x16x32_bf16 v[12:15], v[236:239], v[216:219], v[12:15]
	v_mfma_f32_16x16x32_bf16 v[8:11], v[244:247], v[216:219], v[8:11]
	v_mfma_f32_16x16x32_bf16 v[4:7], v[236:239], v[228:231], v[4:7]
	v_mfma_f32_16x16x32_bf16 v[0:3], v[244:247], v[228:231], v[0:3]
	s_barrier
	s_add_i32 s27, 0, 0x18000
	ds_read_b128 v[128:131], v192 offset:32768
	ds_read_b128 v[132:135], v192 offset:33792
	ds_read_b128 v[136:139], v192 offset:34816
	ds_read_b128 v[140:143], v192 offset:35840
	s_add_u32 s52, s52, 0x40000
	s_addc_u32 s53, s53, 0
	s_mov_b32 m0, s81
	ds_read_b128 v[162:165], v194 offset:32768
	ds_read_b128 v[166:169], v194 offset:33792
	ds_read_b128 v[196:199], v194 offset:34816
	ds_read_b128 v[200:203], v194 offset:35840
	ds_read_b128 v[204:207], v194 offset:36864
	ds_read_b128 v[216:219], v194 offset:37888
	ds_read_b128 v[220:223], v194 offset:38912
	ds_read_b128 v[228:231], v194 offset:39936
	global_load_lds_dwordx4 v146, s[52:53]
	s_mov_b32 m0, s82
	s_nop 0
	global_load_lds_dwordx4 v150, s[52:53]
	s_waitcnt lgkmcnt(0)
	s_barrier
	v_mfma_f32_16x16x32_bf16 v[124:127], v[128:131], v[162:165], v[124:127]
	v_mfma_f32_16x16x32_bf16 v[120:123], v[136:139], v[162:165], v[120:123]
	v_mfma_f32_16x16x32_bf16 v[116:119], v[128:131], v[196:199], v[116:119]
	v_mfma_f32_16x16x32_bf16 v[112:115], v[136:139], v[196:199], v[112:115]
	v_mfma_f32_16x16x32_bf16 v[108:111], v[128:131], v[204:207], v[108:111]
	v_mfma_f32_16x16x32_bf16 v[104:107], v[136:139], v[204:207], v[104:107]
	v_mfma_f32_16x16x32_bf16 v[100:103], v[128:131], v[220:223], v[100:103]
	v_mfma_f32_16x16x32_bf16 v[96:99], v[136:139], v[220:223], v[96:99]
	v_mfma_f32_16x16x32_bf16 v[124:127], v[132:135], v[166:169], v[124:127]
	v_mfma_f32_16x16x32_bf16 v[120:123], v[140:143], v[166:169], v[120:123]
	v_mfma_f32_16x16x32_bf16 v[116:119], v[132:135], v[200:203], v[116:119]
	v_mfma_f32_16x16x32_bf16 v[112:115], v[140:143], v[200:203], v[112:115]
	v_mfma_f32_16x16x32_bf16 v[108:111], v[132:135], v[216:219], v[108:111]
	v_mfma_f32_16x16x32_bf16 v[104:107], v[140:143], v[216:219], v[104:107]
	v_mfma_f32_16x16x32_bf16 v[100:103], v[132:135], v[228:231], v[100:103]
	v_mfma_f32_16x16x32_bf16 v[96:99], v[140:143], v[228:231], v[96:99]
	s_barrier
	s_add_i32 s37, 0, 0x1c000
	s_add_i32 s27, s27, s76
	s_add_u32 s56, s50, s18
	s_addc_u32 s57, s51, s19
	s_mov_b32 m0, s27
	ds_read_b128 v[232:235], v192 offset:49152
	ds_read_b128 v[236:239], v192 offset:50176
	ds_read_b128 v[240:243], v192 offset:51200
	ds_read_b128 v[244:247], v192 offset:52224
	global_load_lds_dwordx4 v148, s[56:57]
	s_add_u32 s56, s50, s18
	s_addc_u32 s57, s51, s19
	s_add_i32 m0, s27, 0x2000
	s_nop 0
	global_load_lds_dwordx4 v152, s[56:57]
	s_waitcnt lgkmcnt(0)
	s_barrier
	v_mfma_f32_16x16x32_bf16 v[92:95], v[232:235], v[162:165], v[92:95]
	v_mfma_f32_16x16x32_bf16 v[88:91], v[240:243], v[162:165], v[88:91]
	v_mfma_f32_16x16x32_bf16 v[84:87], v[232:235], v[196:199], v[84:87]
	v_mfma_f32_16x16x32_bf16 v[80:83], v[240:243], v[196:199], v[80:83]
	v_mfma_f32_16x16x32_bf16 v[76:79], v[232:235], v[204:207], v[76:79]
	v_mfma_f32_16x16x32_bf16 v[72:75], v[240:243], v[204:207], v[72:75]
	v_mfma_f32_16x16x32_bf16 v[68:71], v[232:235], v[220:223], v[68:71]
	v_mfma_f32_16x16x32_bf16 v[64:67], v[240:243], v[220:223], v[64:67]
	v_mfma_f32_16x16x32_bf16 v[92:95], v[236:239], v[166:169], v[92:95]
	v_mfma_f32_16x16x32_bf16 v[88:91], v[244:247], v[166:169], v[88:91]
	v_mfma_f32_16x16x32_bf16 v[84:87], v[236:239], v[200:203], v[84:87]
	v_mfma_f32_16x16x32_bf16 v[80:83], v[244:247], v[200:203], v[80:83]
	v_mfma_f32_16x16x32_bf16 v[76:79], v[236:239], v[216:219], v[76:79]
	v_mfma_f32_16x16x32_bf16 v[72:75], v[244:247], v[216:219], v[72:75]
	v_mfma_f32_16x16x32_bf16 v[68:71], v[236:239], v[228:231], v[68:71]
	v_mfma_f32_16x16x32_bf16 v[64:67], v[244:247], v[228:231], v[64:67]
	s_barrier
	s_mov_b32 m0, s80
	v_lshl_add_u64 v[176:177], v[224:225], 0, s[18:19]
	ds_read_b128 v[162:165], v194 offset:49152
	ds_read_b128 v[166:169], v194 offset:50176
	ds_read_b128 v[196:199], v194 offset:51200
	ds_read_b128 v[200:203], v194 offset:52224
	ds_read_b128 v[204:207], v194 offset:53248
	ds_read_b128 v[216:219], v194 offset:54272
	ds_read_b128 v[220:223], v194 offset:55296
	ds_read_b128 v[228:231], v194 offset:56320
	global_load_lds_dwordx4 v[176:177], off
	v_lshl_add_u64 v[176:177], v[248:249], 0, s[18:19]
	s_mov_b32 m0, s83
	s_nop 0
	global_load_lds_dwordx4 v[176:177], off
	s_waitcnt lgkmcnt(0)
	s_waitcnt vmcnt(8)
	s_barrier
	v_mfma_f32_16x16x32_bf16 v[60:63], v[128:131], v[162:165], v[60:63]
	v_mfma_f32_16x16x32_bf16 v[56:59], v[136:139], v[162:165], v[56:59]
	v_mfma_f32_16x16x32_bf16 v[52:55], v[128:131], v[196:199], v[52:55]
	v_mfma_f32_16x16x32_bf16 v[48:51], v[136:139], v[196:199], v[48:51]
	v_mfma_f32_16x16x32_bf16 v[44:47], v[128:131], v[204:207], v[44:47]
	v_mfma_f32_16x16x32_bf16 v[40:43], v[136:139], v[204:207], v[40:43]
	v_mfma_f32_16x16x32_bf16 v[36:39], v[128:131], v[220:223], v[36:39]
	v_mfma_f32_16x16x32_bf16 v[32:35], v[136:139], v[220:223], v[32:35]
	v_mfma_f32_16x16x32_bf16 v[60:63], v[132:135], v[166:169], v[60:63]
	v_mfma_f32_16x16x32_bf16 v[56:59], v[140:143], v[166:169], v[56:59]
	v_mfma_f32_16x16x32_bf16 v[52:55], v[132:135], v[200:203], v[52:55]
	v_mfma_f32_16x16x32_bf16 v[48:51], v[140:143], v[200:203], v[48:51]
	v_mfma_f32_16x16x32_bf16 v[44:47], v[132:135], v[216:219], v[44:47]
	v_mfma_f32_16x16x32_bf16 v[40:43], v[140:143], v[216:219], v[40:43]
	v_mfma_f32_16x16x32_bf16 v[36:39], v[132:135], v[228:231], v[36:39]
	v_mfma_f32_16x16x32_bf16 v[32:35], v[140:143], v[228:231], v[32:35]
	s_add_u32 s50, s50, 0x40080
	s_addc_u32 s51, s51, 0
	s_add_i32 s27, s37, s76
	s_mov_b32 m0, s27
	s_nop 0
	global_load_lds_dwordx4 v148, s[50:51]
	s_add_i32 m0, s27, 0x2000
	s_nop 0
	global_load_lds_dwordx4 v152, s[50:51]
	s_waitcnt vmcnt(6)
	v_mfma_f32_16x16x32_bf16 v[28:31], v[232:235], v[162:165], v[28:31]
	v_mfma_f32_16x16x32_bf16 v[24:27], v[240:243], v[162:165], v[24:27]
	v_mfma_f32_16x16x32_bf16 v[20:23], v[232:235], v[196:199], v[20:23]
	v_mfma_f32_16x16x32_bf16 v[16:19], v[240:243], v[196:199], v[16:19]
	v_mfma_f32_16x16x32_bf16 v[12:15], v[232:235], v[204:207], v[12:15]
	v_mfma_f32_16x16x32_bf16 v[8:11], v[240:243], v[204:207], v[8:11]
	v_mfma_f32_16x16x32_bf16 v[4:7], v[232:235], v[220:223], v[4:7]
	v_mfma_f32_16x16x32_bf16 v[0:3], v[240:243], v[220:223], v[0:3]
	v_mfma_f32_16x16x32_bf16 v[28:31], v[236:239], v[166:169], v[28:31]
	v_mfma_f32_16x16x32_bf16 v[24:27], v[244:247], v[166:169], v[24:27]
	v_mfma_f32_16x16x32_bf16 v[20:23], v[236:239], v[200:203], v[20:23]
	v_mfma_f32_16x16x32_bf16 v[16:19], v[244:247], v[200:203], v[16:19]
	v_mfma_f32_16x16x32_bf16 v[12:15], v[236:239], v[216:219], v[12:15]
	v_mfma_f32_16x16x32_bf16 v[8:11], v[244:247], v[216:219], v[8:11]
	v_mfma_f32_16x16x32_bf16 v[4:7], v[236:239], v[228:231], v[4:7]
	v_mfma_f32_16x16x32_bf16 v[0:3], v[244:247], v[228:231], v[0:3]
	s_barrier
	s_add_i32 s36, s36, 2
	s_add_u32 s0, s0, 0x100
	s_addc_u32 s1, s1, 0
	s_add_u32 s34, s34, 0x100
	s_addc_u32 s35, s35, 0
	s_cmp_gt_u32 s36, 13
	s_cbranch_scc0 .LBB0_351
	s_lshl_b32 s0, s11, 8
	s_or_b32 s50, s0, s79
	s_ashr_i32 s51, s50, 31
	v_lshl_add_u64 v[140:141], s[50:51], 3, v[154:155]
	global_load_dwordx4 v[128:131], v[140:141], off offset:48
	global_load_dwordx4 v[132:135], v[140:141], off offset:32
	global_load_dwordx4 v[136:139], v[140:141], off offset:16
	global_load_dwordx4 v[162:165], v[140:141], off
	s_mov_b32 s34, 0x35800000
	s_mov_b32 s0, 0x358637bd
	v_mov_b64_e32 v[168:169], s[0:1]
	s_mov_b32 s30, 0x45800000
	s_cmp_lt_u32 s10, 2
	s_waitcnt vmcnt(0)
	v_ffbh_u32_e32 v142, v165
	v_min_u32_e32 v161, 32, v142
	v_lshlrev_b64 v[142:143], v161, v[164:165]
	v_min_u32_e32 v142, 1, v142
	v_or_b32_e32 v142, v143, v142
	v_cvt_f32_u32_e32 v142, v142
	v_sub_u32_e32 v143, 32, v161
	v_ldexp_f32 v143, v142, v143
	v_ffbh_u32_e32 v142, v163
	v_min_u32_e32 v142, 32, v142
	v_lshlrev_b64 v[162:163], v142, v[162:163]
	v_min_u32_e32 v161, 1, v162
	v_or_b32_e32 v161, v163, v161
	v_cvt_f32_u32_e32 v161, v161
	v_sub_u32_e32 v142, 32, v142
	v_ldexp_f32 v142, v161, v142
	v_pk_mul_f32 v[142:143], v[142:143], s[34:35] op_sel_hi:[1,0]
	s_nop 0
	v_pk_fma_f32 v[142:143], v[142:143], s[2:3], v[168:169] op_sel_hi:[1,0,0]
	s_nop 0
	v_mul_f32_e32 v161, 0x4b800000, v142
	v_cmp_gt_f32_e64 s[0:1], s89, v142
	v_cmp_gt_f32_e32 vcc, s89, v143
	s_nop 0
	v_cndmask_b32_e64 v142, v142, v161, s[0:1]
	v_mul_f32_e32 v161, 0x4b800000, v143
	v_cndmask_b32_e32 v143, v143, v161, vcc
	v_rsq_f32_e32 v142, v142
	v_rsq_f32_e32 v143, v143
	s_nop 0
	v_pk_mul_f32 v[162:163], v[142:143], s[30:31] op_sel_hi:[1,0]
	s_nop 0
	v_cndmask_b32_e64 v166, v142, v162, s[0:1]
	v_ffbh_u32_e32 v142, v139
	v_min_u32_e32 v142, 32, v142
	v_lshlrev_b64 v[138:139], v142, v[138:139]
	v_min_u32_e32 v138, 1, v138
	v_or_b32_e32 v138, v139, v138
	v_cvt_f32_u32_e32 v138, v138
	v_sub_u32_e32 v139, 32, v142
	v_cndmask_b32_e32 v167, v143, v163, vcc
	v_pk_mul_f32 v[60:61], v[60:61], v[166:167]
	v_ldexp_f32 v139, v138, v139
	v_ffbh_u32_e32 v138, v137
	v_min_u32_e32 v138, 32, v138
	v_lshlrev_b64 v[136:137], v138, v[136:137]
	v_min_u32_e32 v136, 1, v136
	v_or_b32_e32 v136, v137, v136
	v_cvt_f32_u32_e32 v136, v136
	v_sub_u32_e32 v137, 32, v138
	v_pk_mul_f32 v[52:53], v[52:53], v[166:167]
	v_pk_mul_f32 v[44:45], v[44:45], v[166:167]
	v_ldexp_f32 v138, v136, v137
	v_pk_mul_f32 v[136:137], v[138:139], s[34:35] op_sel_hi:[1,0]
	v_pk_mul_f32 v[36:37], v[36:37], v[166:167]
	v_pk_fma_f32 v[136:137], v[136:137], s[2:3], v[168:169] op_sel_hi:[1,0,0]
	s_nop 0
	v_mul_f32_e32 v138, 0x4b800000, v136
	v_cmp_gt_f32_e64 s[0:1], s89, v136
	v_cmp_gt_f32_e32 vcc, s89, v137
	s_nop 0
	v_cndmask_b32_e64 v136, v136, v138, s[0:1]
	v_mul_f32_e32 v138, 0x4b800000, v137
	v_cndmask_b32_e32 v137, v137, v138, vcc
	v_rsq_f32_e32 v136, v136
	v_rsq_f32_e32 v137, v137
	s_nop 0
	v_pk_mul_f32 v[138:139], v[136:137], s[30:31] op_sel_hi:[1,0]
	s_nop 0
	v_cndmask_b32_e64 v162, v136, v138, s[0:1]
	v_ffbh_u32_e32 v136, v135
	v_min_u32_e32 v136, 32, v136
	v_lshlrev_b64 v[134:135], v136, v[134:135]
	v_min_u32_e32 v134, 1, v134
	v_or_b32_e32 v134, v135, v134
	v_cvt_f32_u32_e32 v134, v134
	v_sub_u32_e32 v135, 32, v136
	v_cndmask_b32_e32 v163, v137, v139, vcc
	v_ldexp_f32 v135, v134, v135
	v_ffbh_u32_e32 v134, v133
	v_min_u32_e32 v134, 32, v134
	v_lshlrev_b64 v[132:133], v134, v[132:133]
	v_min_u32_e32 v132, 1, v132
	v_or_b32_e32 v132, v133, v132
	v_cvt_f32_u32_e32 v132, v132
	v_sub_u32_e32 v133, 32, v134
	v_ldexp_f32 v134, v132, v133
	v_pk_mul_f32 v[132:133], v[134:135], s[34:35] op_sel_hi:[1,0]
	s_nop 0
	v_pk_fma_f32 v[132:133], v[132:133], s[2:3], v[168:169] op_sel_hi:[1,0,0]
	s_nop 0
	v_mul_f32_e32 v134, 0x4b800000, v132
	v_cmp_gt_f32_e64 s[0:1], s89, v132
	v_cmp_gt_f32_e32 vcc, s89, v133
	s_nop 0
	v_cndmask_b32_e64 v132, v132, v134, s[0:1]
	v_mul_f32_e32 v134, 0x4b800000, v133
	v_cndmask_b32_e32 v133, v133, v134, vcc
	v_rsq_f32_e32 v132, v132
	v_rsq_f32_e32 v133, v133
	s_nop 0
	v_pk_mul_f32 v[134:135], v[132:133], s[30:31] op_sel_hi:[1,0]
	s_nop 0
	v_cndmask_b32_e64 v188, v132, v134, s[0:1]
	v_ffbh_u32_e32 v132, v131
	v_min_u32_e32 v132, 32, v132
	v_lshlrev_b64 v[130:131], v132, v[130:131]
	v_min_u32_e32 v130, 1, v130
	v_or_b32_e32 v130, v131, v130
	v_cvt_f32_u32_e32 v130, v130
	v_sub_u32_e32 v131, 32, v132
	v_cndmask_b32_e32 v189, v133, v135, vcc
	v_pk_mul_f32 v[56:57], v[56:57], v[188:189]
	v_ldexp_f32 v131, v130, v131
	v_ffbh_u32_e32 v130, v129
	v_min_u32_e32 v130, 32, v130
	v_lshlrev_b64 v[128:129], v130, v[128:129]
	v_min_u32_e32 v128, 1, v128
	v_or_b32_e32 v128, v129, v128
	v_cvt_f32_u32_e32 v128, v128
	v_sub_u32_e32 v129, 32, v130
	v_pk_mul_f32 v[48:49], v[48:49], v[188:189]
	v_pk_mul_f32 v[40:41], v[40:41], v[188:189]
	v_ldexp_f32 v130, v128, v129
	v_pk_mul_f32 v[128:129], v[130:131], s[34:35] op_sel_hi:[1,0]
	v_pk_mul_f32 v[32:33], v[32:33], v[188:189]
	v_pk_fma_f32 v[128:129], v[128:129], s[2:3], v[168:169] op_sel_hi:[1,0,0]
	s_nop 0
	v_mul_f32_e32 v130, 0x4b800000, v128
	v_cmp_gt_f32_e64 s[0:1], s89, v128
	v_cmp_gt_f32_e32 vcc, s89, v129
	s_nop 0
	v_cndmask_b32_e64 v128, v128, v130, s[0:1]
	v_mul_f32_e32 v130, 0x4b800000, v129
	v_cndmask_b32_e32 v129, v129, v130, vcc
	v_rsq_f32_e32 v128, v128
	v_rsq_f32_e32 v129, v129
	s_nop 0
	v_pk_mul_f32 v[130:131], v[128:129], s[30:31] op_sel_hi:[1,0]
	s_nop 0
	v_cndmask_b32_e32 v165, v129, v131, vcc
	v_cndmask_b32_e64 v164, v128, v130, s[0:1]
	global_load_dwordx4 v[128:131], v[140:141], off offset:1072
	global_load_dwordx4 v[132:135], v[140:141], off offset:1056
	global_load_dwordx4 v[136:139], v[140:141], off offset:1040
	s_nop 0
	global_load_dwordx4 v[140:143], v[140:141], off offset:1024
	s_waitcnt vmcnt(0)
	v_ffbh_u32_e32 v161, v143
	v_min_u32_e32 v161, 32, v161
	v_lshlrev_b64 v[142:143], v161, v[142:143]
	v_min_u32_e32 v142, 1, v142
	v_or_b32_e32 v142, v143, v142
	v_cvt_f32_u32_e32 v142, v142
	v_sub_u32_e32 v143, 32, v161
	v_ldexp_f32 v143, v142, v143
	v_ffbh_u32_e32 v142, v141
	v_min_u32_e32 v142, 32, v142
	v_lshlrev_b64 v[140:141], v142, v[140:141]
	v_min_u32_e32 v140, 1, v140
	v_or_b32_e32 v140, v141, v140
	v_cvt_f32_u32_e32 v140, v140
	v_sub_u32_e32 v141, 32, v142
	v_ldexp_f32 v142, v140, v141
	v_pk_mul_f32 v[140:141], v[142:143], s[34:35] op_sel_hi:[1,0]
	s_nop 0
	v_pk_fma_f32 v[140:141], v[140:141], s[2:3], v[168:169] op_sel_hi:[1,0,0]
	s_nop 0
	v_mul_f32_e32 v142, 0x4b800000, v140
	v_cmp_gt_f32_e64 s[0:1], s89, v140
	v_cmp_gt_f32_e32 vcc, s89, v141
	s_nop 0
	v_cndmask_b32_e64 v140, v140, v142, s[0:1]
	v_mul_f32_e32 v142, 0x4b800000, v141
	v_cndmask_b32_e32 v141, v141, v142, vcc
	v_rsq_f32_e32 v140, v140
	v_rsq_f32_e32 v141, v141
	s_nop 0
	v_pk_mul_f32 v[142:143], v[140:141], s[30:31] op_sel_hi:[1,0]
	s_nop 0
	v_cndmask_b32_e64 v142, v140, v142, s[0:1]
	v_ffbh_u32_e32 v140, v139
	v_min_u32_e32 v140, 32, v140
	v_lshlrev_b64 v[138:139], v140, v[138:139]
	v_min_u32_e32 v138, 1, v138
	v_or_b32_e32 v138, v139, v138
	v_cvt_f32_u32_e32 v138, v138
	v_sub_u32_e32 v139, 32, v140
	v_cndmask_b32_e32 v143, v141, v143, vcc
	v_pk_mul_f32 v[140:141], v[124:125], v[166:167]
	v_ldexp_f32 v139, v138, v139
	v_ffbh_u32_e32 v138, v137
	v_min_u32_e32 v138, 32, v138
	v_lshlrev_b64 v[136:137], v138, v[136:137]
	v_min_u32_e32 v136, 1, v136
	v_or_b32_e32 v136, v137, v136
	v_cvt_f32_u32_e32 v136, v136
	v_sub_u32_e32 v137, 32, v138
	v_pk_mul_f32 v[28:29], v[28:29], v[142:143]
	v_pk_mul_f32 v[20:21], v[20:21], v[142:143]
	v_ldexp_f32 v138, v136, v137
	v_pk_mul_f32 v[136:137], v[138:139], s[34:35] op_sel_hi:[1,0]
	v_pk_mul_f32 v[12:13], v[12:13], v[142:143]
	v_pk_fma_f32 v[136:137], v[136:137], s[2:3], v[168:169] op_sel_hi:[1,0,0]
	v_pk_mul_f32 v[4:5], v[4:5], v[142:143]
	v_mul_f32_e32 v138, 0x4b800000, v136
	v_cmp_gt_f32_e64 s[0:1], s89, v136
	v_cmp_gt_f32_e32 vcc, s89, v137
	s_nop 0
	v_cndmask_b32_e64 v136, v136, v138, s[0:1]
	v_mul_f32_e32 v138, 0x4b800000, v137
	v_cndmask_b32_e32 v137, v137, v138, vcc
	v_rsq_f32_e32 v136, v136
	v_rsq_f32_e32 v137, v137
	s_nop 0
	v_pk_mul_f32 v[138:139], v[136:137], s[30:31] op_sel_hi:[1,0]
	s_nop 0
	v_cndmask_b32_e64 v136, v136, v138, s[0:1]
	v_ffbh_u32_e32 v138, v135
	v_min_u32_e32 v138, 32, v138
	v_lshlrev_b64 v[134:135], v138, v[134:135]
	v_min_u32_e32 v134, 1, v134
	v_or_b32_e32 v134, v135, v134
	v_cvt_f32_u32_e32 v134, v134
	v_sub_u32_e32 v135, 32, v138
	v_cndmask_b32_e32 v137, v137, v139, vcc
	v_pk_mul_f32 v[138:139], v[120:121], v[188:189]
	v_ldexp_f32 v135, v134, v135
	v_ffbh_u32_e32 v134, v133
	v_min_u32_e32 v134, 32, v134
	v_lshlrev_b64 v[132:133], v134, v[132:133]
	v_min_u32_e32 v132, 1, v132
	v_or_b32_e32 v132, v133, v132
	v_cvt_f32_u32_e32 v132, v132
	v_sub_u32_e32 v133, 32, v134
	v_pk_mul_f32 v[120:121], v[84:85], v[142:143]
	v_ldexp_f32 v134, v132, v133
	v_pk_mul_f32 v[132:133], v[134:135], s[34:35] op_sel_hi:[1,0]
	s_nop 0
	v_pk_fma_f32 v[132:133], v[132:133], s[2:3], v[168:169] op_sel_hi:[1,0,0]
	s_nop 0
	v_mul_f32_e32 v134, 0x4b800000, v132
	v_cmp_gt_f32_e64 s[0:1], s89, v132
	v_cmp_gt_f32_e32 vcc, s89, v133
	s_nop 0
	v_cndmask_b32_e64 v132, v132, v134, s[0:1]
	v_mul_f32_e32 v134, 0x4b800000, v133
	v_cndmask_b32_e32 v133, v133, v134, vcc
	v_rsq_f32_e32 v132, v132
	v_rsq_f32_e32 v133, v133
	s_nop 0
	v_pk_mul_f32 v[134:135], v[132:133], s[30:31] op_sel_hi:[1,0]
	s_nop 0
	v_cndmask_b32_e64 v176, v132, v134, s[0:1]
	v_ffbh_u32_e32 v132, v131
	v_min_u32_e32 v132, 32, v132
	v_lshlrev_b64 v[130:131], v132, v[130:131]
	v_min_u32_e32 v130, 1, v130
	v_or_b32_e32 v130, v131, v130
	v_cvt_f32_u32_e32 v130, v130
	v_sub_u32_e32 v131, 32, v132
	v_cndmask_b32_e32 v177, v133, v135, vcc
	v_pk_mul_f32 v[124:125], v[88:89], v[176:177]
	v_ldexp_f32 v131, v130, v131
	v_ffbh_u32_e32 v130, v129
	v_min_u32_e32 v130, 32, v130
	v_lshlrev_b64 v[128:129], v130, v[128:129]
	v_min_u32_e32 v128, 1, v128
	v_or_b32_e32 v128, v129, v128
	v_cvt_f32_u32_e32 v128, v128
	v_sub_u32_e32 v129, 32, v130
	v_pk_mul_f32 v[134:135], v[116:117], v[166:167]
	v_pk_mul_f32 v[132:133], v[112:113], v[188:189]
	v_ldexp_f32 v130, v128, v129
	v_pk_mul_f32 v[128:129], v[130:131], s[34:35] op_sel_hi:[1,0]
	v_pk_mul_f32 v[116:117], v[80:81], v[176:177]
	v_pk_fma_f32 v[128:129], v[128:129], s[2:3], v[168:169] op_sel_hi:[1,0,0]
	v_pk_mul_f32 v[88:89], v[104:105], v[188:189]
	v_mul_f32_e32 v130, 0x4b800000, v128
	v_cmp_gt_f32_e64 s[0:1], s89, v128
	v_cmp_gt_f32_e32 vcc, s89, v129
	v_pk_mul_f32 v[112:113], v[76:77], v[142:143]
	v_cndmask_b32_e64 v128, v128, v130, s[0:1]
	v_mul_f32_e32 v130, 0x4b800000, v129
	v_cndmask_b32_e32 v129, v129, v130, vcc
	v_rsq_f32_e32 v128, v128
	v_rsq_f32_e32 v129, v129
	v_pk_mul_f32 v[76:77], v[100:101], v[166:167]
	v_pk_mul_f32 v[104:105], v[68:69], v[142:143]
	v_pk_mul_f32 v[24:25], v[24:25], v[176:177]
	v_pk_mul_f32 v[130:131], v[128:129], s[30:31] op_sel_hi:[1,0]
	v_pk_mul_f32 v[16:17], v[16:17], v[176:177]
	v_cndmask_b32_e32 v129, v129, v131, vcc
	v_cndmask_b32_e64 v128, v128, v130, s[0:1]
	s_mov_b64 s[0:1], -1
	v_pk_mul_f32 v[130:131], v[92:93], v[142:143]
	v_pk_mul_f32 v[92:93], v[108:109], v[166:167]
	v_pk_mul_f32 v[108:109], v[72:73], v[176:177]
	v_pk_mul_f32 v[72:73], v[96:97], v[188:189]
	v_pk_mul_f32 v[96:97], v[64:65], v[176:177]
	v_pk_mul_f32 v[8:9], v[8:9], v[176:177]
	v_pk_mul_f32 v[0:1], v[0:1], v[176:177]
	s_cbranch_scc1 .LBB0_354
	v_lshl_add_u32 v68, s10, 8, v193
	v_ashrrev_i32_e32 v69, 31, v68
	v_pk_mul_f32 v[64:65], v[126:127], v[162:163]
	v_cvt_pk_bf16_f32 v80, v140, v141
	s_lshl_b64 s[0:1], s[50:51], 1
	v_cvt_pk_bf16_f32 v81, v64, v65
	v_lshlrev_b64 v[64:65], 13, v[68:69]
	v_lshl_add_u64 v[64:65], s[44:45], 0, v[64:65]
	v_lshl_add_u64 v[64:65], v[64:65], 0, s[0:1]
	v_lshl_add_u64 v[64:65], v[64:65], 0, v[144:145]
	v_mov_b32_e32 v161, v145
	v_lshl_add_u64 v[64:65], v[64:65], 0, v[160:161]
	global_store_dwordx2 v[64:65], v[80:81], off
	v_pk_mul_f32 v[80:81], v[122:123], v[164:165]
	v_cvt_pk_bf16_f32 v84, v138, v139
	s_nop 0
	v_cvt_pk_bf16_f32 v85, v80, v81
	v_pk_mul_f32 v[80:81], v[94:95], v[136:137]
	global_store_dwordx2 v[64:65], v[84:85], off offset:16
	v_cvt_pk_bf16_f32 v84, v130, v131
	v_cvt_pk_bf16_f32 v85, v80, v81
	v_pk_mul_f32 v[80:81], v[90:91], v[128:129]
	global_store_dwordx2 v[64:65], v[84:85], off offset:256
	v_cvt_pk_bf16_f32 v84, v124, v125
	v_cvt_pk_bf16_f32 v85, v80, v81
	v_or_b32_e32 v80, 16, v68
	v_ashrrev_i32_e32 v81, 31, v80
	v_lshlrev_b64 v[80:81], 13, v[80:81]
	v_lshl_add_u64 v[80:81], s[44:45], 0, v[80:81]
	v_lshl_add_u64 v[80:81], v[80:81], 0, s[0:1]
	v_lshl_add_u64 v[80:81], v[80:81], 0, v[144:145]
	global_store_dwordx2 v[64:65], v[84:85], off offset:272
	v_pk_mul_f32 v[84:85], v[118:119], v[162:163]
	v_cvt_pk_bf16_f32 v100, v134, v135
	v_lshl_add_u64 v[80:81], v[80:81], 0, v[160:161]
	v_cvt_pk_bf16_f32 v101, v84, v85
	global_store_dwordx2 v[80:81], v[100:101], off
	v_pk_mul_f32 v[84:85], v[114:115], v[164:165]
	v_cvt_pk_bf16_f32 v100, v132, v133
	s_nop 0
	v_cvt_pk_bf16_f32 v101, v84, v85
	global_store_dwordx2 v[80:81], v[100:101], off offset:16
	v_pk_mul_f32 v[84:85], v[86:87], v[136:137]
	v_cvt_pk_bf16_f32 v100, v120, v121
	s_nop 0
	v_cvt_pk_bf16_f32 v101, v84, v85
	global_store_dwordx2 v[80:81], v[100:101], off offset:256
	v_pk_mul_f32 v[84:85], v[82:83], v[128:129]
	v_cvt_pk_bf16_f32 v100, v116, v117
	s_nop 0
	v_cvt_pk_bf16_f32 v101, v84, v85
	global_store_dwordx2 v[80:81], v[100:101], off offset:272
	v_or_b32_e32 v80, 32, v68
	v_ashrrev_i32_e32 v81, 31, v80
	v_lshlrev_b64 v[80:81], 13, v[80:81]
	v_lshl_add_u64 v[80:81], s[44:45], 0, v[80:81]
	v_or_b32_e32 v68, 48, v68
	v_lshl_add_u64 v[80:81], v[80:81], 0, s[0:1]
	v_ashrrev_i32_e32 v69, 31, v68
	v_pk_mul_f32 v[84:85], v[110:111], v[162:163]
	v_lshl_add_u64 v[80:81], v[80:81], 0, v[144:145]
	v_lshlrev_b64 v[68:69], 13, v[68:69]
	v_cvt_pk_bf16_f32 v100, v92, v93
	v_cvt_pk_bf16_f32 v101, v84, v85
	v_lshl_add_u64 v[80:81], v[80:81], 0, v[160:161]
	v_pk_mul_f32 v[84:85], v[106:107], v[164:165]
	v_lshl_add_u64 v[68:69], s[44:45], 0, v[68:69]
	global_store_dwordx2 v[80:81], v[100:101], off
	v_cvt_pk_bf16_f32 v100, v88, v89
	v_cvt_pk_bf16_f32 v101, v84, v85
	v_pk_mul_f32 v[84:85], v[78:79], v[136:137]
	v_lshl_add_u64 v[68:69], v[68:69], 0, s[0:1]
	global_store_dwordx2 v[80:81], v[100:101], off offset:16
	v_cvt_pk_bf16_f32 v100, v112, v113
	v_cvt_pk_bf16_f32 v101, v84, v85
	v_pk_mul_f32 v[84:85], v[74:75], v[128:129]
	v_lshl_add_u64 v[68:69], v[68:69], 0, v[144:145]
	global_store_dwordx2 v[80:81], v[100:101], off offset:256
	v_cvt_pk_bf16_f32 v100, v108, v109
	v_cvt_pk_bf16_f32 v101, v84, v85
	global_store_dwordx2 v[80:81], v[100:101], off offset:272
	v_cvt_pk_bf16_f32 v84, v76, v77
	v_lshl_add_u64 v[68:69], v[68:69], 0, v[160:161]
	v_pk_mul_f32 v[80:81], v[102:103], v[162:163]
	s_mov_b64 s[0:1], 0x100000
	v_cvt_pk_bf16_f32 v85, v80, v81
	global_store_dwordx2 v[68:69], v[84:85], off
	v_cvt_pk_bf16_f32 v84, v72, v73
	v_pk_mul_f32 v[80:81], v[98:99], v[164:165]
	s_nop 0
	v_cvt_pk_bf16_f32 v85, v80, v81
	global_store_dwordx2 v[68:69], v[84:85], off offset:16
	v_cvt_pk_bf16_f32 v84, v104, v105
	v_pk_mul_f32 v[80:81], v[70:71], v[136:137]
	s_nop 0
	v_cvt_pk_bf16_f32 v85, v80, v81
	global_store_dwordx2 v[68:69], v[84:85], off offset:256
	v_cvt_pk_bf16_f32 v84, v96, v97
	v_pk_mul_f32 v[80:81], v[66:67], v[128:129]
	s_nop 0
	v_cvt_pk_bf16_f32 v85, v80, v81
	global_store_dwordx2 v[68:69], v[84:85], off offset:272
	v_add_co_u32_e32 v84, vcc, s29, v64
	v_pk_mul_f32 v[68:69], v[62:63], v[162:163]
	s_nop 0
	v_addc_co_u32_e32 v85, vcc, 0, v65, vcc
	v_cvt_pk_bf16_f32 v80, v60, v61
	v_cvt_pk_bf16_f32 v81, v68, v69
	v_lshl_add_u64 v[68:69], v[64:65], 0, s[0:1]
	global_store_dwordx2 v[84:85], v[80:81], off
	v_cvt_pk_bf16_f32 v84, v56, v57
	v_pk_mul_f32 v[80:81], v[58:59], v[164:165]
	s_mov_b64 s[0:1], 0x120000
	v_cvt_pk_bf16_f32 v85, v80, v81
	global_store_dwordx2 v[68:69], v[84:85], off offset:16
	v_cvt_pk_bf16_f32 v84, v28, v29
	v_pk_mul_f32 v[80:81], v[30:31], v[136:137]
	s_nop 0
	v_cvt_pk_bf16_f32 v85, v80, v81
	global_store_dwordx2 v[68:69], v[84:85], off offset:256
	v_cvt_pk_bf16_f32 v84, v24, v25
	v_pk_mul_f32 v[80:81], v[26:27], v[128:129]
	s_nop 0
	v_cvt_pk_bf16_f32 v85, v80, v81
	global_store_dwordx2 v[68:69], v[84:85], off offset:272
	v_add_co_u32_e32 v84, vcc, s49, v64
	v_pk_mul_f32 v[68:69], v[54:55], v[162:163]
	v_cvt_pk_bf16_f32 v80, v52, v53
	s_nop 0
	v_addc_co_u32_e32 v85, vcc, 0, v65, vcc
	v_cvt_pk_bf16_f32 v81, v68, v69
	v_lshl_add_u64 v[68:69], v[64:65], 0, s[0:1]
	global_store_dwordx2 v[84:85], v[80:81], off
	v_pk_mul_f32 v[80:81], v[50:51], v[164:165]
	v_cvt_pk_bf16_f32 v84, v48, v49
	s_mov_b64 s[0:1], 0x140000
	v_cvt_pk_bf16_f32 v85, v80, v81
	global_store_dwordx2 v[68:69], v[84:85], off offset:16
	v_pk_mul_f32 v[80:81], v[22:23], v[136:137]
	v_cvt_pk_bf16_f32 v84, v20, v21
	s_nop 0
	v_cvt_pk_bf16_f32 v85, v80, v81
	global_store_dwordx2 v[68:69], v[84:85], off offset:256
	v_pk_mul_f32 v[80:81], v[18:19], v[128:129]
	v_cvt_pk_bf16_f32 v84, v16, v17
	s_nop 0
	v_cvt_pk_bf16_f32 v85, v80, v81
	global_store_dwordx2 v[68:69], v[84:85], off offset:272
	v_pk_mul_f32 v[68:69], v[46:47], v[162:163]
	v_cvt_pk_bf16_f32 v80, v44, v45
	s_nop 0
	v_cvt_pk_bf16_f32 v81, v68, v69
	v_lshl_add_u64 v[68:69], v[64:65], 0, s[0:1]
	s_mov_b32 s0, 0x140000
	v_add_co_u32_e32 v84, vcc, s0, v64
	s_mov_b64 s[0:1], 0x160000
	s_nop 0
	v_addc_co_u32_e32 v85, vcc, 0, v65, vcc
	global_store_dwordx2 v[84:85], v[80:81], off
	v_pk_mul_f32 v[80:81], v[42:43], v[164:165]
	v_cvt_pk_bf16_f32 v84, v40, v41
	s_nop 0
	v_cvt_pk_bf16_f32 v85, v80, v81
	global_store_dwordx2 v[68:69], v[84:85], off offset:16
	v_pk_mul_f32 v[80:81], v[14:15], v[136:137]
	v_cvt_pk_bf16_f32 v84, v12, v13
	s_nop 0
	v_cvt_pk_bf16_f32 v85, v80, v81
	global_store_dwordx2 v[68:69], v[84:85], off offset:256
	v_pk_mul_f32 v[80:81], v[10:11], v[128:129]
	v_cvt_pk_bf16_f32 v84, v8, v9
	s_nop 0
	v_cvt_pk_bf16_f32 v85, v80, v81
	global_store_dwordx2 v[68:69], v[84:85], off offset:272
	v_pk_mul_f32 v[68:69], v[38:39], v[162:163]
	v_cvt_pk_bf16_f32 v80, v36, v37
	s_nop 0
	v_cvt_pk_bf16_f32 v81, v68, v69
	v_lshl_add_u64 v[68:69], v[64:65], 0, s[0:1]
	s_mov_b32 s0, 0x160000
	v_add_co_u32_e32 v64, vcc, s0, v64
	s_mov_b64 s[0:1], 0
	s_nop 0
	v_addc_co_u32_e32 v65, vcc, 0, v65, vcc
	global_store_dwordx2 v[64:65], v[80:81], off
	v_pk_mul_f32 v[64:65], v[34:35], v[164:165]
	v_cvt_pk_bf16_f32 v80, v32, v33
	s_nop 0
	v_cvt_pk_bf16_f32 v81, v64, v65
	global_store_dwordx2 v[68:69], v[80:81], off offset:16
	v_pk_mul_f32 v[64:65], v[6:7], v[136:137]
	v_cvt_pk_bf16_f32 v80, v4, v5
	s_nop 0
	v_cvt_pk_bf16_f32 v81, v64, v65
	global_store_dwordx2 v[68:69], v[80:81], off offset:256
	v_pk_mul_f32 v[64:65], v[2:3], v[128:129]
	v_cvt_pk_bf16_f32 v80, v0, v1
	s_nop 0
	v_cvt_pk_bf16_f32 v81, v64, v65
	s_nop 1
	global_store_dwordx2 v[68:69], v[80:81], off offset:272
